# MFMA block entry/exit trimmed: redundant lgkmcnt wait dropped, setprio 1 after first MFMA, setprio 0 after the closing barrier
# speedup vs baseline: 1.0107x; 1.0060x over previous
.LBB0_92:
	s_add_u32 s8, s6, 0xfffc0080
	s_addc_u32 s9, s7, -1
	s_add_i32 s35, 0, 0x10000
	s_cmp_eq_u32 s59, 12
	s_cselect_b32 s11, s5, s9
	s_cselect_b32 s10, s24, s8
	v_add_u32_e32 v140, s35, v165
	s_cselect_b32 s9, s47, s58
	s_cselect_b32 s8, s51, s53
	s_add_i32 s74, 0, 0x14000
	ds_read_b128 v[142:145], v140
	ds_read_b128 v[146:149], v140 offset:1024
	ds_read_b128 v[150:153], v140 offset:2048
	ds_read_b128 v[154:157], v140 offset:3072
	v_add_u32_e32 v140, s74, v165
	ds_read_b128 v[158:161], v140
	ds_read_b128 v[168:171], v140 offset:1024
	ds_read_b128 v[172:175], v140 offset:2048
	ds_read_b128 v[176:179], v140 offset:3072
	v_lshl_add_u64 v[162:163], s[6:7], 0, v[136:137]
	s_add_i32 m0, s27, 0xc000
	ds_read_b128 v[180:183], v166
	ds_read_b128 v[184:187], v166 offset:1024
	ds_read_b128 v[188:191], v166 offset:2048
	ds_read_b128 v[192:195], v166 offset:3072
	ds_read_b128 v[200:203], v166 offset:4096
	ds_read_b128 v[206:209], v166 offset:5120
	ds_read_b128 v[210:213], v166 offset:6144
	ds_read_b128 v[214:217], v166 offset:7168
	global_load_lds_dwordx4 v[162:163], off
	v_lshl_add_u64 v[162:163], s[6:7], 0, v[138:139]
	s_add_i32 m0, s27, 0xe000
	s_nop 0
	global_load_lds_dwordx4 v[162:163], off
	s_waitcnt vmcnt(8)
	s_waitcnt lgkmcnt(0)
	s_barrier
	v_mfma_f32_16x16x32_bf16 v[124:127], v[142:145], v[180:183], v[124:127]
	s_setprio 1
	v_mfma_f32_16x16x32_bf16 v[120:123], v[150:153], v[180:183], v[120:123]
	v_mfma_f32_16x16x32_bf16 v[108:111], v[142:145], v[188:191], v[108:111]
	v_mfma_f32_16x16x32_bf16 v[104:107], v[150:153], v[188:191], v[104:107]
	v_mfma_f32_16x16x32_bf16 v[92:95], v[142:145], v[200:203], v[92:95]
	v_mfma_f32_16x16x32_bf16 v[88:91], v[150:153], v[200:203], v[88:91]
	v_mfma_f32_16x16x32_bf16 v[76:79], v[142:145], v[210:213], v[76:79]
	v_mfma_f32_16x16x32_bf16 v[72:75], v[150:153], v[210:213], v[72:75]
	v_mfma_f32_16x16x32_bf16 v[124:127], v[146:149], v[184:187], v[124:127]
	v_mfma_f32_16x16x32_bf16 v[120:123], v[154:157], v[184:187], v[120:123]
	v_mfma_f32_16x16x32_bf16 v[108:111], v[146:149], v[192:195], v[108:111]
	v_mfma_f32_16x16x32_bf16 v[104:107], v[154:157], v[192:195], v[104:107]
	v_mfma_f32_16x16x32_bf16 v[92:95], v[146:149], v[206:209], v[92:95]
	v_mfma_f32_16x16x32_bf16 v[88:91], v[154:157], v[206:209], v[88:91]
	v_mfma_f32_16x16x32_bf16 v[76:79], v[146:149], v[214:217], v[76:79]
	v_mfma_f32_16x16x32_bf16 v[72:75], v[154:157], v[214:217], v[72:75]
	v_mfma_f32_16x16x32_bf16 v[116:119], v[158:161], v[180:183], v[116:119]
	v_mfma_f32_16x16x32_bf16 v[112:115], v[172:175], v[180:183], v[112:115]
	v_mfma_f32_16x16x32_bf16 v[100:103], v[158:161], v[188:191], v[100:103]
	v_mfma_f32_16x16x32_bf16 v[96:99], v[172:175], v[188:191], v[96:99]
	v_mfma_f32_16x16x32_bf16 v[84:87], v[158:161], v[200:203], v[84:87]
	v_mfma_f32_16x16x32_bf16 v[80:83], v[172:175], v[200:203], v[80:83]
	v_mfma_f32_16x16x32_bf16 v[68:71], v[158:161], v[210:213], v[68:71]
	v_mfma_f32_16x16x32_bf16 v[64:67], v[172:175], v[210:213], v[64:67]
	v_mfma_f32_16x16x32_bf16 v[116:119], v[168:171], v[184:187], v[116:119]
	v_mfma_f32_16x16x32_bf16 v[112:115], v[176:179], v[184:187], v[112:115]
	v_mfma_f32_16x16x32_bf16 v[100:103], v[168:171], v[192:195], v[100:103]
	v_mfma_f32_16x16x32_bf16 v[96:99], v[176:179], v[192:195], v[96:99]
	v_mfma_f32_16x16x32_bf16 v[84:87], v[168:171], v[206:209], v[84:87]
	v_mfma_f32_16x16x32_bf16 v[80:83], v[176:179], v[206:209], v[80:83]
	v_mfma_f32_16x16x32_bf16 v[68:71], v[168:171], v[214:217], v[68:71]
	v_mfma_f32_16x16x32_bf16 v[64:67], v[176:179], v[214:217], v[64:67]
	s_barrier
	s_setprio 0
	s_add_i32 s35, s35, s13
	v_lshl_add_u64 v[162:163], s[8:9], 0, v[132:133]
	s_mov_b32 m0, s35
	ds_read_b128 v[180:183], v166 offset:16384
	ds_read_b128 v[184:187], v166 offset:17408
	ds_read_b128 v[188:191], v166 offset:18432
	ds_read_b128 v[192:195], v166 offset:19456
	ds_read_b128 v[200:203], v166 offset:20480
	ds_read_b128 v[206:209], v166 offset:21504
	ds_read_b128 v[210:213], v166 offset:22528
	ds_read_b128 v[214:217], v166 offset:23552
	global_load_lds_dwordx4 v[162:163], off
	s_add_i32 m0, s35, 0x2000
	s_add_u32 s60, s8, 0x40000
	v_lshl_add_u64 v[196:197], s[8:9], 0, v[128:129]
	s_addc_u32 s61, s9, 0
	s_add_i32 s35, s74, s13
	global_load_lds_dwordx4 v[196:197], off
	v_lshl_add_u64 v[198:199], s[60:61], 0, v[132:133]
	s_mov_b32 m0, s35
	v_lshl_add_u64 v[204:205], s[10:11], 0, v[130:131]
	global_load_lds_dwordx4 v[198:199], off
	v_lshl_add_u64 v[198:199], s[60:61], 0, v[128:129]
	s_add_i32 m0, s35, 0x2000
	s_nop 0
	global_load_lds_dwordx4 v[198:199], off
	v_lshl_add_u64 v[198:199], s[10:11], 0, v[134:135]
	s_mov_b32 m0, s27
	s_nop 0
	global_load_lds_dwordx4 v[198:199], off
	s_mov_b32 m0, s28
	s_nop 0
	global_load_lds_dwordx4 v[204:205], off
	s_waitcnt vmcnt(8)
	s_waitcnt lgkmcnt(0)
	s_barrier
	v_mfma_f32_16x16x32_bf16 v[60:63], v[142:145], v[180:183], v[60:63]
	s_setprio 1
	v_mfma_f32_16x16x32_bf16 v[56:59], v[150:153], v[180:183], v[56:59]
	v_mfma_f32_16x16x32_bf16 v[44:47], v[142:145], v[188:191], v[44:47]
	v_mfma_f32_16x16x32_bf16 v[40:43], v[150:153], v[188:191], v[40:43]
	v_mfma_f32_16x16x32_bf16 v[28:31], v[142:145], v[200:203], v[28:31]
	v_mfma_f32_16x16x32_bf16 v[24:27], v[150:153], v[200:203], v[24:27]
	v_mfma_f32_16x16x32_bf16 v[12:15], v[142:145], v[210:213], v[12:15]
	v_mfma_f32_16x16x32_bf16 v[8:11], v[150:153], v[210:213], v[8:11]
	v_mfma_f32_16x16x32_bf16 v[60:63], v[146:149], v[184:187], v[60:63]
	v_mfma_f32_16x16x32_bf16 v[56:59], v[154:157], v[184:187], v[56:59]
	v_mfma_f32_16x16x32_bf16 v[44:47], v[146:149], v[192:195], v[44:47]
	v_mfma_f32_16x16x32_bf16 v[40:43], v[154:157], v[192:195], v[40:43]
	v_mfma_f32_16x16x32_bf16 v[28:31], v[146:149], v[206:209], v[28:31]
	v_mfma_f32_16x16x32_bf16 v[24:27], v[154:157], v[206:209], v[24:27]
	v_mfma_f32_16x16x32_bf16 v[12:15], v[146:149], v[214:217], v[12:15]
	v_mfma_f32_16x16x32_bf16 v[8:11], v[154:157], v[214:217], v[8:11]
	v_mfma_f32_16x16x32_bf16 v[52:55], v[158:161], v[180:183], v[52:55]
	v_mfma_f32_16x16x32_bf16 v[48:51], v[172:175], v[180:183], v[48:51]
	v_mfma_f32_16x16x32_bf16 v[36:39], v[158:161], v[188:191], v[36:39]
	v_mfma_f32_16x16x32_bf16 v[32:35], v[172:175], v[188:191], v[32:35]
	v_mfma_f32_16x16x32_bf16 v[20:23], v[158:161], v[200:203], v[20:23]
	v_mfma_f32_16x16x32_bf16 v[16:19], v[172:175], v[200:203], v[16:19]
	v_mfma_f32_16x16x32_bf16 v[4:7], v[158:161], v[210:213], v[4:7]
	v_mfma_f32_16x16x32_bf16 v[0:3], v[172:175], v[210:213], v[0:3]
	v_mfma_f32_16x16x32_bf16 v[52:55], v[168:171], v[184:187], v[52:55]
	v_mfma_f32_16x16x32_bf16 v[48:51], v[176:179], v[184:187], v[48:51]
	v_mfma_f32_16x16x32_bf16 v[36:39], v[168:171], v[192:195], v[36:39]
	v_mfma_f32_16x16x32_bf16 v[32:35], v[176:179], v[192:195], v[32:35]
	v_mfma_f32_16x16x32_bf16 v[20:23], v[168:171], v[206:209], v[20:23]
	v_mfma_f32_16x16x32_bf16 v[16:19], v[176:179], v[206:209], v[16:19]
	v_mfma_f32_16x16x32_bf16 v[4:7], v[168:171], v[214:217], v[4:7]
	v_mfma_f32_16x16x32_bf16 v[0:3], v[176:179], v[214:217], v[0:3]
	s_barrier
	s_setprio 0
	s_add_i32 s35, 0, 0x18000
	v_add_u32_e32 v140, s35, v165
	s_add_i32 s60, 0, 0x1c000
	ds_read_b128 v[142:145], v140
	ds_read_b128 v[146:149], v140 offset:1024
	ds_read_b128 v[150:153], v140 offset:2048
	ds_read_b128 v[154:157], v140 offset:3072
	v_add_u32_e32 v140, s60, v165
	ds_read_b128 v[158:161], v140
	ds_read_b128 v[168:171], v140 offset:1024
	ds_read_b128 v[172:175], v140 offset:2048
	ds_read_b128 v[176:179], v140 offset:3072
	s_add_u32 s10, s10, 0x40000
	s_addc_u32 s11, s11, 0
	s_mov_b32 m0, s29
	v_lshl_add_u64 v[218:219], s[10:11], 0, v[134:135]
	ds_read_b128 v[180:183], v166 offset:32768
	ds_read_b128 v[184:187], v166 offset:33792
	ds_read_b128 v[188:191], v166 offset:34816
	ds_read_b128 v[192:195], v166 offset:35840
	ds_read_b128 v[200:203], v166 offset:36864
	ds_read_b128 v[206:209], v166 offset:37888
	ds_read_b128 v[210:213], v166 offset:38912
	ds_read_b128 v[214:217], v166 offset:39936
	global_load_lds_dwordx4 v[218:219], off
	v_lshl_add_u64 v[218:219], s[10:11], 0, v[130:131]
	s_mov_b32 m0, s38
	s_nop 0
	global_load_lds_dwordx4 v[218:219], off
	s_waitcnt vmcnt(8)
	s_waitcnt lgkmcnt(0)
	s_barrier
	v_mfma_f32_16x16x32_bf16 v[124:127], v[142:145], v[180:183], v[124:127]
	s_setprio 1
	v_mfma_f32_16x16x32_bf16 v[120:123], v[150:153], v[180:183], v[120:123]
	v_mfma_f32_16x16x32_bf16 v[108:111], v[142:145], v[188:191], v[108:111]
	v_mfma_f32_16x16x32_bf16 v[104:107], v[150:153], v[188:191], v[104:107]
	v_mfma_f32_16x16x32_bf16 v[92:95], v[142:145], v[200:203], v[92:95]
	v_mfma_f32_16x16x32_bf16 v[88:91], v[150:153], v[200:203], v[88:91]
	v_mfma_f32_16x16x32_bf16 v[76:79], v[142:145], v[210:213], v[76:79]
	v_mfma_f32_16x16x32_bf16 v[72:75], v[150:153], v[210:213], v[72:75]
	v_mfma_f32_16x16x32_bf16 v[124:127], v[146:149], v[184:187], v[124:127]
	v_mfma_f32_16x16x32_bf16 v[120:123], v[154:157], v[184:187], v[120:123]
	v_mfma_f32_16x16x32_bf16 v[108:111], v[146:149], v[192:195], v[108:111]
	v_mfma_f32_16x16x32_bf16 v[104:107], v[154:157], v[192:195], v[104:107]
	v_mfma_f32_16x16x32_bf16 v[92:95], v[146:149], v[206:209], v[92:95]
	v_mfma_f32_16x16x32_bf16 v[88:91], v[154:157], v[206:209], v[88:91]
	v_mfma_f32_16x16x32_bf16 v[76:79], v[146:149], v[214:217], v[76:79]
	v_mfma_f32_16x16x32_bf16 v[72:75], v[154:157], v[214:217], v[72:75]
	v_mfma_f32_16x16x32_bf16 v[116:119], v[158:161], v[180:183], v[116:119]
	v_mfma_f32_16x16x32_bf16 v[112:115], v[172:175], v[180:183], v[112:115]
	v_mfma_f32_16x16x32_bf16 v[100:103], v[158:161], v[188:191], v[100:103]
	v_mfma_f32_16x16x32_bf16 v[96:99], v[172:175], v[188:191], v[96:99]
	v_mfma_f32_16x16x32_bf16 v[84:87], v[158:161], v[200:203], v[84:87]
	v_mfma_f32_16x16x32_bf16 v[80:83], v[172:175], v[200:203], v[80:83]
	v_mfma_f32_16x16x32_bf16 v[68:71], v[158:161], v[210:213], v[68:71]
	v_mfma_f32_16x16x32_bf16 v[64:67], v[172:175], v[210:213], v[64:67]
	v_mfma_f32_16x16x32_bf16 v[116:119], v[168:171], v[184:187], v[116:119]
	v_mfma_f32_16x16x32_bf16 v[112:115], v[176:179], v[184:187], v[112:115]
	v_mfma_f32_16x16x32_bf16 v[100:103], v[168:171], v[192:195], v[100:103]
	v_mfma_f32_16x16x32_bf16 v[96:99], v[176:179], v[192:195], v[96:99]
	v_mfma_f32_16x16x32_bf16 v[84:87], v[168:171], v[206:209], v[84:87]
	v_mfma_f32_16x16x32_bf16 v[80:83], v[176:179], v[206:209], v[80:83]
	v_mfma_f32_16x16x32_bf16 v[68:71], v[168:171], v[214:217], v[68:71]
	v_mfma_f32_16x16x32_bf16 v[64:67], v[176:179], v[214:217], v[64:67]
	s_barrier
	s_setprio 0
	s_add_i32 s10, s35, s13
	v_lshl_add_u64 v[162:163], v[162:163], 0, s[36:37]
	s_mov_b32 m0, s10
	ds_read_b128 v[180:183], v166 offset:49152
	ds_read_b128 v[184:187], v166 offset:50176
	ds_read_b128 v[188:191], v166 offset:51200
	ds_read_b128 v[192:195], v166 offset:52224
	ds_read_b128 v[200:203], v166 offset:53248
	ds_read_b128 v[206:209], v166 offset:54272
	ds_read_b128 v[210:213], v166 offset:55296
	ds_read_b128 v[214:217], v166 offset:56320
	global_load_lds_dwordx4 v[162:163], off
	s_add_i32 m0, s10, 0x2000
	s_add_u32 s8, s8, 0x40080
	v_lshl_add_u64 v[162:163], v[196:197], 0, s[36:37]
	s_addc_u32 s9, s9, 0
	s_add_i32 s10, s60, s13
	global_load_lds_dwordx4 v[162:163], off
	v_lshl_add_u64 v[162:163], s[8:9], 0, v[132:133]
	s_mov_b32 m0, s10
	s_nop 0
	global_load_lds_dwordx4 v[162:163], off
	v_lshl_add_u64 v[162:163], s[8:9], 0, v[128:129]
	s_add_i32 m0, s10, 0x2000
	s_nop 0
	global_load_lds_dwordx4 v[162:163], off
	v_lshl_add_u64 v[162:163], v[198:199], 0, s[36:37]
	s_mov_b32 m0, s42
	s_nop 0
	global_load_lds_dwordx4 v[162:163], off
	v_lshl_add_u64 v[162:163], v[204:205], 0, s[36:37]
	s_mov_b32 m0, s43
	s_nop 0
	global_load_lds_dwordx4 v[162:163], off
	s_waitcnt vmcnt(8)
	s_waitcnt lgkmcnt(0)
	s_barrier
	v_mfma_f32_16x16x32_bf16 v[60:63], v[142:145], v[180:183], v[60:63]
	s_setprio 1
	v_mfma_f32_16x16x32_bf16 v[56:59], v[150:153], v[180:183], v[56:59]
	v_mfma_f32_16x16x32_bf16 v[44:47], v[142:145], v[188:191], v[44:47]
	v_mfma_f32_16x16x32_bf16 v[40:43], v[150:153], v[188:191], v[40:43]
	v_mfma_f32_16x16x32_bf16 v[28:31], v[142:145], v[200:203], v[28:31]
	v_mfma_f32_16x16x32_bf16 v[24:27], v[150:153], v[200:203], v[24:27]
	v_mfma_f32_16x16x32_bf16 v[12:15], v[142:145], v[210:213], v[12:15]
	v_mfma_f32_16x16x32_bf16 v[8:11], v[150:153], v[210:213], v[8:11]
	v_mfma_f32_16x16x32_bf16 v[60:63], v[146:149], v[184:187], v[60:63]
	v_mfma_f32_16x16x32_bf16 v[56:59], v[154:157], v[184:187], v[56:59]
	v_mfma_f32_16x16x32_bf16 v[44:47], v[146:149], v[192:195], v[44:47]
	v_mfma_f32_16x16x32_bf16 v[40:43], v[154:157], v[192:195], v[40:43]
	v_mfma_f32_16x16x32_bf16 v[28:31], v[146:149], v[206:209], v[28:31]
	v_mfma_f32_16x16x32_bf16 v[24:27], v[154:157], v[206:209], v[24:27]
	v_mfma_f32_16x16x32_bf16 v[12:15], v[146:149], v[214:217], v[12:15]
	v_mfma_f32_16x16x32_bf16 v[8:11], v[154:157], v[214:217], v[8:11]
	v_mfma_f32_16x16x32_bf16 v[52:55], v[158:161], v[180:183], v[52:55]
	v_mfma_f32_16x16x32_bf16 v[48:51], v[172:175], v[180:183], v[48:51]
	v_mfma_f32_16x16x32_bf16 v[36:39], v[158:161], v[188:191], v[36:39]
	v_mfma_f32_16x16x32_bf16 v[32:35], v[172:175], v[188:191], v[32:35]
	v_mfma_f32_16x16x32_bf16 v[20:23], v[158:161], v[200:203], v[20:23]
	v_mfma_f32_16x16x32_bf16 v[16:19], v[172:175], v[200:203], v[16:19]
	v_mfma_f32_16x16x32_bf16 v[4:7], v[158:161], v[210:213], v[4:7]
	v_mfma_f32_16x16x32_bf16 v[0:3], v[172:175], v[210:213], v[0:3]
	v_mfma_f32_16x16x32_bf16 v[52:55], v[168:171], v[184:187], v[52:55]
	v_mfma_f32_16x16x32_bf16 v[48:51], v[176:179], v[184:187], v[48:51]
	v_mfma_f32_16x16x32_bf16 v[36:39], v[168:171], v[192:195], v[36:39]
	v_mfma_f32_16x16x32_bf16 v[32:35], v[176:179], v[192:195], v[32:35]
	v_mfma_f32_16x16x32_bf16 v[20:23], v[168:171], v[206:209], v[20:23]
	v_mfma_f32_16x16x32_bf16 v[16:19], v[176:179], v[206:209], v[16:19]
	v_mfma_f32_16x16x32_bf16 v[4:7], v[168:171], v[214:217], v[4:7]
	v_mfma_f32_16x16x32_bf16 v[0:3], v[176:179], v[214:217], v[0:3]
	s_barrier
	s_setprio 0
	s_add_i32 s59, s59, 2
	s_add_u32 s6, s6, 0x100
	s_addc_u32 s7, s7, 0
	s_add_u32 s53, s53, 0x100
	s_addc_u32 s58, s58, 0
	s_cmp_gt_u32 s59, 13
	s_cbranch_scc0 .LBB0_92
	s_and_b64 vcc, exec, s[48:49]
	s_cbranch_vccz .LBB0_95
	s_barrier

.LBB0_147:
	s_add_u32 s8, s6, 0xfffc0080
	s_addc_u32 s9, s7, -1
	s_add_i32 s35, 0, 0x10000
	s_cmp_eq_u32 s74, 12
	s_cselect_b32 s11, s24, s9
	s_cselect_b32 s10, s38, s8
	s_cselect_b32 s9, s53, s61
	s_cselect_b32 s8, s55, s60
	s_add_i32 s75, 0, 0x14000
	v_add_u32_e32 v142, s35, v178
	v_add_u32_e32 v168, s75, v178
	ds_read_b128 v[128:131], v142
	ds_read_b128 v[132:135], v142 offset:1024
	ds_read_b128 v[136:139], v142 offset:2048
	ds_read_b128 v[142:145], v142 offset:3072
	ds_read_b128 v[146:149], v168
	ds_read_b128 v[150:153], v168 offset:1024
	ds_read_b128 v[154:157], v168 offset:2048
	ds_read_b128 v[168:171], v168 offset:3072
	v_lshl_add_u64 v[176:177], s[6:7], 0, v[164:165]
	s_add_i32 m0, s15, 0xc000
	ds_read_b128 v[172:175], v179
	ds_read_b128 v[180:183], v179 offset:1024
	ds_read_b128 v[184:187], v179 offset:2048
	ds_read_b128 v[188:191], v179 offset:3072
	ds_read_b128 v[192:195], v179 offset:4096
	ds_read_b128 v[200:203], v179 offset:5120
	ds_read_b128 v[206:209], v179 offset:6144
	ds_read_b128 v[210:213], v179 offset:7168
	global_load_lds_dwordx4 v[176:177], off
	v_lshl_add_u64 v[176:177], s[6:7], 0, v[166:167]
	s_add_i32 m0, s15, 0xe000
	s_nop 0
	global_load_lds_dwordx4 v[176:177], off
	s_waitcnt vmcnt(8)
	s_waitcnt lgkmcnt(0)
	s_barrier
	v_mfma_f32_16x16x32_bf16 v[124:127], v[128:131], v[172:175], v[124:127]
	s_setprio 1
	v_mfma_f32_16x16x32_bf16 v[120:123], v[136:139], v[172:175], v[120:123]
	v_mfma_f32_16x16x32_bf16 v[108:111], v[128:131], v[184:187], v[108:111]
	v_mfma_f32_16x16x32_bf16 v[104:107], v[136:139], v[184:187], v[104:107]
	v_mfma_f32_16x16x32_bf16 v[92:95], v[128:131], v[192:195], v[92:95]
	v_mfma_f32_16x16x32_bf16 v[88:91], v[136:139], v[192:195], v[88:91]
	v_mfma_f32_16x16x32_bf16 v[76:79], v[128:131], v[206:209], v[76:79]
	v_mfma_f32_16x16x32_bf16 v[72:75], v[136:139], v[206:209], v[72:75]
	v_mfma_f32_16x16x32_bf16 v[124:127], v[132:135], v[180:183], v[124:127]
	v_mfma_f32_16x16x32_bf16 v[120:123], v[142:145], v[180:183], v[120:123]
	v_mfma_f32_16x16x32_bf16 v[108:111], v[132:135], v[188:191], v[108:111]
	v_mfma_f32_16x16x32_bf16 v[104:107], v[142:145], v[188:191], v[104:107]
	v_mfma_f32_16x16x32_bf16 v[92:95], v[132:135], v[200:203], v[92:95]
	v_mfma_f32_16x16x32_bf16 v[88:91], v[142:145], v[200:203], v[88:91]
	v_mfma_f32_16x16x32_bf16 v[76:79], v[132:135], v[210:213], v[76:79]
	v_mfma_f32_16x16x32_bf16 v[72:75], v[142:145], v[210:213], v[72:75]
	v_mfma_f32_16x16x32_bf16 v[116:119], v[146:149], v[172:175], v[116:119]
	v_mfma_f32_16x16x32_bf16 v[112:115], v[154:157], v[172:175], v[112:115]
	v_mfma_f32_16x16x32_bf16 v[100:103], v[146:149], v[184:187], v[100:103]
	v_mfma_f32_16x16x32_bf16 v[96:99], v[154:157], v[184:187], v[96:99]
	v_mfma_f32_16x16x32_bf16 v[84:87], v[146:149], v[192:195], v[84:87]
	v_mfma_f32_16x16x32_bf16 v[80:83], v[154:157], v[192:195], v[80:83]
	v_mfma_f32_16x16x32_bf16 v[68:71], v[146:149], v[206:209], v[68:71]
	v_mfma_f32_16x16x32_bf16 v[64:67], v[154:157], v[206:209], v[64:67]
	v_mfma_f32_16x16x32_bf16 v[116:119], v[150:153], v[180:183], v[116:119]
	v_mfma_f32_16x16x32_bf16 v[112:115], v[168:171], v[180:183], v[112:115]
	v_mfma_f32_16x16x32_bf16 v[100:103], v[150:153], v[188:191], v[100:103]
	v_mfma_f32_16x16x32_bf16 v[96:99], v[168:171], v[188:191], v[96:99]
	v_mfma_f32_16x16x32_bf16 v[84:87], v[150:153], v[200:203], v[84:87]
	v_mfma_f32_16x16x32_bf16 v[80:83], v[168:171], v[200:203], v[80:83]
	v_mfma_f32_16x16x32_bf16 v[68:71], v[150:153], v[210:213], v[68:71]
	v_mfma_f32_16x16x32_bf16 v[64:67], v[168:171], v[210:213], v[64:67]
	s_barrier
	s_setprio 0
	s_add_i32 s35, s35, s13
	v_lshl_add_u64 v[176:177], s[8:9], 0, v[140:141]
	s_mov_b32 m0, s35
	ds_read_b128 v[172:175], v179 offset:16384
	ds_read_b128 v[180:183], v179 offset:17408
	ds_read_b128 v[184:187], v179 offset:18432
	ds_read_b128 v[188:191], v179 offset:19456
	ds_read_b128 v[192:195], v179 offset:20480
	ds_read_b128 v[200:203], v179 offset:21504
	ds_read_b128 v[206:209], v179 offset:22528
	ds_read_b128 v[210:213], v179 offset:23552
	global_load_lds_dwordx4 v[176:177], off
	s_add_i32 m0, s35, 0x2000
	s_add_u32 s84, s8, 0x40000
	v_lshl_add_u64 v[196:197], s[8:9], 0, v[158:159]
	s_addc_u32 s85, s9, 0
	s_add_i32 s35, s75, s13
	global_load_lds_dwordx4 v[196:197], off
	v_lshl_add_u64 v[198:199], s[84:85], 0, v[140:141]
	s_mov_b32 m0, s35
	v_lshl_add_u64 v[204:205], s[10:11], 0, v[160:161]
	global_load_lds_dwordx4 v[198:199], off
	v_lshl_add_u64 v[198:199], s[84:85], 0, v[158:159]
	s_add_i32 m0, s35, 0x2000
	s_nop 0
	global_load_lds_dwordx4 v[198:199], off
	v_lshl_add_u64 v[198:199], s[10:11], 0, v[162:163]
	s_mov_b32 m0, s15
	s_nop 0
	global_load_lds_dwordx4 v[198:199], off
	s_mov_b32 m0, s26
	s_nop 0
	global_load_lds_dwordx4 v[204:205], off
	s_waitcnt vmcnt(8)
	s_waitcnt lgkmcnt(0)
	s_barrier
	v_mfma_f32_16x16x32_bf16 v[60:63], v[128:131], v[172:175], v[60:63]
	s_setprio 1
	v_mfma_f32_16x16x32_bf16 v[56:59], v[136:139], v[172:175], v[56:59]
	v_mfma_f32_16x16x32_bf16 v[44:47], v[128:131], v[184:187], v[44:47]
	v_mfma_f32_16x16x32_bf16 v[40:43], v[136:139], v[184:187], v[40:43]
	v_mfma_f32_16x16x32_bf16 v[28:31], v[128:131], v[192:195], v[28:31]
	v_mfma_f32_16x16x32_bf16 v[24:27], v[136:139], v[192:195], v[24:27]
	v_mfma_f32_16x16x32_bf16 v[12:15], v[128:131], v[206:209], v[12:15]
	v_mfma_f32_16x16x32_bf16 v[8:11], v[136:139], v[206:209], v[8:11]
	v_mfma_f32_16x16x32_bf16 v[60:63], v[132:135], v[180:183], v[60:63]
	v_mfma_f32_16x16x32_bf16 v[56:59], v[142:145], v[180:183], v[56:59]
	v_mfma_f32_16x16x32_bf16 v[44:47], v[132:135], v[188:191], v[44:47]
	v_mfma_f32_16x16x32_bf16 v[40:43], v[142:145], v[188:191], v[40:43]
	v_mfma_f32_16x16x32_bf16 v[28:31], v[132:135], v[200:203], v[28:31]
	v_mfma_f32_16x16x32_bf16 v[24:27], v[142:145], v[200:203], v[24:27]
	v_mfma_f32_16x16x32_bf16 v[12:15], v[132:135], v[210:213], v[12:15]
	v_mfma_f32_16x16x32_bf16 v[8:11], v[142:145], v[210:213], v[8:11]
	v_mfma_f32_16x16x32_bf16 v[52:55], v[146:149], v[172:175], v[52:55]
	v_mfma_f32_16x16x32_bf16 v[48:51], v[154:157], v[172:175], v[48:51]
	v_mfma_f32_16x16x32_bf16 v[36:39], v[146:149], v[184:187], v[36:39]
	v_mfma_f32_16x16x32_bf16 v[32:35], v[154:157], v[184:187], v[32:35]
	v_mfma_f32_16x16x32_bf16 v[20:23], v[146:149], v[192:195], v[20:23]
	v_mfma_f32_16x16x32_bf16 v[16:19], v[154:157], v[192:195], v[16:19]
	v_mfma_f32_16x16x32_bf16 v[4:7], v[146:149], v[206:209], v[4:7]
	v_mfma_f32_16x16x32_bf16 v[0:3], v[154:157], v[206:209], v[0:3]
	v_mfma_f32_16x16x32_bf16 v[52:55], v[150:153], v[180:183], v[52:55]
	v_mfma_f32_16x16x32_bf16 v[48:51], v[168:171], v[180:183], v[48:51]
	v_mfma_f32_16x16x32_bf16 v[36:39], v[150:153], v[188:191], v[36:39]
	v_mfma_f32_16x16x32_bf16 v[32:35], v[168:171], v[188:191], v[32:35]
	v_mfma_f32_16x16x32_bf16 v[20:23], v[150:153], v[200:203], v[20:23]
	v_mfma_f32_16x16x32_bf16 v[16:19], v[168:171], v[200:203], v[16:19]
	v_mfma_f32_16x16x32_bf16 v[4:7], v[150:153], v[210:213], v[4:7]
	v_mfma_f32_16x16x32_bf16 v[0:3], v[168:171], v[210:213], v[0:3]
	s_barrier
	s_setprio 0
	s_add_i32 s35, 0, 0x18000
	s_add_i32 s75, 0, 0x1c000
	v_add_u32_e32 v142, s35, v178
	v_add_u32_e32 v168, s75, v178
	ds_read_b128 v[128:131], v142
	ds_read_b128 v[132:135], v142 offset:1024
	ds_read_b128 v[136:139], v142 offset:2048
	ds_read_b128 v[142:145], v142 offset:3072
	ds_read_b128 v[146:149], v168
	ds_read_b128 v[150:153], v168 offset:1024
	ds_read_b128 v[154:157], v168 offset:2048
	ds_read_b128 v[168:171], v168 offset:3072
	s_add_u32 s10, s10, 0x40000
	s_addc_u32 s11, s11, 0
	s_mov_b32 m0, s27
	v_lshl_add_u64 v[214:215], s[10:11], 0, v[162:163]
	ds_read_b128 v[172:175], v179 offset:32768
	ds_read_b128 v[180:183], v179 offset:33792
	ds_read_b128 v[184:187], v179 offset:34816
	ds_read_b128 v[188:191], v179 offset:35840
	ds_read_b128 v[192:195], v179 offset:36864
	ds_read_b128 v[200:203], v179 offset:37888
	ds_read_b128 v[206:209], v179 offset:38912
	ds_read_b128 v[210:213], v179 offset:39936
	global_load_lds_dwordx4 v[214:215], off
	v_lshl_add_u64 v[214:215], s[10:11], 0, v[160:161]
	s_mov_b32 m0, s28
	s_nop 0
	global_load_lds_dwordx4 v[214:215], off
	s_waitcnt vmcnt(8)
	s_waitcnt lgkmcnt(0)
	s_barrier
	v_mfma_f32_16x16x32_bf16 v[124:127], v[128:131], v[172:175], v[124:127]
	s_setprio 1
	v_mfma_f32_16x16x32_bf16 v[120:123], v[136:139], v[172:175], v[120:123]
	v_mfma_f32_16x16x32_bf16 v[108:111], v[128:131], v[184:187], v[108:111]
	v_mfma_f32_16x16x32_bf16 v[104:107], v[136:139], v[184:187], v[104:107]
	v_mfma_f32_16x16x32_bf16 v[92:95], v[128:131], v[192:195], v[92:95]
	v_mfma_f32_16x16x32_bf16 v[88:91], v[136:139], v[192:195], v[88:91]
	v_mfma_f32_16x16x32_bf16 v[76:79], v[128:131], v[206:209], v[76:79]
	v_mfma_f32_16x16x32_bf16 v[72:75], v[136:139], v[206:209], v[72:75]
	v_mfma_f32_16x16x32_bf16 v[124:127], v[132:135], v[180:183], v[124:127]
	v_mfma_f32_16x16x32_bf16 v[120:123], v[142:145], v[180:183], v[120:123]
	v_mfma_f32_16x16x32_bf16 v[108:111], v[132:135], v[188:191], v[108:111]
	v_mfma_f32_16x16x32_bf16 v[104:107], v[142:145], v[188:191], v[104:107]
	v_mfma_f32_16x16x32_bf16 v[92:95], v[132:135], v[200:203], v[92:95]
	v_mfma_f32_16x16x32_bf16 v[88:91], v[142:145], v[200:203], v[88:91]
	v_mfma_f32_16x16x32_bf16 v[76:79], v[132:135], v[210:213], v[76:79]
	v_mfma_f32_16x16x32_bf16 v[72:75], v[142:145], v[210:213], v[72:75]
	v_mfma_f32_16x16x32_bf16 v[116:119], v[146:149], v[172:175], v[116:119]
	v_mfma_f32_16x16x32_bf16 v[112:115], v[154:157], v[172:175], v[112:115]
	v_mfma_f32_16x16x32_bf16 v[100:103], v[146:149], v[184:187], v[100:103]
	v_mfma_f32_16x16x32_bf16 v[96:99], v[154:157], v[184:187], v[96:99]
	v_mfma_f32_16x16x32_bf16 v[84:87], v[146:149], v[192:195], v[84:87]
	v_mfma_f32_16x16x32_bf16 v[80:83], v[154:157], v[192:195], v[80:83]
	v_mfma_f32_16x16x32_bf16 v[68:71], v[146:149], v[206:209], v[68:71]
	v_mfma_f32_16x16x32_bf16 v[64:67], v[154:157], v[206:209], v[64:67]
	v_mfma_f32_16x16x32_bf16 v[116:119], v[150:153], v[180:183], v[116:119]
	v_mfma_f32_16x16x32_bf16 v[112:115], v[168:171], v[180:183], v[112:115]
	v_mfma_f32_16x16x32_bf16 v[100:103], v[150:153], v[188:191], v[100:103]
	v_mfma_f32_16x16x32_bf16 v[96:99], v[168:171], v[188:191], v[96:99]
	v_mfma_f32_16x16x32_bf16 v[84:87], v[150:153], v[200:203], v[84:87]
	v_mfma_f32_16x16x32_bf16 v[80:83], v[168:171], v[200:203], v[80:83]
	v_mfma_f32_16x16x32_bf16 v[68:71], v[150:153], v[210:213], v[68:71]
	v_mfma_f32_16x16x32_bf16 v[64:67], v[168:171], v[210:213], v[64:67]
	s_barrier
	s_setprio 0
	s_add_i32 s10, s35, s13
	v_lshl_add_u64 v[176:177], v[176:177], 0, s[36:37]
	s_mov_b32 m0, s10
	ds_read_b128 v[172:175], v179 offset:49152
	ds_read_b128 v[180:183], v179 offset:50176
	ds_read_b128 v[184:187], v179 offset:51200
	ds_read_b128 v[188:191], v179 offset:52224
	ds_read_b128 v[192:195], v179 offset:53248
	ds_read_b128 v[200:203], v179 offset:54272
	ds_read_b128 v[206:209], v179 offset:55296
	ds_read_b128 v[210:213], v179 offset:56320
	global_load_lds_dwordx4 v[176:177], off
	s_add_i32 m0, s10, 0x2000
	s_add_u32 s8, s8, 0x40080
	v_lshl_add_u64 v[176:177], v[196:197], 0, s[36:37]
	s_addc_u32 s9, s9, 0
	s_add_i32 s10, s75, s13
	global_load_lds_dwordx4 v[176:177], off
	v_lshl_add_u64 v[176:177], s[8:9], 0, v[140:141]
	s_mov_b32 m0, s10
	s_nop 0
	global_load_lds_dwordx4 v[176:177], off
	v_lshl_add_u64 v[176:177], s[8:9], 0, v[158:159]
	s_add_i32 m0, s10, 0x2000
	s_nop 0
	global_load_lds_dwordx4 v[176:177], off
	v_lshl_add_u64 v[176:177], v[198:199], 0, s[36:37]
	s_mov_b32 m0, s29
	s_nop 0
	global_load_lds_dwordx4 v[176:177], off
	v_lshl_add_u64 v[176:177], v[204:205], 0, s[36:37]
	s_mov_b32 m0, s42
	s_nop 0
	global_load_lds_dwordx4 v[176:177], off
	s_waitcnt vmcnt(8)
	s_waitcnt lgkmcnt(0)
	s_barrier
	v_mfma_f32_16x16x32_bf16 v[60:63], v[128:131], v[172:175], v[60:63]
	s_setprio 1
	v_mfma_f32_16x16x32_bf16 v[56:59], v[136:139], v[172:175], v[56:59]
	v_mfma_f32_16x16x32_bf16 v[44:47], v[128:131], v[184:187], v[44:47]
	v_mfma_f32_16x16x32_bf16 v[40:43], v[136:139], v[184:187], v[40:43]
	v_mfma_f32_16x16x32_bf16 v[28:31], v[128:131], v[192:195], v[28:31]
	v_mfma_f32_16x16x32_bf16 v[24:27], v[136:139], v[192:195], v[24:27]
	v_mfma_f32_16x16x32_bf16 v[12:15], v[128:131], v[206:209], v[12:15]
	v_mfma_f32_16x16x32_bf16 v[8:11], v[136:139], v[206:209], v[8:11]
	v_mfma_f32_16x16x32_bf16 v[60:63], v[132:135], v[180:183], v[60:63]
	v_mfma_f32_16x16x32_bf16 v[56:59], v[142:145], v[180:183], v[56:59]
	v_mfma_f32_16x16x32_bf16 v[44:47], v[132:135], v[188:191], v[44:47]
	v_mfma_f32_16x16x32_bf16 v[40:43], v[142:145], v[188:191], v[40:43]
	v_mfma_f32_16x16x32_bf16 v[28:31], v[132:135], v[200:203], v[28:31]
	v_mfma_f32_16x16x32_bf16 v[24:27], v[142:145], v[200:203], v[24:27]
	v_mfma_f32_16x16x32_bf16 v[12:15], v[132:135], v[210:213], v[12:15]
	v_mfma_f32_16x16x32_bf16 v[8:11], v[142:145], v[210:213], v[8:11]
	v_mfma_f32_16x16x32_bf16 v[52:55], v[146:149], v[172:175], v[52:55]
	v_mfma_f32_16x16x32_bf16 v[48:51], v[154:157], v[172:175], v[48:51]
	v_mfma_f32_16x16x32_bf16 v[36:39], v[146:149], v[184:187], v[36:39]
	v_mfma_f32_16x16x32_bf16 v[32:35], v[154:157], v[184:187], v[32:35]
	v_mfma_f32_16x16x32_bf16 v[20:23], v[146:149], v[192:195], v[20:23]
	v_mfma_f32_16x16x32_bf16 v[16:19], v[154:157], v[192:195], v[16:19]
	v_mfma_f32_16x16x32_bf16 v[4:7], v[146:149], v[206:209], v[4:7]
	v_mfma_f32_16x16x32_bf16 v[0:3], v[154:157], v[206:209], v[0:3]
	v_mfma_f32_16x16x32_bf16 v[52:55], v[150:153], v[180:183], v[52:55]
	v_mfma_f32_16x16x32_bf16 v[48:51], v[168:171], v[180:183], v[48:51]
	v_mfma_f32_16x16x32_bf16 v[36:39], v[150:153], v[188:191], v[36:39]
	v_mfma_f32_16x16x32_bf16 v[32:35], v[168:171], v[188:191], v[32:35]
	v_mfma_f32_16x16x32_bf16 v[20:23], v[150:153], v[200:203], v[20:23]
	v_mfma_f32_16x16x32_bf16 v[16:19], v[168:171], v[200:203], v[16:19]
	v_mfma_f32_16x16x32_bf16 v[4:7], v[150:153], v[210:213], v[4:7]
	v_mfma_f32_16x16x32_bf16 v[0:3], v[168:171], v[210:213], v[0:3]
	s_barrier
	s_setprio 0
	s_add_i32 s74, s74, 2
	s_add_u32 s6, s6, 0x100
	s_addc_u32 s7, s7, 0
	s_add_u32 s60, s60, 0x100
	s_addc_u32 s61, s61, 0
	s_cmp_gt_u32 s74, 13
	s_cbranch_scc0 .LBB0_147
	s_and_b64 vcc, exec, s[50:51]
	s_cbranch_vccz .LBB0_150
	s_barrier

.LBB0_234:
	s_add_u32 s8, s6, 0xfffc0080
	s_addc_u32 s9, s7, -1
	s_add_i32 s35, 0, 0x10000
	s_cmp_eq_u32 s53, 12
	s_cselect_b32 s11, s4, s9
	s_cselect_b32 s10, s5, s8
	v_add_u32_e32 v140, s35, v206
	s_cselect_b32 s9, s24, s51
	s_cselect_b32 s8, s42, s43
	s_add_i32 s76, 0, 0x14000
	ds_read_b128 v[142:145], v140
	ds_read_b128 v[146:149], v140 offset:1024
	ds_read_b128 v[150:153], v140 offset:2048
	ds_read_b128 v[154:157], v140 offset:3072
	v_add_u32_e32 v140, s76, v206
	ds_read_b128 v[158:161], v140
	ds_read_b128 v[162:165], v140 offset:1024
	ds_read_b128 v[166:169], v140 offset:2048
	ds_read_b128 v[170:173], v140 offset:3072
	v_lshl_add_u64 v[198:199], s[6:7], 0, v[136:137]
	s_add_i32 m0, s15, 0xc000
	ds_read_b128 v[174:177], v207
	ds_read_b128 v[178:181], v207 offset:1024
	ds_read_b128 v[182:185], v207 offset:2048
	ds_read_b128 v[186:189], v207 offset:3072
	ds_read_b128 v[190:193], v207 offset:4096
	ds_read_b128 v[194:197], v207 offset:5120
	ds_read_b128 v[200:203], v207 offset:6144
	ds_read_b128 v[208:211], v207 offset:7168
	global_load_lds_dwordx4 v[198:199], off
	v_lshl_add_u64 v[198:199], s[6:7], 0, v[138:139]
	s_add_i32 m0, s15, 0xe000
	s_nop 0
	global_load_lds_dwordx4 v[198:199], off
	s_waitcnt vmcnt(8)
	s_waitcnt lgkmcnt(0)
	s_barrier
	v_mfma_f32_16x16x32_bf16 v[124:127], v[142:145], v[174:177], v[124:127]
	s_setprio 1
	v_mfma_f32_16x16x32_bf16 v[120:123], v[150:153], v[174:177], v[120:123]
	v_mfma_f32_16x16x32_bf16 v[108:111], v[142:145], v[182:185], v[108:111]
	v_mfma_f32_16x16x32_bf16 v[104:107], v[150:153], v[182:185], v[104:107]
	v_mfma_f32_16x16x32_bf16 v[92:95], v[142:145], v[190:193], v[92:95]
	v_mfma_f32_16x16x32_bf16 v[88:91], v[150:153], v[190:193], v[88:91]
	v_mfma_f32_16x16x32_bf16 v[76:79], v[142:145], v[200:203], v[76:79]
	v_mfma_f32_16x16x32_bf16 v[72:75], v[150:153], v[200:203], v[72:75]
	v_mfma_f32_16x16x32_bf16 v[124:127], v[146:149], v[178:181], v[124:127]
	v_mfma_f32_16x16x32_bf16 v[120:123], v[154:157], v[178:181], v[120:123]
	v_mfma_f32_16x16x32_bf16 v[108:111], v[146:149], v[186:189], v[108:111]
	v_mfma_f32_16x16x32_bf16 v[104:107], v[154:157], v[186:189], v[104:107]
	v_mfma_f32_16x16x32_bf16 v[92:95], v[146:149], v[194:197], v[92:95]
	v_mfma_f32_16x16x32_bf16 v[88:91], v[154:157], v[194:197], v[88:91]
	v_mfma_f32_16x16x32_bf16 v[76:79], v[146:149], v[208:211], v[76:79]
	v_mfma_f32_16x16x32_bf16 v[72:75], v[154:157], v[208:211], v[72:75]
	v_mfma_f32_16x16x32_bf16 v[116:119], v[158:161], v[174:177], v[116:119]
	v_mfma_f32_16x16x32_bf16 v[112:115], v[166:169], v[174:177], v[112:115]
	v_mfma_f32_16x16x32_bf16 v[100:103], v[158:161], v[182:185], v[100:103]
	v_mfma_f32_16x16x32_bf16 v[96:99], v[166:169], v[182:185], v[96:99]
	v_mfma_f32_16x16x32_bf16 v[84:87], v[158:161], v[190:193], v[84:87]
	v_mfma_f32_16x16x32_bf16 v[80:83], v[166:169], v[190:193], v[80:83]
	v_mfma_f32_16x16x32_bf16 v[68:71], v[158:161], v[200:203], v[68:71]
	v_mfma_f32_16x16x32_bf16 v[64:67], v[166:169], v[200:203], v[64:67]
	v_mfma_f32_16x16x32_bf16 v[116:119], v[162:165], v[178:181], v[116:119]
	v_mfma_f32_16x16x32_bf16 v[112:115], v[170:173], v[178:181], v[112:115]
	v_mfma_f32_16x16x32_bf16 v[100:103], v[162:165], v[186:189], v[100:103]
	v_mfma_f32_16x16x32_bf16 v[96:99], v[170:173], v[186:189], v[96:99]
	v_mfma_f32_16x16x32_bf16 v[84:87], v[162:165], v[194:197], v[84:87]
	v_mfma_f32_16x16x32_bf16 v[80:83], v[170:173], v[194:197], v[80:83]
	v_mfma_f32_16x16x32_bf16 v[68:71], v[162:165], v[208:211], v[68:71]
	v_mfma_f32_16x16x32_bf16 v[64:67], v[170:173], v[208:211], v[64:67]
	s_barrier
	s_setprio 0
	s_add_i32 s35, s35, s13
	v_lshl_add_u64 v[198:199], s[8:9], 0, v[132:133]
	s_mov_b32 m0, s35
	ds_read_b128 v[174:177], v207 offset:16384
	ds_read_b128 v[178:181], v207 offset:17408
	ds_read_b128 v[182:185], v207 offset:18432
	ds_read_b128 v[186:189], v207 offset:19456
	ds_read_b128 v[190:193], v207 offset:20480
	ds_read_b128 v[194:197], v207 offset:21504
	ds_read_b128 v[200:203], v207 offset:22528
	ds_read_b128 v[208:211], v207 offset:23552
	global_load_lds_dwordx4 v[198:199], off
	s_add_i32 m0, s35, 0x2000
	s_add_u32 s60, s8, 0x40000
	v_lshl_add_u64 v[204:205], s[8:9], 0, v[128:129]
	s_addc_u32 s61, s9, 0
	s_add_i32 s35, s76, s13
	global_load_lds_dwordx4 v[204:205], off
	v_lshl_add_u64 v[212:213], s[60:61], 0, v[132:133]
	s_mov_b32 m0, s35
	v_lshl_add_u64 v[214:215], s[10:11], 0, v[130:131]
	global_load_lds_dwordx4 v[212:213], off
	v_lshl_add_u64 v[212:213], s[60:61], 0, v[128:129]
	s_add_i32 m0, s35, 0x2000
	s_nop 0
	global_load_lds_dwordx4 v[212:213], off
	v_lshl_add_u64 v[212:213], s[10:11], 0, v[134:135]
	s_mov_b32 m0, s15
	s_nop 0
	global_load_lds_dwordx4 v[212:213], off
	s_mov_b32 m0, s26
	s_nop 0
	global_load_lds_dwordx4 v[214:215], off
	s_waitcnt vmcnt(8)
	s_waitcnt lgkmcnt(0)
	s_barrier
	v_mfma_f32_16x16x32_bf16 v[60:63], v[142:145], v[174:177], v[60:63]
	s_setprio 1
	v_mfma_f32_16x16x32_bf16 v[56:59], v[150:153], v[174:177], v[56:59]
	v_mfma_f32_16x16x32_bf16 v[44:47], v[142:145], v[182:185], v[44:47]
	v_mfma_f32_16x16x32_bf16 v[40:43], v[150:153], v[182:185], v[40:43]
	v_mfma_f32_16x16x32_bf16 v[28:31], v[142:145], v[190:193], v[28:31]
	v_mfma_f32_16x16x32_bf16 v[24:27], v[150:153], v[190:193], v[24:27]
	v_mfma_f32_16x16x32_bf16 v[12:15], v[142:145], v[200:203], v[12:15]
	v_mfma_f32_16x16x32_bf16 v[8:11], v[150:153], v[200:203], v[8:11]
	v_mfma_f32_16x16x32_bf16 v[60:63], v[146:149], v[178:181], v[60:63]
	v_mfma_f32_16x16x32_bf16 v[56:59], v[154:157], v[178:181], v[56:59]
	v_mfma_f32_16x16x32_bf16 v[44:47], v[146:149], v[186:189], v[44:47]
	v_mfma_f32_16x16x32_bf16 v[40:43], v[154:157], v[186:189], v[40:43]
	v_mfma_f32_16x16x32_bf16 v[28:31], v[146:149], v[194:197], v[28:31]
	v_mfma_f32_16x16x32_bf16 v[24:27], v[154:157], v[194:197], v[24:27]
	v_mfma_f32_16x16x32_bf16 v[12:15], v[146:149], v[208:211], v[12:15]
	v_mfma_f32_16x16x32_bf16 v[8:11], v[154:157], v[208:211], v[8:11]
	v_mfma_f32_16x16x32_bf16 v[52:55], v[158:161], v[174:177], v[52:55]
	v_mfma_f32_16x16x32_bf16 v[48:51], v[166:169], v[174:177], v[48:51]
	v_mfma_f32_16x16x32_bf16 v[36:39], v[158:161], v[182:185], v[36:39]
	v_mfma_f32_16x16x32_bf16 v[32:35], v[166:169], v[182:185], v[32:35]
	v_mfma_f32_16x16x32_bf16 v[20:23], v[158:161], v[190:193], v[20:23]
	v_mfma_f32_16x16x32_bf16 v[16:19], v[166:169], v[190:193], v[16:19]
	v_mfma_f32_16x16x32_bf16 v[4:7], v[158:161], v[200:203], v[4:7]
	v_mfma_f32_16x16x32_bf16 v[0:3], v[166:169], v[200:203], v[0:3]
	v_mfma_f32_16x16x32_bf16 v[52:55], v[162:165], v[178:181], v[52:55]
	v_mfma_f32_16x16x32_bf16 v[48:51], v[170:173], v[178:181], v[48:51]
	v_mfma_f32_16x16x32_bf16 v[36:39], v[162:165], v[186:189], v[36:39]
	v_mfma_f32_16x16x32_bf16 v[32:35], v[170:173], v[186:189], v[32:35]
	v_mfma_f32_16x16x32_bf16 v[20:23], v[162:165], v[194:197], v[20:23]
	v_mfma_f32_16x16x32_bf16 v[16:19], v[170:173], v[194:197], v[16:19]
	v_mfma_f32_16x16x32_bf16 v[4:7], v[162:165], v[208:211], v[4:7]
	v_mfma_f32_16x16x32_bf16 v[0:3], v[170:173], v[208:211], v[0:3]
	s_barrier
	s_setprio 0
	s_add_i32 s35, 0, 0x18000
	v_add_u32_e32 v140, s35, v206
	s_add_i32 s60, 0, 0x1c000
	ds_read_b128 v[142:145], v140
	ds_read_b128 v[146:149], v140 offset:1024
	ds_read_b128 v[150:153], v140 offset:2048
	ds_read_b128 v[154:157], v140 offset:3072
	v_add_u32_e32 v140, s60, v206
	ds_read_b128 v[158:161], v140
	ds_read_b128 v[162:165], v140 offset:1024
	ds_read_b128 v[166:169], v140 offset:2048
	ds_read_b128 v[170:173], v140 offset:3072
	s_add_u32 s10, s10, 0x40000
	s_addc_u32 s11, s11, 0
	s_mov_b32 m0, s27
	v_lshl_add_u64 v[216:217], s[10:11], 0, v[134:135]
	ds_read_b128 v[174:177], v207 offset:32768
	ds_read_b128 v[178:181], v207 offset:33792
	ds_read_b128 v[182:185], v207 offset:34816
	ds_read_b128 v[186:189], v207 offset:35840
	ds_read_b128 v[190:193], v207 offset:36864
	ds_read_b128 v[194:197], v207 offset:37888
	ds_read_b128 v[200:203], v207 offset:38912
	ds_read_b128 v[208:211], v207 offset:39936
	global_load_lds_dwordx4 v[216:217], off
	v_lshl_add_u64 v[216:217], s[10:11], 0, v[130:131]
	s_mov_b32 m0, s28
	s_nop 0
	global_load_lds_dwordx4 v[216:217], off
	s_waitcnt vmcnt(8)
	s_waitcnt lgkmcnt(0)
	s_barrier
	v_mfma_f32_16x16x32_bf16 v[124:127], v[142:145], v[174:177], v[124:127]
	s_setprio 1
	v_mfma_f32_16x16x32_bf16 v[120:123], v[150:153], v[174:177], v[120:123]
	v_mfma_f32_16x16x32_bf16 v[108:111], v[142:145], v[182:185], v[108:111]
	v_mfma_f32_16x16x32_bf16 v[104:107], v[150:153], v[182:185], v[104:107]
	v_mfma_f32_16x16x32_bf16 v[92:95], v[142:145], v[190:193], v[92:95]
	v_mfma_f32_16x16x32_bf16 v[88:91], v[150:153], v[190:193], v[88:91]
	v_mfma_f32_16x16x32_bf16 v[76:79], v[142:145], v[200:203], v[76:79]
	v_mfma_f32_16x16x32_bf16 v[72:75], v[150:153], v[200:203], v[72:75]
	v_mfma_f32_16x16x32_bf16 v[124:127], v[146:149], v[178:181], v[124:127]
	v_mfma_f32_16x16x32_bf16 v[120:123], v[154:157], v[178:181], v[120:123]
	v_mfma_f32_16x16x32_bf16 v[108:111], v[146:149], v[186:189], v[108:111]
	v_mfma_f32_16x16x32_bf16 v[104:107], v[154:157], v[186:189], v[104:107]
	v_mfma_f32_16x16x32_bf16 v[92:95], v[146:149], v[194:197], v[92:95]
	v_mfma_f32_16x16x32_bf16 v[88:91], v[154:157], v[194:197], v[88:91]
	v_mfma_f32_16x16x32_bf16 v[76:79], v[146:149], v[208:211], v[76:79]
	v_mfma_f32_16x16x32_bf16 v[72:75], v[154:157], v[208:211], v[72:75]
	v_mfma_f32_16x16x32_bf16 v[116:119], v[158:161], v[174:177], v[116:119]
	v_mfma_f32_16x16x32_bf16 v[112:115], v[166:169], v[174:177], v[112:115]
	v_mfma_f32_16x16x32_bf16 v[100:103], v[158:161], v[182:185], v[100:103]
	v_mfma_f32_16x16x32_bf16 v[96:99], v[166:169], v[182:185], v[96:99]
	v_mfma_f32_16x16x32_bf16 v[84:87], v[158:161], v[190:193], v[84:87]
	v_mfma_f32_16x16x32_bf16 v[80:83], v[166:169], v[190:193], v[80:83]
	v_mfma_f32_16x16x32_bf16 v[68:71], v[158:161], v[200:203], v[68:71]
	v_mfma_f32_16x16x32_bf16 v[64:67], v[166:169], v[200:203], v[64:67]
	v_mfma_f32_16x16x32_bf16 v[116:119], v[162:165], v[178:181], v[116:119]
	v_mfma_f32_16x16x32_bf16 v[112:115], v[170:173], v[178:181], v[112:115]
	v_mfma_f32_16x16x32_bf16 v[100:103], v[162:165], v[186:189], v[100:103]
	v_mfma_f32_16x16x32_bf16 v[96:99], v[170:173], v[186:189], v[96:99]
	v_mfma_f32_16x16x32_bf16 v[84:87], v[162:165], v[194:197], v[84:87]
	v_mfma_f32_16x16x32_bf16 v[80:83], v[170:173], v[194:197], v[80:83]
	v_mfma_f32_16x16x32_bf16 v[68:71], v[162:165], v[208:211], v[68:71]
	v_mfma_f32_16x16x32_bf16 v[64:67], v[170:173], v[208:211], v[64:67]
	s_barrier
	s_setprio 0
	s_add_i32 s10, s35, s13
	v_lshl_add_u64 v[198:199], v[198:199], 0, s[36:37]
	s_mov_b32 m0, s10
	ds_read_b128 v[174:177], v207 offset:49152
	ds_read_b128 v[178:181], v207 offset:50176
	ds_read_b128 v[182:185], v207 offset:51200
	ds_read_b128 v[186:189], v207 offset:52224
	ds_read_b128 v[190:193], v207 offset:53248
	ds_read_b128 v[194:197], v207 offset:54272
	ds_read_b128 v[200:203], v207 offset:55296
	ds_read_b128 v[208:211], v207 offset:56320
	global_load_lds_dwordx4 v[198:199], off
	s_add_i32 m0, s10, 0x2000
	s_add_u32 s8, s8, 0x40080
	v_lshl_add_u64 v[198:199], v[204:205], 0, s[36:37]
	s_addc_u32 s9, s9, 0
	s_add_i32 s10, s60, s13
	global_load_lds_dwordx4 v[198:199], off
	v_lshl_add_u64 v[198:199], s[8:9], 0, v[132:133]
	s_mov_b32 m0, s10
	s_nop 0
	global_load_lds_dwordx4 v[198:199], off
	v_lshl_add_u64 v[198:199], s[8:9], 0, v[128:129]
	s_add_i32 m0, s10, 0x2000
	s_nop 0
	global_load_lds_dwordx4 v[198:199], off
	v_lshl_add_u64 v[198:199], v[212:213], 0, s[36:37]
	s_mov_b32 m0, s29
	s_nop 0
	global_load_lds_dwordx4 v[198:199], off
	v_lshl_add_u64 v[198:199], v[214:215], 0, s[36:37]
	s_mov_b32 m0, s38
	s_nop 0
	global_load_lds_dwordx4 v[198:199], off
	s_waitcnt vmcnt(8)
	s_waitcnt lgkmcnt(0)
	s_barrier
	v_mfma_f32_16x16x32_bf16 v[60:63], v[142:145], v[174:177], v[60:63]
	s_setprio 1
	v_mfma_f32_16x16x32_bf16 v[56:59], v[150:153], v[174:177], v[56:59]
	v_mfma_f32_16x16x32_bf16 v[44:47], v[142:145], v[182:185], v[44:47]
	v_mfma_f32_16x16x32_bf16 v[40:43], v[150:153], v[182:185], v[40:43]
	v_mfma_f32_16x16x32_bf16 v[28:31], v[142:145], v[190:193], v[28:31]
	v_mfma_f32_16x16x32_bf16 v[24:27], v[150:153], v[190:193], v[24:27]
	v_mfma_f32_16x16x32_bf16 v[12:15], v[142:145], v[200:203], v[12:15]
	v_mfma_f32_16x16x32_bf16 v[8:11], v[150:153], v[200:203], v[8:11]
	v_mfma_f32_16x16x32_bf16 v[60:63], v[146:149], v[178:181], v[60:63]
	v_mfma_f32_16x16x32_bf16 v[56:59], v[154:157], v[178:181], v[56:59]
	v_mfma_f32_16x16x32_bf16 v[44:47], v[146:149], v[186:189], v[44:47]
	v_mfma_f32_16x16x32_bf16 v[40:43], v[154:157], v[186:189], v[40:43]
	v_mfma_f32_16x16x32_bf16 v[28:31], v[146:149], v[194:197], v[28:31]
	v_mfma_f32_16x16x32_bf16 v[24:27], v[154:157], v[194:197], v[24:27]
	v_mfma_f32_16x16x32_bf16 v[12:15], v[146:149], v[208:211], v[12:15]
	v_mfma_f32_16x16x32_bf16 v[8:11], v[154:157], v[208:211], v[8:11]
	v_mfma_f32_16x16x32_bf16 v[52:55], v[158:161], v[174:177], v[52:55]
	v_mfma_f32_16x16x32_bf16 v[48:51], v[166:169], v[174:177], v[48:51]
	v_mfma_f32_16x16x32_bf16 v[36:39], v[158:161], v[182:185], v[36:39]
	v_mfma_f32_16x16x32_bf16 v[32:35], v[166:169], v[182:185], v[32:35]
	v_mfma_f32_16x16x32_bf16 v[20:23], v[158:161], v[190:193], v[20:23]
	v_mfma_f32_16x16x32_bf16 v[16:19], v[166:169], v[190:193], v[16:19]
	v_mfma_f32_16x16x32_bf16 v[4:7], v[158:161], v[200:203], v[4:7]
	v_mfma_f32_16x16x32_bf16 v[0:3], v[166:169], v[200:203], v[0:3]
	v_mfma_f32_16x16x32_bf16 v[52:55], v[162:165], v[178:181], v[52:55]
	v_mfma_f32_16x16x32_bf16 v[48:51], v[170:173], v[178:181], v[48:51]
	v_mfma_f32_16x16x32_bf16 v[36:39], v[162:165], v[186:189], v[36:39]
	v_mfma_f32_16x16x32_bf16 v[32:35], v[170:173], v[186:189], v[32:35]
	v_mfma_f32_16x16x32_bf16 v[20:23], v[162:165], v[194:197], v[20:23]
	v_mfma_f32_16x16x32_bf16 v[16:19], v[170:173], v[194:197], v[16:19]
	v_mfma_f32_16x16x32_bf16 v[4:7], v[162:165], v[208:211], v[4:7]
	v_mfma_f32_16x16x32_bf16 v[0:3], v[170:173], v[208:211], v[0:3]
	s_barrier
	s_setprio 0
	s_add_i32 s53, s53, 2
	s_add_u32 s6, s6, 0x100
	s_addc_u32 s7, s7, 0
	s_add_u32 s43, s43, 0x100
	s_addc_u32 s51, s51, 0
	s_cmp_gt_u32 s53, 13
	s_cbranch_scc0 .LBB0_234
	s_and_b64 vcc, exec, s[48:49]
	s_cbranch_vccz .LBB0_237
	s_barrier

.LBB0_333:
	s_add_i32 s56, s8, 2
	s_add_u32 s9, s6, 0x8000
	s_addc_u32 s10, s7, 0
	s_cmp_eq_u32 s94, s8
	s_cselect_b32 s11, s43, s10
	s_cselect_b32 s10, s42, s9
	s_cselect_b32 s60, s54, s24
	s_cselect_b32 s61, s55, s38
	s_add_u32 s8, s10, 0x8000
	s_addc_u32 s9, s11, 0
	s_add_i32 s35, 0, 0x10000
	s_add_i32 s57, 0, 0x14000
	v_add_u32_e32 v142, s35, v178
	v_add_u32_e32 v168, s57, v178
	ds_read_b128 v[128:131], v142
	ds_read_b128 v[132:135], v142 offset:1024
	ds_read_b128 v[136:139], v142 offset:2048
	ds_read_b128 v[142:145], v142 offset:3072
	ds_read_b128 v[146:149], v168
	ds_read_b128 v[150:153], v168 offset:1024
	ds_read_b128 v[154:157], v168 offset:2048
	ds_read_b128 v[168:171], v168 offset:3072
	v_lshl_add_u64 v[176:177], s[6:7], 0, v[164:165]
	s_add_i32 m0, s75, 0xc000
	ds_read_b128 v[172:175], v179
	ds_read_b128 v[180:183], v179 offset:1024
	ds_read_b128 v[184:187], v179 offset:2048
	ds_read_b128 v[188:191], v179 offset:3072
	ds_read_b128 v[192:195], v179 offset:4096
	ds_read_b128 v[200:203], v179 offset:5120
	ds_read_b128 v[206:209], v179 offset:6144
	ds_read_b128 v[210:213], v179 offset:7168
	global_load_lds_dwordx4 v[176:177], off
	v_lshl_add_u64 v[176:177], s[6:7], 0, v[166:167]
	s_add_i32 m0, s75, 0xe000
	s_nop 0
	global_load_lds_dwordx4 v[176:177], off
	s_waitcnt vmcnt(8)
	s_waitcnt lgkmcnt(0)
	s_barrier
	v_mfma_f32_16x16x32_bf16 v[124:127], v[128:131], v[172:175], v[124:127]
	s_setprio 1
	v_mfma_f32_16x16x32_bf16 v[120:123], v[136:139], v[172:175], v[120:123]
	v_mfma_f32_16x16x32_bf16 v[108:111], v[128:131], v[184:187], v[108:111]
	v_mfma_f32_16x16x32_bf16 v[104:107], v[136:139], v[184:187], v[104:107]
	v_mfma_f32_16x16x32_bf16 v[92:95], v[128:131], v[192:195], v[92:95]
	v_mfma_f32_16x16x32_bf16 v[88:91], v[136:139], v[192:195], v[88:91]
	v_mfma_f32_16x16x32_bf16 v[76:79], v[128:131], v[206:209], v[76:79]
	v_mfma_f32_16x16x32_bf16 v[72:75], v[136:139], v[206:209], v[72:75]
	v_mfma_f32_16x16x32_bf16 v[124:127], v[132:135], v[180:183], v[124:127]
	v_mfma_f32_16x16x32_bf16 v[120:123], v[142:145], v[180:183], v[120:123]
	v_mfma_f32_16x16x32_bf16 v[108:111], v[132:135], v[188:191], v[108:111]
	v_mfma_f32_16x16x32_bf16 v[104:107], v[142:145], v[188:191], v[104:107]
	v_mfma_f32_16x16x32_bf16 v[92:95], v[132:135], v[200:203], v[92:95]
	v_mfma_f32_16x16x32_bf16 v[88:91], v[142:145], v[200:203], v[88:91]
	v_mfma_f32_16x16x32_bf16 v[76:79], v[132:135], v[210:213], v[76:79]
	v_mfma_f32_16x16x32_bf16 v[72:75], v[142:145], v[210:213], v[72:75]
	v_mfma_f32_16x16x32_bf16 v[116:119], v[146:149], v[172:175], v[116:119]
	v_mfma_f32_16x16x32_bf16 v[112:115], v[154:157], v[172:175], v[112:115]
	v_mfma_f32_16x16x32_bf16 v[100:103], v[146:149], v[184:187], v[100:103]
	v_mfma_f32_16x16x32_bf16 v[96:99], v[154:157], v[184:187], v[96:99]
	v_mfma_f32_16x16x32_bf16 v[84:87], v[146:149], v[192:195], v[84:87]
	v_mfma_f32_16x16x32_bf16 v[80:83], v[154:157], v[192:195], v[80:83]
	v_mfma_f32_16x16x32_bf16 v[68:71], v[146:149], v[206:209], v[68:71]
	v_mfma_f32_16x16x32_bf16 v[64:67], v[154:157], v[206:209], v[64:67]
	v_mfma_f32_16x16x32_bf16 v[116:119], v[150:153], v[180:183], v[116:119]
	v_mfma_f32_16x16x32_bf16 v[112:115], v[168:171], v[180:183], v[112:115]
	v_mfma_f32_16x16x32_bf16 v[100:103], v[150:153], v[188:191], v[100:103]
	v_mfma_f32_16x16x32_bf16 v[96:99], v[168:171], v[188:191], v[96:99]
	v_mfma_f32_16x16x32_bf16 v[84:87], v[150:153], v[200:203], v[84:87]
	v_mfma_f32_16x16x32_bf16 v[80:83], v[168:171], v[200:203], v[80:83]
	v_mfma_f32_16x16x32_bf16 v[68:71], v[150:153], v[210:213], v[68:71]
	v_mfma_f32_16x16x32_bf16 v[64:67], v[168:171], v[210:213], v[64:67]
	s_barrier
	s_setprio 0
	s_add_i32 s35, s35, s74
	v_lshl_add_u64 v[176:177], s[60:61], 0, v[140:141]
	s_mov_b32 m0, s35
	ds_read_b128 v[172:175], v179 offset:16384
	ds_read_b128 v[180:183], v179 offset:17408
	ds_read_b128 v[184:187], v179 offset:18432
	ds_read_b128 v[188:191], v179 offset:19456
	ds_read_b128 v[192:195], v179 offset:20480
	ds_read_b128 v[200:203], v179 offset:21504
	ds_read_b128 v[206:209], v179 offset:22528
	ds_read_b128 v[210:213], v179 offset:23552
	global_load_lds_dwordx4 v[176:177], off
	s_add_i32 m0, s35, 0x2000
	v_lshl_add_u64 v[196:197], s[60:61], 0, v[158:159]
	s_add_u32 s60, s60, s13
	s_addc_u32 s61, s61, 0
	s_add_i32 s35, s57, s74
	global_load_lds_dwordx4 v[196:197], off
	v_lshl_add_u64 v[198:199], s[60:61], 0, v[140:141]
	s_mov_b32 m0, s35
	v_lshl_add_u64 v[204:205], s[60:61], 0, v[158:159]
	global_load_lds_dwordx4 v[198:199], off
	s_add_i32 m0, s35, 0x2000
	v_lshl_add_u64 v[214:215], s[10:11], 0, v[162:163]
	global_load_lds_dwordx4 v[204:205], off
	s_mov_b32 m0, s75
	s_nop 0
	global_load_lds_dwordx4 v[214:215], off
	v_lshl_add_u64 v[214:215], s[10:11], 0, v[160:161]
	s_mov_b32 m0, s26
	s_nop 0
	global_load_lds_dwordx4 v[214:215], off
	s_waitcnt vmcnt(8)
	s_waitcnt lgkmcnt(0)
	s_barrier
	v_mfma_f32_16x16x32_bf16 v[60:63], v[128:131], v[172:175], v[60:63]
	s_setprio 1
	v_mfma_f32_16x16x32_bf16 v[56:59], v[136:139], v[172:175], v[56:59]
	v_mfma_f32_16x16x32_bf16 v[44:47], v[128:131], v[184:187], v[44:47]
	v_mfma_f32_16x16x32_bf16 v[40:43], v[136:139], v[184:187], v[40:43]
	v_mfma_f32_16x16x32_bf16 v[28:31], v[128:131], v[192:195], v[28:31]
	v_mfma_f32_16x16x32_bf16 v[24:27], v[136:139], v[192:195], v[24:27]
	v_mfma_f32_16x16x32_bf16 v[12:15], v[128:131], v[206:209], v[12:15]
	v_mfma_f32_16x16x32_bf16 v[8:11], v[136:139], v[206:209], v[8:11]
	v_mfma_f32_16x16x32_bf16 v[60:63], v[132:135], v[180:183], v[60:63]
	v_mfma_f32_16x16x32_bf16 v[56:59], v[142:145], v[180:183], v[56:59]
	v_mfma_f32_16x16x32_bf16 v[44:47], v[132:135], v[188:191], v[44:47]
	v_mfma_f32_16x16x32_bf16 v[40:43], v[142:145], v[188:191], v[40:43]
	v_mfma_f32_16x16x32_bf16 v[28:31], v[132:135], v[200:203], v[28:31]
	v_mfma_f32_16x16x32_bf16 v[24:27], v[142:145], v[200:203], v[24:27]
	v_mfma_f32_16x16x32_bf16 v[12:15], v[132:135], v[210:213], v[12:15]
	v_mfma_f32_16x16x32_bf16 v[8:11], v[142:145], v[210:213], v[8:11]
	v_mfma_f32_16x16x32_bf16 v[52:55], v[146:149], v[172:175], v[52:55]
	v_mfma_f32_16x16x32_bf16 v[48:51], v[154:157], v[172:175], v[48:51]
	v_mfma_f32_16x16x32_bf16 v[36:39], v[146:149], v[184:187], v[36:39]
	v_mfma_f32_16x16x32_bf16 v[32:35], v[154:157], v[184:187], v[32:35]
	v_mfma_f32_16x16x32_bf16 v[20:23], v[146:149], v[192:195], v[20:23]
	v_mfma_f32_16x16x32_bf16 v[16:19], v[154:157], v[192:195], v[16:19]
	v_mfma_f32_16x16x32_bf16 v[4:7], v[146:149], v[206:209], v[4:7]
	v_mfma_f32_16x16x32_bf16 v[0:3], v[154:157], v[206:209], v[0:3]
	v_mfma_f32_16x16x32_bf16 v[52:55], v[150:153], v[180:183], v[52:55]
	v_mfma_f32_16x16x32_bf16 v[48:51], v[168:171], v[180:183], v[48:51]
	v_mfma_f32_16x16x32_bf16 v[36:39], v[150:153], v[188:191], v[36:39]
	v_mfma_f32_16x16x32_bf16 v[32:35], v[168:171], v[188:191], v[32:35]
	v_mfma_f32_16x16x32_bf16 v[20:23], v[150:153], v[200:203], v[20:23]
	v_mfma_f32_16x16x32_bf16 v[16:19], v[168:171], v[200:203], v[16:19]
	v_mfma_f32_16x16x32_bf16 v[4:7], v[150:153], v[210:213], v[4:7]
	v_mfma_f32_16x16x32_bf16 v[0:3], v[168:171], v[210:213], v[0:3]
	s_barrier
	s_setprio 0
	s_add_i32 s35, 0, 0x18000
	s_add_i32 s57, 0, 0x1c000
	v_add_u32_e32 v142, s35, v178
	v_add_u32_e32 v168, s57, v178
	ds_read_b128 v[128:131], v142
	ds_read_b128 v[132:135], v142 offset:1024
	ds_read_b128 v[136:139], v142 offset:2048
	ds_read_b128 v[142:145], v142 offset:3072
	ds_read_b128 v[146:149], v168
	ds_read_b128 v[150:153], v168 offset:1024
	ds_read_b128 v[154:157], v168 offset:2048
	ds_read_b128 v[168:171], v168 offset:3072
	s_add_u32 s10, s10, s48
	s_addc_u32 s11, s11, 0
	s_mov_b32 m0, s27
	v_lshl_add_u64 v[214:215], s[10:11], 0, v[162:163]
	ds_read_b128 v[172:175], v179 offset:32768
	ds_read_b128 v[180:183], v179 offset:33792
	ds_read_b128 v[184:187], v179 offset:34816
	ds_read_b128 v[188:191], v179 offset:35840
	ds_read_b128 v[192:195], v179 offset:36864
	ds_read_b128 v[200:203], v179 offset:37888
	ds_read_b128 v[206:209], v179 offset:38912
	ds_read_b128 v[210:213], v179 offset:39936
	global_load_lds_dwordx4 v[214:215], off
	v_lshl_add_u64 v[214:215], s[10:11], 0, v[160:161]
	s_mov_b32 m0, s15
	s_nop 0
	global_load_lds_dwordx4 v[214:215], off
	s_waitcnt vmcnt(8)
	s_waitcnt lgkmcnt(0)
	s_barrier
	v_mfma_f32_16x16x32_bf16 v[124:127], v[128:131], v[172:175], v[124:127]
	s_setprio 1
	v_mfma_f32_16x16x32_bf16 v[120:123], v[136:139], v[172:175], v[120:123]
	v_mfma_f32_16x16x32_bf16 v[108:111], v[128:131], v[184:187], v[108:111]
	v_mfma_f32_16x16x32_bf16 v[104:107], v[136:139], v[184:187], v[104:107]
	v_mfma_f32_16x16x32_bf16 v[92:95], v[128:131], v[192:195], v[92:95]
	v_mfma_f32_16x16x32_bf16 v[88:91], v[136:139], v[192:195], v[88:91]
	v_mfma_f32_16x16x32_bf16 v[76:79], v[128:131], v[206:209], v[76:79]
	v_mfma_f32_16x16x32_bf16 v[72:75], v[136:139], v[206:209], v[72:75]
	v_mfma_f32_16x16x32_bf16 v[124:127], v[132:135], v[180:183], v[124:127]
	v_mfma_f32_16x16x32_bf16 v[120:123], v[142:145], v[180:183], v[120:123]
	v_mfma_f32_16x16x32_bf16 v[108:111], v[132:135], v[188:191], v[108:111]
	v_mfma_f32_16x16x32_bf16 v[104:107], v[142:145], v[188:191], v[104:107]
	v_mfma_f32_16x16x32_bf16 v[92:95], v[132:135], v[200:203], v[92:95]
	v_mfma_f32_16x16x32_bf16 v[88:91], v[142:145], v[200:203], v[88:91]
	v_mfma_f32_16x16x32_bf16 v[76:79], v[132:135], v[210:213], v[76:79]
	v_mfma_f32_16x16x32_bf16 v[72:75], v[142:145], v[210:213], v[72:75]
	v_mfma_f32_16x16x32_bf16 v[116:119], v[146:149], v[172:175], v[116:119]
	v_mfma_f32_16x16x32_bf16 v[112:115], v[154:157], v[172:175], v[112:115]
	v_mfma_f32_16x16x32_bf16 v[100:103], v[146:149], v[184:187], v[100:103]
	v_mfma_f32_16x16x32_bf16 v[96:99], v[154:157], v[184:187], v[96:99]
	v_mfma_f32_16x16x32_bf16 v[84:87], v[146:149], v[192:195], v[84:87]
	v_mfma_f32_16x16x32_bf16 v[80:83], v[154:157], v[192:195], v[80:83]
	v_mfma_f32_16x16x32_bf16 v[68:71], v[146:149], v[206:209], v[68:71]
	v_mfma_f32_16x16x32_bf16 v[64:67], v[154:157], v[206:209], v[64:67]
	v_mfma_f32_16x16x32_bf16 v[116:119], v[150:153], v[180:183], v[116:119]
	v_mfma_f32_16x16x32_bf16 v[112:115], v[168:171], v[180:183], v[112:115]
	v_mfma_f32_16x16x32_bf16 v[100:103], v[150:153], v[188:191], v[100:103]
	v_mfma_f32_16x16x32_bf16 v[96:99], v[168:171], v[188:191], v[96:99]
	v_mfma_f32_16x16x32_bf16 v[84:87], v[150:153], v[200:203], v[84:87]
	v_mfma_f32_16x16x32_bf16 v[80:83], v[168:171], v[200:203], v[80:83]
	v_mfma_f32_16x16x32_bf16 v[68:71], v[150:153], v[210:213], v[68:71]
	v_mfma_f32_16x16x32_bf16 v[64:67], v[168:171], v[210:213], v[64:67]
	s_barrier
	s_setprio 0
	s_add_i32 s10, s35, s74
	v_lshl_add_u64 v[176:177], v[176:177], 0, s[36:37]
	s_mov_b32 m0, s10
	ds_read_b128 v[172:175], v179 offset:49152
	ds_read_b128 v[180:183], v179 offset:50176
	ds_read_b128 v[184:187], v179 offset:51200
	ds_read_b128 v[188:191], v179 offset:52224
	ds_read_b128 v[192:195], v179 offset:53248
	ds_read_b128 v[200:203], v179 offset:54272
	ds_read_b128 v[206:209], v179 offset:55296
	ds_read_b128 v[210:213], v179 offset:56320
	global_load_lds_dwordx4 v[176:177], off
	v_lshl_add_u64 v[176:177], v[196:197], 0, s[36:37]
	s_add_i32 m0, s10, 0x2000
	s_add_i32 s10, s57, s74
	global_load_lds_dwordx4 v[176:177], off
	v_lshl_add_u64 v[176:177], v[198:199], 0, s[36:37]
	s_mov_b32 m0, s10
	s_nop 0
	global_load_lds_dwordx4 v[176:177], off
	v_lshl_add_u64 v[176:177], v[204:205], 0, s[36:37]
	s_add_i32 m0, s10, 0x2000
	s_nop 0
	global_load_lds_dwordx4 v[176:177], off
	v_lshl_add_u64 v[176:177], s[8:9], 0, v[162:163]
	s_mov_b32 m0, s28
	s_nop 0
	global_load_lds_dwordx4 v[176:177], off
	v_lshl_add_u64 v[176:177], s[8:9], 0, v[160:161]
	s_mov_b32 m0, s29
	s_nop 0
	global_load_lds_dwordx4 v[176:177], off
	s_waitcnt vmcnt(8)
	s_waitcnt lgkmcnt(0)
	s_barrier
	v_mfma_f32_16x16x32_bf16 v[60:63], v[128:131], v[172:175], v[60:63]
	s_setprio 1
	v_mfma_f32_16x16x32_bf16 v[56:59], v[136:139], v[172:175], v[56:59]
	v_mfma_f32_16x16x32_bf16 v[44:47], v[128:131], v[184:187], v[44:47]
	v_mfma_f32_16x16x32_bf16 v[40:43], v[136:139], v[184:187], v[40:43]
	v_mfma_f32_16x16x32_bf16 v[28:31], v[128:131], v[192:195], v[28:31]
	v_mfma_f32_16x16x32_bf16 v[24:27], v[136:139], v[192:195], v[24:27]
	v_mfma_f32_16x16x32_bf16 v[12:15], v[128:131], v[206:209], v[12:15]
	v_mfma_f32_16x16x32_bf16 v[8:11], v[136:139], v[206:209], v[8:11]
	v_mfma_f32_16x16x32_bf16 v[60:63], v[132:135], v[180:183], v[60:63]
	v_mfma_f32_16x16x32_bf16 v[56:59], v[142:145], v[180:183], v[56:59]
	v_mfma_f32_16x16x32_bf16 v[44:47], v[132:135], v[188:191], v[44:47]
	v_mfma_f32_16x16x32_bf16 v[40:43], v[142:145], v[188:191], v[40:43]
	v_mfma_f32_16x16x32_bf16 v[28:31], v[132:135], v[200:203], v[28:31]
	v_mfma_f32_16x16x32_bf16 v[24:27], v[142:145], v[200:203], v[24:27]
	v_mfma_f32_16x16x32_bf16 v[12:15], v[132:135], v[210:213], v[12:15]
	v_mfma_f32_16x16x32_bf16 v[8:11], v[142:145], v[210:213], v[8:11]
	v_mfma_f32_16x16x32_bf16 v[52:55], v[146:149], v[172:175], v[52:55]
	v_mfma_f32_16x16x32_bf16 v[48:51], v[154:157], v[172:175], v[48:51]
	v_mfma_f32_16x16x32_bf16 v[36:39], v[146:149], v[184:187], v[36:39]
	v_mfma_f32_16x16x32_bf16 v[32:35], v[154:157], v[184:187], v[32:35]
	v_mfma_f32_16x16x32_bf16 v[20:23], v[146:149], v[192:195], v[20:23]
	v_mfma_f32_16x16x32_bf16 v[16:19], v[154:157], v[192:195], v[16:19]
	v_mfma_f32_16x16x32_bf16 v[4:7], v[146:149], v[206:209], v[4:7]
	v_mfma_f32_16x16x32_bf16 v[0:3], v[154:157], v[206:209], v[0:3]
	v_mfma_f32_16x16x32_bf16 v[52:55], v[150:153], v[180:183], v[52:55]
	v_mfma_f32_16x16x32_bf16 v[48:51], v[168:171], v[180:183], v[48:51]
	v_mfma_f32_16x16x32_bf16 v[36:39], v[150:153], v[188:191], v[36:39]
	v_mfma_f32_16x16x32_bf16 v[32:35], v[168:171], v[188:191], v[32:35]
	v_mfma_f32_16x16x32_bf16 v[20:23], v[150:153], v[200:203], v[20:23]
	v_mfma_f32_16x16x32_bf16 v[16:19], v[168:171], v[200:203], v[16:19]
	v_mfma_f32_16x16x32_bf16 v[4:7], v[150:153], v[210:213], v[4:7]
	v_mfma_f32_16x16x32_bf16 v[0:3], v[168:171], v[210:213], v[0:3]
	s_barrier
	s_setprio 0
	s_add_u32 s24, s24, 0x100
	s_addc_u32 s38, s38, 0
	s_add_u32 s6, s6, 0x10000
	s_addc_u32 s7, s7, 0
	s_cmp_ge_u32 s56, s12
	s_mov_b32 s8, s56
	s_cbranch_scc0 .LBB0_333
	s_and_b64 vcc, exec, s[52:53]
	s_cbranch_vccz .LBB0_336
	s_barrier

.LBB0_375:
	s_add_i32 s24, s8, 2
	s_add_u32 s35, s6, 0x80
	s_addc_u32 s9, s7, 0
	s_add_i32 s38, 0, 0x10000
	s_cmp_eq_u32 s94, s8
	s_cselect_b32 s9, s43, s9
	s_cselect_b32 s8, s42, s35
	s_cselect_b32 s57, s55, s11
	s_cselect_b32 s56, s54, s10
	s_add_i32 s35, 0, 0x14000
	v_add_u32_e32 v142, s38, v178
	v_add_u32_e32 v168, s35, v178
	ds_read_b128 v[128:131], v142
	ds_read_b128 v[132:135], v142 offset:1024
	ds_read_b128 v[136:139], v142 offset:2048
	ds_read_b128 v[142:145], v142 offset:3072
	ds_read_b128 v[146:149], v168
	ds_read_b128 v[150:153], v168 offset:1024
	ds_read_b128 v[154:157], v168 offset:2048
	ds_read_b128 v[168:171], v168 offset:3072
	v_lshl_add_u64 v[176:177], s[6:7], 0, v[164:165]
	s_add_i32 m0, s15, 0xc000
	ds_read_b128 v[172:175], v179
	ds_read_b128 v[180:183], v179 offset:1024
	ds_read_b128 v[184:187], v179 offset:2048
	ds_read_b128 v[188:191], v179 offset:3072
	ds_read_b128 v[192:195], v179 offset:4096
	ds_read_b128 v[200:203], v179 offset:5120
	ds_read_b128 v[206:209], v179 offset:6144
	ds_read_b128 v[210:213], v179 offset:7168
	global_load_lds_dwordx4 v[176:177], off
	v_lshl_add_u64 v[176:177], s[6:7], 0, v[166:167]
	s_add_i32 m0, s15, 0xe000
	s_nop 0
	global_load_lds_dwordx4 v[176:177], off
	s_waitcnt vmcnt(8)
	s_waitcnt lgkmcnt(0)
	s_barrier
	v_mfma_f32_16x16x32_bf16 v[124:127], v[128:131], v[172:175], v[124:127]
	s_setprio 1
	v_mfma_f32_16x16x32_bf16 v[120:123], v[136:139], v[172:175], v[120:123]
	v_mfma_f32_16x16x32_bf16 v[108:111], v[128:131], v[184:187], v[108:111]
	v_mfma_f32_16x16x32_bf16 v[104:107], v[136:139], v[184:187], v[104:107]
	v_mfma_f32_16x16x32_bf16 v[92:95], v[128:131], v[192:195], v[92:95]
	v_mfma_f32_16x16x32_bf16 v[88:91], v[136:139], v[192:195], v[88:91]
	v_mfma_f32_16x16x32_bf16 v[76:79], v[128:131], v[206:209], v[76:79]
	v_mfma_f32_16x16x32_bf16 v[72:75], v[136:139], v[206:209], v[72:75]
	v_mfma_f32_16x16x32_bf16 v[124:127], v[132:135], v[180:183], v[124:127]
	v_mfma_f32_16x16x32_bf16 v[120:123], v[142:145], v[180:183], v[120:123]
	v_mfma_f32_16x16x32_bf16 v[108:111], v[132:135], v[188:191], v[108:111]
	v_mfma_f32_16x16x32_bf16 v[104:107], v[142:145], v[188:191], v[104:107]
	v_mfma_f32_16x16x32_bf16 v[92:95], v[132:135], v[200:203], v[92:95]
	v_mfma_f32_16x16x32_bf16 v[88:91], v[142:145], v[200:203], v[88:91]
	v_mfma_f32_16x16x32_bf16 v[76:79], v[132:135], v[210:213], v[76:79]
	v_mfma_f32_16x16x32_bf16 v[72:75], v[142:145], v[210:213], v[72:75]
	v_mfma_f32_16x16x32_bf16 v[116:119], v[146:149], v[172:175], v[116:119]
	v_mfma_f32_16x16x32_bf16 v[112:115], v[154:157], v[172:175], v[112:115]
	v_mfma_f32_16x16x32_bf16 v[100:103], v[146:149], v[184:187], v[100:103]
	v_mfma_f32_16x16x32_bf16 v[96:99], v[154:157], v[184:187], v[96:99]
	v_mfma_f32_16x16x32_bf16 v[84:87], v[146:149], v[192:195], v[84:87]
	v_mfma_f32_16x16x32_bf16 v[80:83], v[154:157], v[192:195], v[80:83]
	v_mfma_f32_16x16x32_bf16 v[68:71], v[146:149], v[206:209], v[68:71]
	v_mfma_f32_16x16x32_bf16 v[64:67], v[154:157], v[206:209], v[64:67]
	v_mfma_f32_16x16x32_bf16 v[116:119], v[150:153], v[180:183], v[116:119]
	v_mfma_f32_16x16x32_bf16 v[112:115], v[168:171], v[180:183], v[112:115]
	v_mfma_f32_16x16x32_bf16 v[100:103], v[150:153], v[188:191], v[100:103]
	v_mfma_f32_16x16x32_bf16 v[96:99], v[168:171], v[188:191], v[96:99]
	v_mfma_f32_16x16x32_bf16 v[84:87], v[150:153], v[200:203], v[84:87]
	v_mfma_f32_16x16x32_bf16 v[80:83], v[168:171], v[200:203], v[80:83]
	v_mfma_f32_16x16x32_bf16 v[68:71], v[150:153], v[210:213], v[68:71]
	v_mfma_f32_16x16x32_bf16 v[64:67], v[168:171], v[210:213], v[64:67]
	s_barrier
	s_setprio 0
	s_add_i32 s38, s38, s75
	v_lshl_add_u64 v[176:177], s[56:57], 0, v[140:141]
	s_mov_b32 m0, s38
	ds_read_b128 v[172:175], v179 offset:16384
	ds_read_b128 v[180:183], v179 offset:17408
	ds_read_b128 v[184:187], v179 offset:18432
	ds_read_b128 v[188:191], v179 offset:19456
	ds_read_b128 v[192:195], v179 offset:20480
	ds_read_b128 v[200:203], v179 offset:21504
	ds_read_b128 v[206:209], v179 offset:22528
	ds_read_b128 v[210:213], v179 offset:23552
	global_load_lds_dwordx4 v[176:177], off
	s_add_i32 m0, s38, 0x2000
	v_lshl_add_u64 v[196:197], s[56:57], 0, v[158:159]
	s_add_u32 s56, s56, s13
	s_addc_u32 s57, s57, 0
	s_add_i32 s35, s35, s75
	global_load_lds_dwordx4 v[196:197], off
	v_lshl_add_u64 v[198:199], s[56:57], 0, v[140:141]
	s_mov_b32 m0, s35
	v_lshl_add_u64 v[204:205], s[56:57], 0, v[158:159]
	global_load_lds_dwordx4 v[198:199], off
	s_add_i32 m0, s35, 0x2000
	v_lshl_add_u64 v[214:215], s[8:9], 0, v[162:163]
	global_load_lds_dwordx4 v[204:205], off
	s_mov_b32 m0, s15
	v_lshl_add_u64 v[216:217], s[8:9], 0, v[160:161]
	global_load_lds_dwordx4 v[214:215], off
	s_mov_b32 m0, s26
	s_nop 0
	global_load_lds_dwordx4 v[216:217], off
	s_waitcnt vmcnt(8)
	s_waitcnt lgkmcnt(0)
	s_barrier
	v_mfma_f32_16x16x32_bf16 v[60:63], v[128:131], v[172:175], v[60:63]
	s_setprio 1
	v_mfma_f32_16x16x32_bf16 v[56:59], v[136:139], v[172:175], v[56:59]
	v_mfma_f32_16x16x32_bf16 v[44:47], v[128:131], v[184:187], v[44:47]
	v_mfma_f32_16x16x32_bf16 v[40:43], v[136:139], v[184:187], v[40:43]
	v_mfma_f32_16x16x32_bf16 v[28:31], v[128:131], v[192:195], v[28:31]
	v_mfma_f32_16x16x32_bf16 v[24:27], v[136:139], v[192:195], v[24:27]
	v_mfma_f32_16x16x32_bf16 v[12:15], v[128:131], v[206:209], v[12:15]
	v_mfma_f32_16x16x32_bf16 v[8:11], v[136:139], v[206:209], v[8:11]
	v_mfma_f32_16x16x32_bf16 v[60:63], v[132:135], v[180:183], v[60:63]
	v_mfma_f32_16x16x32_bf16 v[56:59], v[142:145], v[180:183], v[56:59]
	v_mfma_f32_16x16x32_bf16 v[44:47], v[132:135], v[188:191], v[44:47]
	v_mfma_f32_16x16x32_bf16 v[40:43], v[142:145], v[188:191], v[40:43]
	v_mfma_f32_16x16x32_bf16 v[28:31], v[132:135], v[200:203], v[28:31]
	v_mfma_f32_16x16x32_bf16 v[24:27], v[142:145], v[200:203], v[24:27]
	v_mfma_f32_16x16x32_bf16 v[12:15], v[132:135], v[210:213], v[12:15]
	v_mfma_f32_16x16x32_bf16 v[8:11], v[142:145], v[210:213], v[8:11]
	v_mfma_f32_16x16x32_bf16 v[52:55], v[146:149], v[172:175], v[52:55]
	v_mfma_f32_16x16x32_bf16 v[48:51], v[154:157], v[172:175], v[48:51]
	v_mfma_f32_16x16x32_bf16 v[36:39], v[146:149], v[184:187], v[36:39]
	v_mfma_f32_16x16x32_bf16 v[32:35], v[154:157], v[184:187], v[32:35]
	v_mfma_f32_16x16x32_bf16 v[20:23], v[146:149], v[192:195], v[20:23]
	v_mfma_f32_16x16x32_bf16 v[16:19], v[154:157], v[192:195], v[16:19]
	v_mfma_f32_16x16x32_bf16 v[4:7], v[146:149], v[206:209], v[4:7]
	v_mfma_f32_16x16x32_bf16 v[0:3], v[154:157], v[206:209], v[0:3]
	v_mfma_f32_16x16x32_bf16 v[52:55], v[150:153], v[180:183], v[52:55]
	v_mfma_f32_16x16x32_bf16 v[48:51], v[168:171], v[180:183], v[48:51]
	v_mfma_f32_16x16x32_bf16 v[36:39], v[150:153], v[188:191], v[36:39]
	v_mfma_f32_16x16x32_bf16 v[32:35], v[168:171], v[188:191], v[32:35]
	v_mfma_f32_16x16x32_bf16 v[20:23], v[150:153], v[200:203], v[20:23]
	v_mfma_f32_16x16x32_bf16 v[16:19], v[168:171], v[200:203], v[16:19]
	v_mfma_f32_16x16x32_bf16 v[4:7], v[150:153], v[210:213], v[4:7]
	v_mfma_f32_16x16x32_bf16 v[0:3], v[168:171], v[210:213], v[0:3]
	s_barrier
	s_setprio 0
	s_add_i32 s35, 0, 0x18000
	s_add_i32 s38, 0, 0x1c000
	v_add_u32_e32 v142, s35, v178
	v_add_u32_e32 v168, s38, v178
	ds_read_b128 v[128:131], v142
	ds_read_b128 v[132:135], v142 offset:1024
	ds_read_b128 v[136:139], v142 offset:2048
	ds_read_b128 v[142:145], v142 offset:3072
	ds_read_b128 v[146:149], v168
	ds_read_b128 v[150:153], v168 offset:1024
	ds_read_b128 v[154:157], v168 offset:2048
	ds_read_b128 v[168:171], v168 offset:3072
	s_add_u32 s8, s8, s48
	s_addc_u32 s9, s9, 0
	s_mov_b32 m0, s27
	v_lshl_add_u64 v[218:219], s[8:9], 0, v[162:163]
	ds_read_b128 v[172:175], v179 offset:32768
	ds_read_b128 v[180:183], v179 offset:33792
	ds_read_b128 v[184:187], v179 offset:34816
	ds_read_b128 v[188:191], v179 offset:35840
	ds_read_b128 v[192:195], v179 offset:36864
	ds_read_b128 v[200:203], v179 offset:37888
	ds_read_b128 v[206:209], v179 offset:38912
	ds_read_b128 v[210:213], v179 offset:39936
	global_load_lds_dwordx4 v[218:219], off
	v_lshl_add_u64 v[218:219], s[8:9], 0, v[160:161]
	s_mov_b32 m0, s28
	s_nop 0
	global_load_lds_dwordx4 v[218:219], off
	s_waitcnt vmcnt(8)
	s_waitcnt lgkmcnt(0)
	s_barrier
	v_mfma_f32_16x16x32_bf16 v[124:127], v[128:131], v[172:175], v[124:127]
	s_setprio 1
	v_mfma_f32_16x16x32_bf16 v[120:123], v[136:139], v[172:175], v[120:123]
	v_mfma_f32_16x16x32_bf16 v[108:111], v[128:131], v[184:187], v[108:111]
	v_mfma_f32_16x16x32_bf16 v[104:107], v[136:139], v[184:187], v[104:107]
	v_mfma_f32_16x16x32_bf16 v[92:95], v[128:131], v[192:195], v[92:95]
	v_mfma_f32_16x16x32_bf16 v[88:91], v[136:139], v[192:195], v[88:91]
	v_mfma_f32_16x16x32_bf16 v[76:79], v[128:131], v[206:209], v[76:79]
	v_mfma_f32_16x16x32_bf16 v[72:75], v[136:139], v[206:209], v[72:75]
	v_mfma_f32_16x16x32_bf16 v[124:127], v[132:135], v[180:183], v[124:127]
	v_mfma_f32_16x16x32_bf16 v[120:123], v[142:145], v[180:183], v[120:123]
	v_mfma_f32_16x16x32_bf16 v[108:111], v[132:135], v[188:191], v[108:111]
	v_mfma_f32_16x16x32_bf16 v[104:107], v[142:145], v[188:191], v[104:107]
	v_mfma_f32_16x16x32_bf16 v[92:95], v[132:135], v[200:203], v[92:95]
	v_mfma_f32_16x16x32_bf16 v[88:91], v[142:145], v[200:203], v[88:91]
	v_mfma_f32_16x16x32_bf16 v[76:79], v[132:135], v[210:213], v[76:79]
	v_mfma_f32_16x16x32_bf16 v[72:75], v[142:145], v[210:213], v[72:75]
	v_mfma_f32_16x16x32_bf16 v[116:119], v[146:149], v[172:175], v[116:119]
	v_mfma_f32_16x16x32_bf16 v[112:115], v[154:157], v[172:175], v[112:115]
	v_mfma_f32_16x16x32_bf16 v[100:103], v[146:149], v[184:187], v[100:103]
	v_mfma_f32_16x16x32_bf16 v[96:99], v[154:157], v[184:187], v[96:99]
	v_mfma_f32_16x16x32_bf16 v[84:87], v[146:149], v[192:195], v[84:87]
	v_mfma_f32_16x16x32_bf16 v[80:83], v[154:157], v[192:195], v[80:83]
	v_mfma_f32_16x16x32_bf16 v[68:71], v[146:149], v[206:209], v[68:71]
	v_mfma_f32_16x16x32_bf16 v[64:67], v[154:157], v[206:209], v[64:67]
	v_mfma_f32_16x16x32_bf16 v[116:119], v[150:153], v[180:183], v[116:119]
	v_mfma_f32_16x16x32_bf16 v[112:115], v[168:171], v[180:183], v[112:115]
	v_mfma_f32_16x16x32_bf16 v[100:103], v[150:153], v[188:191], v[100:103]
	v_mfma_f32_16x16x32_bf16 v[96:99], v[168:171], v[188:191], v[96:99]
	v_mfma_f32_16x16x32_bf16 v[84:87], v[150:153], v[200:203], v[84:87]
	v_mfma_f32_16x16x32_bf16 v[80:83], v[168:171], v[200:203], v[80:83]
	v_mfma_f32_16x16x32_bf16 v[68:71], v[150:153], v[210:213], v[68:71]
	v_mfma_f32_16x16x32_bf16 v[64:67], v[168:171], v[210:213], v[64:67]
	s_barrier
	s_setprio 0
	s_add_i32 s8, s35, s75
	v_lshl_add_u64 v[176:177], v[176:177], 0, s[36:37]
	s_mov_b32 m0, s8
	ds_read_b128 v[172:175], v179 offset:49152
	ds_read_b128 v[180:183], v179 offset:50176
	ds_read_b128 v[184:187], v179 offset:51200
	ds_read_b128 v[188:191], v179 offset:52224
	ds_read_b128 v[192:195], v179 offset:53248
	ds_read_b128 v[200:203], v179 offset:54272
	ds_read_b128 v[206:209], v179 offset:55296
	ds_read_b128 v[210:213], v179 offset:56320
	global_load_lds_dwordx4 v[176:177], off
	v_lshl_add_u64 v[176:177], v[196:197], 0, s[36:37]
	s_add_i32 m0, s8, 0x2000
	s_add_i32 s8, s38, s75
	global_load_lds_dwordx4 v[176:177], off
	v_lshl_add_u64 v[176:177], v[198:199], 0, s[36:37]
	s_mov_b32 m0, s8
	s_nop 0
	global_load_lds_dwordx4 v[176:177], off
	v_lshl_add_u64 v[176:177], v[204:205], 0, s[36:37]
	s_add_i32 m0, s8, 0x2000
	s_nop 0
	global_load_lds_dwordx4 v[176:177], off
	v_lshl_add_u64 v[176:177], v[214:215], 0, s[36:37]
	s_mov_b32 m0, s29
	s_nop 0
	global_load_lds_dwordx4 v[176:177], off
	v_lshl_add_u64 v[176:177], v[216:217], 0, s[36:37]
	s_mov_b32 m0, s58
	s_nop 0
	global_load_lds_dwordx4 v[176:177], off
	s_waitcnt vmcnt(8)
	s_waitcnt lgkmcnt(0)
	s_barrier
	v_mfma_f32_16x16x32_bf16 v[60:63], v[128:131], v[172:175], v[60:63]
	s_setprio 1
	v_mfma_f32_16x16x32_bf16 v[56:59], v[136:139], v[172:175], v[56:59]
	v_mfma_f32_16x16x32_bf16 v[44:47], v[128:131], v[184:187], v[44:47]
	v_mfma_f32_16x16x32_bf16 v[40:43], v[136:139], v[184:187], v[40:43]
	v_mfma_f32_16x16x32_bf16 v[28:31], v[128:131], v[192:195], v[28:31]
	v_mfma_f32_16x16x32_bf16 v[24:27], v[136:139], v[192:195], v[24:27]
	v_mfma_f32_16x16x32_bf16 v[12:15], v[128:131], v[206:209], v[12:15]
	v_mfma_f32_16x16x32_bf16 v[8:11], v[136:139], v[206:209], v[8:11]
	v_mfma_f32_16x16x32_bf16 v[60:63], v[132:135], v[180:183], v[60:63]
	v_mfma_f32_16x16x32_bf16 v[56:59], v[142:145], v[180:183], v[56:59]
	v_mfma_f32_16x16x32_bf16 v[44:47], v[132:135], v[188:191], v[44:47]
	v_mfma_f32_16x16x32_bf16 v[40:43], v[142:145], v[188:191], v[40:43]
	v_mfma_f32_16x16x32_bf16 v[28:31], v[132:135], v[200:203], v[28:31]
	v_mfma_f32_16x16x32_bf16 v[24:27], v[142:145], v[200:203], v[24:27]
	v_mfma_f32_16x16x32_bf16 v[12:15], v[132:135], v[210:213], v[12:15]
	v_mfma_f32_16x16x32_bf16 v[8:11], v[142:145], v[210:213], v[8:11]
	v_mfma_f32_16x16x32_bf16 v[52:55], v[146:149], v[172:175], v[52:55]
	v_mfma_f32_16x16x32_bf16 v[48:51], v[154:157], v[172:175], v[48:51]
	v_mfma_f32_16x16x32_bf16 v[36:39], v[146:149], v[184:187], v[36:39]
	v_mfma_f32_16x16x32_bf16 v[32:35], v[154:157], v[184:187], v[32:35]
	v_mfma_f32_16x16x32_bf16 v[20:23], v[146:149], v[192:195], v[20:23]
	v_mfma_f32_16x16x32_bf16 v[16:19], v[154:157], v[192:195], v[16:19]
	v_mfma_f32_16x16x32_bf16 v[4:7], v[146:149], v[206:209], v[4:7]
	v_mfma_f32_16x16x32_bf16 v[0:3], v[154:157], v[206:209], v[0:3]
	v_mfma_f32_16x16x32_bf16 v[52:55], v[150:153], v[180:183], v[52:55]
	v_mfma_f32_16x16x32_bf16 v[48:51], v[168:171], v[180:183], v[48:51]
	v_mfma_f32_16x16x32_bf16 v[36:39], v[150:153], v[188:191], v[36:39]
	v_mfma_f32_16x16x32_bf16 v[32:35], v[168:171], v[188:191], v[32:35]
	v_mfma_f32_16x16x32_bf16 v[20:23], v[150:153], v[200:203], v[20:23]
	v_mfma_f32_16x16x32_bf16 v[16:19], v[168:171], v[200:203], v[16:19]
	v_mfma_f32_16x16x32_bf16 v[4:7], v[150:153], v[210:213], v[4:7]
	v_mfma_f32_16x16x32_bf16 v[0:3], v[168:171], v[210:213], v[0:3]
	s_barrier
	s_setprio 0
	s_add_u32 s6, s6, 0x100
	s_addc_u32 s7, s7, 0
	s_add_u32 s10, s10, 0x100
	s_addc_u32 s11, s11, 0
	s_cmp_ge_u32 s24, s12
	s_mov_b32 s8, s24
	s_cbranch_scc0 .LBB0_375
	s_and_b64 vcc, exec, s[52:53]
	s_cbranch_vccz .LBB0_378
	s_barrier

.LBB0_417:
	s_lshl_b64 s[10:11], s[52:53], 17
	s_add_u32 s56, s12, s10
	s_addc_u32 s57, s13, s11
	s_and_b64 s[10:11], s[40:41], exec
	s_cselect_b32 s11, s57, s9
	s_cselect_b32 s10, s56, s8
	s_add_i32 s55, 0, 0x10000
	s_add_i32 s38, 0, 0x14000
	v_add_u32_e32 v212, s55, v174
	v_add_u32_e32 v213, s38, v174
	ds_read_b128 v[0:3], v212
	ds_read_b128 v[4:7], v212 offset:1024
	ds_read_b128 v[8:11], v212 offset:2048
	ds_read_b128 v[12:15], v212 offset:3072
	ds_read_b128 v[16:19], v213
	ds_read_b128 v[20:23], v213 offset:1024
	ds_read_b128 v[24:27], v213 offset:2048
	ds_read_b128 v[28:31], v213 offset:3072
	s_add_u32 s60, s6, 0x40080
	s_addc_u32 s61, s7, 0
	s_add_i32 s59, s26, 0xc000
	v_lshl_add_u64 v[64:65], s[60:61], 0, v[162:163]
	s_mov_b32 m0, s59
	s_add_i32 s24, s26, 0xe000
	ds_read_b128 v[32:35], v175
	ds_read_b128 v[36:39], v175 offset:1024
	ds_read_b128 v[40:43], v175 offset:2048
	ds_read_b128 v[44:47], v175 offset:3072
	ds_read_b128 v[48:51], v175 offset:4096
	ds_read_b128 v[52:55], v175 offset:5120
	ds_read_b128 v[56:59], v175 offset:6144
	ds_read_b128 v[60:63], v175 offset:7168
	global_load_lds_dwordx4 v[64:65], off
	v_lshl_add_u64 v[64:65], s[60:61], 0, v[160:161]
	s_mov_b32 m0, s24
	s_nop 0
	global_load_lds_dwordx4 v[64:65], off
	s_waitcnt vmcnt(8)
	s_waitcnt lgkmcnt(0)
	s_barrier
	v_mfma_f32_16x16x32_bf16 v[64:67], v[0:3], v[32:35], 0
	s_setprio 1
	v_mfma_f32_16x16x32_bf16 v[68:71], v[8:11], v[32:35], 0
	v_mfma_f32_16x16x32_bf16 v[72:75], v[0:3], v[40:43], 0
	v_mfma_f32_16x16x32_bf16 v[76:79], v[8:11], v[40:43], 0
	v_mfma_f32_16x16x32_bf16 v[80:83], v[0:3], v[48:51], 0
	v_mfma_f32_16x16x32_bf16 v[84:87], v[8:11], v[48:51], 0
	v_mfma_f32_16x16x32_bf16 v[88:91], v[0:3], v[56:59], 0
	v_mfma_f32_16x16x32_bf16 v[92:95], v[8:11], v[56:59], 0
	v_mfma_f32_16x16x32_bf16 v[64:67], v[4:7], v[36:39], v[64:67]
	v_mfma_f32_16x16x32_bf16 v[68:71], v[12:15], v[36:39], v[68:71]
	v_mfma_f32_16x16x32_bf16 v[72:75], v[4:7], v[44:47], v[72:75]
	v_mfma_f32_16x16x32_bf16 v[76:79], v[12:15], v[44:47], v[76:79]
	v_mfma_f32_16x16x32_bf16 v[80:83], v[4:7], v[52:55], v[80:83]
	v_mfma_f32_16x16x32_bf16 v[84:87], v[12:15], v[52:55], v[84:87]
	v_mfma_f32_16x16x32_bf16 v[88:91], v[4:7], v[60:63], v[88:91]
	v_mfma_f32_16x16x32_bf16 v[92:95], v[12:15], v[60:63], v[92:95]
	v_mfma_f32_16x16x32_bf16 v[96:99], v[16:19], v[32:35], 0
	v_mfma_f32_16x16x32_bf16 v[32:35], v[24:27], v[32:35], 0
	v_mfma_f32_16x16x32_bf16 v[96:99], v[20:23], v[36:39], v[96:99]
	v_mfma_f32_16x16x32_bf16 v[32:35], v[28:31], v[36:39], v[32:35]
	v_mfma_f32_16x16x32_bf16 v[36:39], v[16:19], v[40:43], 0
	v_mfma_f32_16x16x32_bf16 v[40:43], v[24:27], v[40:43], 0
	v_mfma_f32_16x16x32_bf16 v[36:39], v[20:23], v[44:47], v[36:39]
	v_mfma_f32_16x16x32_bf16 v[40:43], v[28:31], v[44:47], v[40:43]
	v_mfma_f32_16x16x32_bf16 v[44:47], v[16:19], v[48:51], 0
	v_mfma_f32_16x16x32_bf16 v[48:51], v[24:27], v[48:51], 0
	v_mfma_f32_16x16x32_bf16 v[44:47], v[20:23], v[52:55], v[44:47]
	v_mfma_f32_16x16x32_bf16 v[48:51], v[28:31], v[52:55], v[48:51]
	v_mfma_f32_16x16x32_bf16 v[52:55], v[16:19], v[56:59], 0
	v_mfma_f32_16x16x32_bf16 v[56:59], v[24:27], v[56:59], 0
	v_mfma_f32_16x16x32_bf16 v[52:55], v[20:23], v[60:63], v[52:55]
	v_mfma_f32_16x16x32_bf16 v[56:59], v[28:31], v[60:63], v[56:59]
	s_barrier
	s_setprio 0
	s_add_i32 s55, s55, s15
	v_lshl_add_u64 v[172:173], s[8:9], 0, v[140:141]
	s_mov_b64 s[2:3], 0x100
	s_add_i32 s35, s55, 0x2000
	v_lshl_add_u64 v[128:129], v[172:173], 0, s[2:3]
	s_mov_b32 m0, s55
	v_lshl_add_u64 v[196:197], s[8:9], 0, v[158:159]
	s_add_u32 s60, s8, 0x10100
	ds_read_b128 v[60:63], v175 offset:16384
	ds_read_b128 v[100:103], v175 offset:17408
	ds_read_b128 v[104:107], v175 offset:18432
	ds_read_b128 v[108:111], v175 offset:19456
	ds_read_b128 v[112:115], v175 offset:20480
	ds_read_b128 v[116:119], v175 offset:21504
	ds_read_b128 v[120:123], v175 offset:22528
	ds_read_b128 v[124:127], v175 offset:23552
	global_load_lds_dwordx4 v[128:129], off
	v_lshl_add_u64 v[128:129], v[196:197], 0, s[2:3]
	s_mov_b32 m0, s35
	s_addc_u32 s61, s9, 0
	s_add_i32 s38, s38, s15
	global_load_lds_dwordx4 v[128:129], off
	v_lshl_add_u64 v[128:129], s[60:61], 0, v[140:141]
	s_mov_b32 m0, s38
	s_add_i32 s53, s38, 0x2000
	global_load_lds_dwordx4 v[128:129], off
	v_lshl_add_u64 v[128:129], s[60:61], 0, v[158:159]
	s_mov_b32 m0, s53
	v_lshl_add_u64 v[198:199], s[6:7], 0, v[162:163]
	global_load_lds_dwordx4 v[128:129], off
	v_lshl_add_u64 v[128:129], v[198:199], 0, s[2:3]
	s_mov_b32 m0, s26
	v_lshl_add_u64 v[204:205], s[6:7], 0, v[160:161]
	global_load_lds_dwordx4 v[128:129], off
	v_lshl_add_u64 v[128:129], v[204:205], 0, s[2:3]
	s_mov_b32 m0, s27
	s_nop 0
	global_load_lds_dwordx4 v[128:129], off
	s_waitcnt vmcnt(8)
	s_waitcnt lgkmcnt(0)
	s_barrier
	v_mfma_f32_16x16x32_bf16 v[128:131], v[0:3], v[60:63], 0
	s_setprio 1
	v_mfma_f32_16x16x32_bf16 v[136:139], v[0:3], v[104:107], 0
	v_mfma_f32_16x16x32_bf16 v[146:149], v[0:3], v[112:115], 0
	v_mfma_f32_16x16x32_bf16 v[0:3], v[0:3], v[120:123], 0
	v_mfma_f32_16x16x32_bf16 v[128:131], v[4:7], v[100:103], v[128:131]
	v_mfma_f32_16x16x32_bf16 v[132:135], v[8:11], v[60:63], 0
	v_mfma_f32_16x16x32_bf16 v[136:139], v[4:7], v[108:111], v[136:139]
	v_mfma_f32_16x16x32_bf16 v[146:149], v[4:7], v[116:119], v[146:149]
	v_mfma_f32_16x16x32_bf16 v[0:3], v[4:7], v[124:127], v[0:3]
	v_mfma_f32_16x16x32_bf16 v[4:7], v[8:11], v[120:123], 0
	v_mfma_f32_16x16x32_bf16 v[132:135], v[12:15], v[100:103], v[132:135]
	v_mfma_f32_16x16x32_bf16 v[142:145], v[8:11], v[104:107], 0
	v_mfma_f32_16x16x32_bf16 v[150:153], v[8:11], v[112:115], 0
	v_mfma_f32_16x16x32_bf16 v[4:7], v[12:15], v[124:127], v[4:7]
	v_mfma_f32_16x16x32_bf16 v[142:145], v[12:15], v[108:111], v[142:145]
	v_mfma_f32_16x16x32_bf16 v[150:153], v[12:15], v[116:119], v[150:153]
	v_mfma_f32_16x16x32_bf16 v[8:11], v[16:19], v[60:63], 0
	v_mfma_f32_16x16x32_bf16 v[12:15], v[24:27], v[60:63], 0
	v_mfma_f32_16x16x32_bf16 v[8:11], v[20:23], v[100:103], v[8:11]
	v_mfma_f32_16x16x32_bf16 v[12:15], v[28:31], v[100:103], v[12:15]
	v_mfma_f32_16x16x32_bf16 v[60:63], v[16:19], v[104:107], 0
	v_mfma_f32_16x16x32_bf16 v[100:103], v[24:27], v[104:107], 0
	v_mfma_f32_16x16x32_bf16 v[104:107], v[16:19], v[112:115], 0
	v_mfma_f32_16x16x32_bf16 v[16:19], v[16:19], v[120:123], 0
	v_mfma_f32_16x16x32_bf16 v[60:63], v[20:23], v[108:111], v[60:63]
	v_mfma_f32_16x16x32_bf16 v[100:103], v[28:31], v[108:111], v[100:103]
	v_mfma_f32_16x16x32_bf16 v[104:107], v[20:23], v[116:119], v[104:107]
	v_mfma_f32_16x16x32_bf16 v[108:111], v[24:27], v[112:115], 0
	v_mfma_f32_16x16x32_bf16 v[16:19], v[20:23], v[124:127], v[16:19]
	v_mfma_f32_16x16x32_bf16 v[20:23], v[24:27], v[120:123], 0
	v_mfma_f32_16x16x32_bf16 v[108:111], v[28:31], v[116:119], v[108:111]
	v_mfma_f32_16x16x32_bf16 v[20:23], v[28:31], v[124:127], v[20:23]
	s_barrier
	s_setprio 0
	s_add_i32 s58, 0, 0x18000
	s_add_i32 s76, 0, 0x1c000
	v_add_u32_e32 v222, s58, v174
	v_add_u32_e32 v223, s76, v174
	ds_read_b128 v[24:27], v222
	ds_read_b128 v[28:31], v222 offset:1024
	ds_read_b128 v[112:115], v222 offset:2048
	ds_read_b128 v[116:119], v222 offset:3072
	ds_read_b128 v[120:123], v223
	ds_read_b128 v[124:127], v223 offset:1024
	ds_read_b128 v[154:157], v223 offset:2048
	ds_read_b128 v[164:167], v223 offset:3072
	s_add_u32 s60, s6, 0x40100
	s_addc_u32 s61, s7, 0
	s_mov_b32 m0, s28
	v_lshl_add_u64 v[210:211], s[60:61], 0, v[162:163]
	ds_read_b128 v[168:171], v175 offset:32768
	ds_read_b128 v[176:179], v175 offset:33792
	ds_read_b128 v[180:183], v175 offset:34816
	ds_read_b128 v[184:187], v175 offset:35840
	ds_read_b128 v[188:191], v175 offset:36864
	ds_read_b128 v[192:195], v175 offset:37888
	ds_read_b128 v[200:203], v175 offset:38912
	ds_read_b128 v[206:209], v175 offset:39936
	global_load_lds_dwordx4 v[210:211], off
	v_lshl_add_u64 v[210:211], s[60:61], 0, v[160:161]
	s_mov_b32 m0, s29
	s_nop 0
	global_load_lds_dwordx4 v[210:211], off
	s_waitcnt vmcnt(8)
	s_waitcnt lgkmcnt(0)
	s_barrier
	v_mfma_f32_16x16x32_bf16 v[64:67], v[24:27], v[168:171], v[64:67]
	s_setprio 1
	v_mfma_f32_16x16x32_bf16 v[68:71], v[112:115], v[168:171], v[68:71]
	v_mfma_f32_16x16x32_bf16 v[72:75], v[24:27], v[180:183], v[72:75]
	v_mfma_f32_16x16x32_bf16 v[76:79], v[112:115], v[180:183], v[76:79]
	v_mfma_f32_16x16x32_bf16 v[80:83], v[24:27], v[188:191], v[80:83]
	v_mfma_f32_16x16x32_bf16 v[84:87], v[112:115], v[188:191], v[84:87]
	v_mfma_f32_16x16x32_bf16 v[88:91], v[24:27], v[200:203], v[88:91]
	v_mfma_f32_16x16x32_bf16 v[92:95], v[112:115], v[200:203], v[92:95]
	v_mfma_f32_16x16x32_bf16 v[64:67], v[28:31], v[176:179], v[64:67]
	v_mfma_f32_16x16x32_bf16 v[68:71], v[116:119], v[176:179], v[68:71]
	v_mfma_f32_16x16x32_bf16 v[72:75], v[28:31], v[184:187], v[72:75]
	v_mfma_f32_16x16x32_bf16 v[76:79], v[116:119], v[184:187], v[76:79]
	v_mfma_f32_16x16x32_bf16 v[80:83], v[28:31], v[192:195], v[80:83]
	v_mfma_f32_16x16x32_bf16 v[84:87], v[116:119], v[192:195], v[84:87]
	v_mfma_f32_16x16x32_bf16 v[88:91], v[28:31], v[206:209], v[88:91]
	v_mfma_f32_16x16x32_bf16 v[92:95], v[116:119], v[206:209], v[92:95]
	v_mfma_f32_16x16x32_bf16 v[96:99], v[120:123], v[168:171], v[96:99]
	v_mfma_f32_16x16x32_bf16 v[32:35], v[154:157], v[168:171], v[32:35]
	v_mfma_f32_16x16x32_bf16 v[36:39], v[120:123], v[180:183], v[36:39]
	v_mfma_f32_16x16x32_bf16 v[40:43], v[154:157], v[180:183], v[40:43]
	v_mfma_f32_16x16x32_bf16 v[44:47], v[120:123], v[188:191], v[44:47]
	v_mfma_f32_16x16x32_bf16 v[48:51], v[154:157], v[188:191], v[48:51]
	v_mfma_f32_16x16x32_bf16 v[52:55], v[120:123], v[200:203], v[52:55]
	v_mfma_f32_16x16x32_bf16 v[56:59], v[154:157], v[200:203], v[56:59]
	v_mfma_f32_16x16x32_bf16 v[96:99], v[124:127], v[176:179], v[96:99]
	v_mfma_f32_16x16x32_bf16 v[32:35], v[164:167], v[176:179], v[32:35]
	v_mfma_f32_16x16x32_bf16 v[36:39], v[124:127], v[184:187], v[36:39]
	v_mfma_f32_16x16x32_bf16 v[40:43], v[164:167], v[184:187], v[40:43]
	v_mfma_f32_16x16x32_bf16 v[44:47], v[124:127], v[192:195], v[44:47]
	v_mfma_f32_16x16x32_bf16 v[48:51], v[164:167], v[192:195], v[48:51]
	v_mfma_f32_16x16x32_bf16 v[52:55], v[124:127], v[206:209], v[52:55]
	v_mfma_f32_16x16x32_bf16 v[56:59], v[164:167], v[206:209], v[56:59]
	s_barrier
	s_setprio 0
	s_add_i32 s60, s58, s15
	s_mov_b64 s[2:3], 0x180
	s_add_i32 s58, s60, 0x2000
	v_lshl_add_u64 v[172:173], v[172:173], 0, s[2:3]
	s_mov_b32 m0, s60
	s_add_u32 s84, s8, 0x10180
	ds_read_b128 v[168:171], v175 offset:49152
	ds_read_b128 v[176:179], v175 offset:50176
	ds_read_b128 v[180:183], v175 offset:51200
	ds_read_b128 v[184:187], v175 offset:52224
	ds_read_b128 v[188:191], v175 offset:53248
	ds_read_b128 v[192:195], v175 offset:54272
	ds_read_b128 v[200:203], v175 offset:55296
	ds_read_b128 v[206:209], v175 offset:56320
	global_load_lds_dwordx4 v[172:173], off
	v_lshl_add_u64 v[172:173], v[196:197], 0, s[2:3]
	s_mov_b32 m0, s58
	s_addc_u32 s85, s9, 0
	s_add_i32 s8, s76, s15
	global_load_lds_dwordx4 v[172:173], off
	v_lshl_add_u64 v[172:173], s[84:85], 0, v[140:141]
	s_mov_b32 m0, s8
	s_add_i32 s9, s8, 0x2000
	global_load_lds_dwordx4 v[172:173], off
	v_lshl_add_u64 v[172:173], s[84:85], 0, v[158:159]
	s_mov_b32 m0, s9
	s_nop 0
	global_load_lds_dwordx4 v[172:173], off
	v_lshl_add_u64 v[172:173], v[198:199], 0, s[2:3]
	s_mov_b32 m0, s74
	s_nop 0
	global_load_lds_dwordx4 v[172:173], off
	v_lshl_add_u64 v[172:173], v[204:205], 0, s[2:3]
	s_mov_b32 m0, s75
	s_nop 0
	global_load_lds_dwordx4 v[172:173], off
	s_waitcnt vmcnt(8)
	s_waitcnt lgkmcnt(0)
	s_barrier
	v_mfma_f32_16x16x32_bf16 v[132:135], v[112:115], v[168:171], v[132:135]
	s_setprio 1
	v_mfma_f32_16x16x32_bf16 v[136:139], v[24:27], v[180:183], v[136:139]
	v_mfma_f32_16x16x32_bf16 v[0:3], v[24:27], v[200:203], v[0:3]
	v_mfma_f32_16x16x32_bf16 v[4:7], v[112:115], v[200:203], v[4:7]
	v_mfma_f32_16x16x32_bf16 v[128:131], v[24:27], v[168:171], v[128:131]
	v_mfma_f32_16x16x32_bf16 v[132:135], v[116:119], v[176:179], v[132:135]
	v_mfma_f32_16x16x32_bf16 v[136:139], v[28:31], v[184:187], v[136:139]
	v_mfma_f32_16x16x32_bf16 v[142:145], v[112:115], v[180:183], v[142:145]
	v_mfma_f32_16x16x32_bf16 v[146:149], v[24:27], v[188:191], v[146:149]
	v_mfma_f32_16x16x32_bf16 v[150:153], v[112:115], v[188:191], v[150:153]
	v_mfma_f32_16x16x32_bf16 v[0:3], v[28:31], v[206:209], v[0:3]
	v_mfma_f32_16x16x32_bf16 v[4:7], v[116:119], v[206:209], v[4:7]
	v_mfma_f32_16x16x32_bf16 v[128:131], v[28:31], v[176:179], v[128:131]
	v_mfma_f32_16x16x32_bf16 v[142:145], v[116:119], v[184:187], v[142:145]
	v_mfma_f32_16x16x32_bf16 v[146:149], v[28:31], v[192:195], v[146:149]
	v_mfma_f32_16x16x32_bf16 v[150:153], v[116:119], v[192:195], v[150:153]
	v_mfma_f32_16x16x32_bf16 v[8:11], v[120:123], v[168:171], v[8:11]
	v_mfma_f32_16x16x32_bf16 v[12:15], v[154:157], v[168:171], v[12:15]
	v_mfma_f32_16x16x32_bf16 v[24:27], v[120:123], v[180:183], v[60:63]
	v_mfma_f32_16x16x32_bf16 v[28:31], v[154:157], v[180:183], v[100:103]
	v_mfma_f32_16x16x32_bf16 v[60:63], v[120:123], v[188:191], v[104:107]
	v_mfma_f32_16x16x32_bf16 v[100:103], v[154:157], v[188:191], v[108:111]
	v_mfma_f32_16x16x32_bf16 v[16:19], v[120:123], v[200:203], v[16:19]
	v_mfma_f32_16x16x32_bf16 v[20:23], v[154:157], v[200:203], v[20:23]
	v_mfma_f32_16x16x32_bf16 v[8:11], v[124:127], v[176:179], v[8:11]
	v_mfma_f32_16x16x32_bf16 v[12:15], v[164:167], v[176:179], v[12:15]
	v_mfma_f32_16x16x32_bf16 v[24:27], v[124:127], v[184:187], v[24:27]
	v_mfma_f32_16x16x32_bf16 v[28:31], v[164:167], v[184:187], v[28:31]
	v_mfma_f32_16x16x32_bf16 v[60:63], v[124:127], v[192:195], v[60:63]
	v_mfma_f32_16x16x32_bf16 v[100:103], v[164:167], v[192:195], v[100:103]
	v_mfma_f32_16x16x32_bf16 v[16:19], v[124:127], v[206:209], v[16:19]
	v_mfma_f32_16x16x32_bf16 v[20:23], v[164:167], v[206:209], v[20:23]
	s_barrier
	s_setprio 0
	ds_read_b128 v[104:107], v212
	ds_read_b128 v[108:111], v212 offset:1024
	ds_read_b128 v[112:115], v212 offset:2048
	ds_read_b128 v[116:119], v212 offset:3072
	ds_read_b128 v[120:123], v213
	ds_read_b128 v[124:127], v213 offset:1024
	ds_read_b128 v[154:157], v213 offset:2048
	ds_read_b128 v[164:167], v213 offset:3072
	s_add_u32 s6, s6, 0x40180
	s_addc_u32 s7, s7, 0
	s_mov_b32 m0, s59
	v_lshl_add_u64 v[172:173], s[6:7], 0, v[162:163]
	ds_read_b128 v[168:171], v175
	ds_read_b128 v[176:179], v175 offset:1024
	ds_read_b128 v[180:183], v175 offset:2048
	ds_read_b128 v[184:187], v175 offset:3072
	ds_read_b128 v[188:191], v175 offset:4096
	ds_read_b128 v[192:195], v175 offset:5120
	ds_read_b128 v[200:203], v175 offset:6144
	ds_read_b128 v[206:209], v175 offset:7168
	global_load_lds_dwordx4 v[172:173], off
	v_lshl_add_u64 v[172:173], s[6:7], 0, v[160:161]
	s_mov_b32 m0, s24
	s_nop 0
	global_load_lds_dwordx4 v[172:173], off
	s_waitcnt vmcnt(8)
	s_waitcnt lgkmcnt(0)
	s_barrier
	v_mfma_f32_16x16x32_bf16 v[64:67], v[104:107], v[168:171], v[64:67]
	s_setprio 1
	v_mfma_f32_16x16x32_bf16 v[68:71], v[112:115], v[168:171], v[68:71]
	v_mfma_f32_16x16x32_bf16 v[72:75], v[104:107], v[180:183], v[72:75]
	v_mfma_f32_16x16x32_bf16 v[76:79], v[112:115], v[180:183], v[76:79]
	v_mfma_f32_16x16x32_bf16 v[80:83], v[104:107], v[188:191], v[80:83]
	v_mfma_f32_16x16x32_bf16 v[84:87], v[112:115], v[188:191], v[84:87]
	v_mfma_f32_16x16x32_bf16 v[88:91], v[104:107], v[200:203], v[88:91]
	v_mfma_f32_16x16x32_bf16 v[64:67], v[108:111], v[176:179], v[64:67]
	v_mfma_f32_16x16x32_bf16 v[68:71], v[116:119], v[176:179], v[68:71]
	v_mfma_f32_16x16x32_bf16 v[72:75], v[108:111], v[184:187], v[72:75]
	v_mfma_f32_16x16x32_bf16 v[76:79], v[116:119], v[184:187], v[76:79]
	v_mfma_f32_16x16x32_bf16 v[80:83], v[108:111], v[192:195], v[80:83]
	v_mfma_f32_16x16x32_bf16 v[84:87], v[116:119], v[192:195], v[84:87]
	v_mfma_f32_16x16x32_bf16 v[210:213], v[108:111], v[206:209], v[88:91]
	v_mfma_f32_16x16x32_bf16 v[88:91], v[112:115], v[200:203], v[92:95]
	v_mfma_f32_16x16x32_bf16 v[214:217], v[116:119], v[206:209], v[88:91]
	v_mfma_f32_16x16x32_bf16 v[88:91], v[120:123], v[168:171], v[96:99]
	v_mfma_f32_16x16x32_bf16 v[32:35], v[154:157], v[168:171], v[32:35]
	v_mfma_f32_16x16x32_bf16 v[36:39], v[120:123], v[180:183], v[36:39]
	v_mfma_f32_16x16x32_bf16 v[40:43], v[154:157], v[180:183], v[40:43]
	v_mfma_f32_16x16x32_bf16 v[44:47], v[120:123], v[188:191], v[44:47]
	v_mfma_f32_16x16x32_bf16 v[48:51], v[154:157], v[188:191], v[48:51]
	v_mfma_f32_16x16x32_bf16 v[52:55], v[120:123], v[200:203], v[52:55]
	v_mfma_f32_16x16x32_bf16 v[56:59], v[154:157], v[200:203], v[56:59]
	v_mfma_f32_16x16x32_bf16 v[96:99], v[124:127], v[176:179], v[88:91]
	v_mfma_f32_16x16x32_bf16 v[32:35], v[164:167], v[176:179], v[32:35]
	v_mfma_f32_16x16x32_bf16 v[36:39], v[124:127], v[184:187], v[36:39]
	v_mfma_f32_16x16x32_bf16 v[40:43], v[164:167], v[184:187], v[40:43]
	v_mfma_f32_16x16x32_bf16 v[44:47], v[124:127], v[192:195], v[44:47]
	v_mfma_f32_16x16x32_bf16 v[48:51], v[164:167], v[192:195], v[48:51]
	v_mfma_f32_16x16x32_bf16 v[52:55], v[124:127], v[206:209], v[52:55]
	v_mfma_f32_16x16x32_bf16 v[56:59], v[164:167], v[206:209], v[56:59]
	s_barrier
	s_setprio 0
	s_mov_b32 m0, s55
	v_lshl_add_u64 v[172:173], s[10:11], 0, v[140:141]
	s_add_u32 s6, s10, 0x10000
	ds_read_b128 v[88:91], v175 offset:16384
	ds_read_b128 v[92:95], v175 offset:17408
	ds_read_b128 v[168:171], v175 offset:18432
	ds_read_b128 v[176:179], v175 offset:19456
	ds_read_b128 v[180:183], v175 offset:20480
	ds_read_b128 v[184:187], v175 offset:21504
	ds_read_b128 v[188:191], v175 offset:22528
	ds_read_b128 v[192:195], v175 offset:23552
	global_load_lds_dwordx4 v[172:173], off
	v_lshl_add_u64 v[196:197], s[10:11], 0, v[158:159]
	s_mov_b32 m0, s35
	s_addc_u32 s7, s11, 0
	global_load_lds_dwordx4 v[196:197], off
	v_lshl_add_u64 v[198:199], s[6:7], 0, v[140:141]
	s_mov_b32 m0, s38
	v_lshl_add_u64 v[204:205], s[42:43], 0, v[160:161]
	global_load_lds_dwordx4 v[198:199], off
	v_lshl_add_u64 v[198:199], s[6:7], 0, v[158:159]
	s_mov_b32 m0, s53
	s_nop 0
	global_load_lds_dwordx4 v[198:199], off
	v_lshl_add_u64 v[198:199], s[42:43], 0, v[162:163]
	s_mov_b32 m0, s26
	s_nop 0
	global_load_lds_dwordx4 v[198:199], off
	s_mov_b32 m0, s27
	s_nop 0
	global_load_lds_dwordx4 v[204:205], off
	s_waitcnt vmcnt(8)
	s_waitcnt lgkmcnt(0)
	s_barrier
	v_mfma_f32_16x16x32_bf16 v[132:135], v[112:115], v[88:91], v[132:135]
	s_setprio 1
	v_mfma_f32_16x16x32_bf16 v[200:203], v[116:119], v[92:95], v[132:135]
	v_mfma_f32_16x16x32_bf16 v[132:135], v[104:107], v[168:171], v[136:139]
	v_mfma_f32_16x16x32_bf16 v[206:209], v[108:111], v[176:179], v[132:135]
	v_mfma_f32_16x16x32_bf16 v[132:135], v[112:115], v[168:171], v[142:145]
	v_mfma_f32_16x16x32_bf16 v[142:145], v[116:119], v[176:179], v[132:135]
	v_mfma_f32_16x16x32_bf16 v[132:135], v[104:107], v[180:183], v[146:149]
	v_mfma_f32_16x16x32_bf16 v[0:3], v[104:107], v[188:191], v[0:3]
	v_mfma_f32_16x16x32_bf16 v[4:7], v[112:115], v[188:191], v[4:7]
	v_mfma_f32_16x16x32_bf16 v[128:131], v[104:107], v[88:91], v[128:131]
	v_mfma_f32_16x16x32_bf16 v[146:149], v[108:111], v[184:187], v[132:135]
	v_mfma_f32_16x16x32_bf16 v[132:135], v[112:115], v[180:183], v[150:153]
	v_mfma_f32_16x16x32_bf16 v[0:3], v[108:111], v[192:195], v[0:3]
	v_mfma_f32_16x16x32_bf16 v[4:7], v[116:119], v[192:195], v[4:7]
	v_mfma_f32_16x16x32_bf16 v[128:131], v[108:111], v[92:95], v[128:131]
	v_mfma_f32_16x16x32_bf16 v[150:153], v[116:119], v[184:187], v[132:135]
	v_mfma_f32_16x16x32_bf16 v[8:11], v[120:123], v[88:91], v[8:11]
	v_mfma_f32_16x16x32_bf16 v[112:115], v[124:127], v[92:95], v[8:11]
	v_mfma_f32_16x16x32_bf16 v[8:11], v[154:157], v[88:91], v[12:15]
	v_mfma_f32_16x16x32_bf16 v[116:119], v[164:167], v[92:95], v[8:11]
	v_mfma_f32_16x16x32_bf16 v[8:11], v[120:123], v[168:171], v[24:27]
	v_mfma_f32_16x16x32_bf16 v[218:221], v[124:127], v[176:179], v[8:11]
	v_mfma_f32_16x16x32_bf16 v[8:11], v[154:157], v[168:171], v[28:31]
	v_mfma_f32_16x16x32_bf16 v[168:171], v[164:167], v[176:179], v[8:11]
	v_mfma_f32_16x16x32_bf16 v[8:11], v[120:123], v[180:183], v[60:63]
	v_mfma_f32_16x16x32_bf16 v[176:179], v[124:127], v[184:187], v[8:11]
	v_mfma_f32_16x16x32_bf16 v[8:11], v[154:157], v[180:183], v[100:103]
	v_mfma_f32_16x16x32_bf16 v[180:183], v[164:167], v[184:187], v[8:11]
	v_mfma_f32_16x16x32_bf16 v[8:11], v[120:123], v[188:191], v[16:19]
	v_mfma_f32_16x16x32_bf16 v[184:187], v[124:127], v[192:195], v[8:11]
	v_mfma_f32_16x16x32_bf16 v[8:11], v[154:157], v[188:191], v[20:23]
	v_mfma_f32_16x16x32_bf16 v[154:157], v[164:167], v[192:195], v[8:11]
	s_barrier
	s_setprio 0
	s_nop 4
	ds_read_b128 v[8:11], v222
	ds_read_b128 v[12:15], v222 offset:1024
	ds_read_b128 v[16:19], v222 offset:2048
	ds_read_b128 v[20:23], v222 offset:3072
	ds_read_b128 v[164:167], v223
	ds_read_b128 v[188:191], v223 offset:1024
	ds_read_b128 v[192:195], v223 offset:2048
	ds_read_b128 v[222:225], v223 offset:3072
	s_add_u32 s6, s42, 0x40000
	s_addc_u32 s7, s43, 0
	s_mov_b32 m0, s28
	v_lshl_add_u64 v[88:89], s[6:7], 0, v[162:163]
	ds_read_b128 v[24:27], v175 offset:32768
	ds_read_b128 v[28:31], v175 offset:33792
	ds_read_b128 v[60:63], v175 offset:34816
	ds_read_b128 v[226:229], v175 offset:35840
	ds_read_b128 v[230:233], v175 offset:36864
	ds_read_b128 v[234:237], v175 offset:37888
	ds_read_b128 v[238:241], v175 offset:38912
	ds_read_b128 v[242:245], v175 offset:39936
	global_load_lds_dwordx4 v[88:89], off
	v_lshl_add_u64 v[88:89], s[6:7], 0, v[160:161]
	s_mov_b32 m0, s29
	s_nop 0
	global_load_lds_dwordx4 v[88:89], off
	s_waitcnt vmcnt(8)
	s_waitcnt lgkmcnt(0)
	s_barrier
	v_mfma_f32_16x16x32_bf16 v[64:67], v[8:11], v[24:27], v[64:67]
	s_setprio 1
	v_mfma_f32_16x16x32_bf16 v[132:135], v[12:15], v[28:31], v[64:67]
	v_mfma_f32_16x16x32_bf16 v[64:67], v[16:19], v[24:27], v[68:71]
	v_mfma_f32_16x16x32_bf16 v[136:139], v[20:23], v[28:31], v[64:67]
	v_mfma_f32_16x16x32_bf16 v[64:67], v[8:11], v[60:63], v[72:75]
	v_mfma_f32_16x16x32_bf16 v[108:111], v[12:15], v[226:229], v[64:67]
	v_mfma_f32_16x16x32_bf16 v[64:67], v[16:19], v[60:63], v[76:79]
	v_mfma_f32_16x16x32_bf16 v[104:107], v[20:23], v[226:229], v[64:67]
	v_mfma_f32_16x16x32_bf16 v[64:67], v[8:11], v[230:233], v[80:83]
	v_mfma_f32_16x16x32_bf16 v[88:91], v[12:15], v[234:237], v[64:67]
	v_mfma_f32_16x16x32_bf16 v[64:67], v[16:19], v[230:233], v[84:87]
	v_mfma_f32_16x16x32_bf16 v[92:95], v[20:23], v[234:237], v[64:67]
	v_mfma_f32_16x16x32_bf16 v[64:67], v[8:11], v[238:241], v[210:213]
	v_mfma_f32_16x16x32_bf16 v[76:79], v[12:15], v[242:245], v[64:67]
	v_mfma_f32_16x16x32_bf16 v[64:67], v[16:19], v[238:241], v[214:217]
	v_mfma_f32_16x16x32_bf16 v[72:75], v[20:23], v[242:245], v[64:67]
	v_mfma_f32_16x16x32_bf16 v[64:67], v[164:167], v[24:27], v[96:99]
	v_mfma_f32_16x16x32_bf16 v[24:27], v[192:195], v[24:27], v[32:35]
	v_mfma_f32_16x16x32_bf16 v[120:123], v[222:225], v[28:31], v[24:27]
	v_mfma_f32_16x16x32_bf16 v[24:27], v[164:167], v[60:63], v[36:39]
	v_mfma_f32_16x16x32_bf16 v[100:103], v[188:191], v[226:229], v[24:27]
	v_mfma_f32_16x16x32_bf16 v[24:27], v[192:195], v[60:63], v[40:43]
	v_mfma_f32_16x16x32_bf16 v[96:99], v[222:225], v[226:229], v[24:27]
	v_mfma_f32_16x16x32_bf16 v[24:27], v[164:167], v[230:233], v[44:47]
	v_mfma_f32_16x16x32_bf16 v[84:87], v[188:191], v[234:237], v[24:27]
	v_mfma_f32_16x16x32_bf16 v[24:27], v[192:195], v[230:233], v[48:51]
	v_mfma_f32_16x16x32_bf16 v[80:83], v[222:225], v[234:237], v[24:27]
	v_mfma_f32_16x16x32_bf16 v[24:27], v[164:167], v[238:241], v[52:55]
	v_mfma_f32_16x16x32_bf16 v[68:71], v[188:191], v[242:245], v[24:27]
	v_mfma_f32_16x16x32_bf16 v[24:27], v[192:195], v[238:241], v[56:59]
	v_mfma_f32_16x16x32_bf16 v[124:127], v[188:191], v[28:31], v[64:67]
	v_mfma_f32_16x16x32_bf16 v[64:67], v[222:225], v[242:245], v[24:27]
	s_barrier
	s_setprio 0
	s_mov_b32 m0, s60
	s_nop 2
	v_lshl_add_u64 v[24:25], v[172:173], 0, s[36:37]
	s_add_u32 s6, s10, 0x10080
	ds_read_b128 v[32:35], v175 offset:49152
	ds_read_b128 v[36:39], v175 offset:50176
	ds_read_b128 v[210:213], v175 offset:51200
	ds_read_b128 v[214:217], v175 offset:52224
	ds_read_b128 v[226:229], v175 offset:53248
	ds_read_b128 v[230:233], v175 offset:54272
	ds_read_b128 v[234:237], v175 offset:55296
	ds_read_b128 v[238:241], v175 offset:56320
	global_load_lds_dwordx4 v[24:25], off
	v_lshl_add_u64 v[24:25], v[196:197], 0, s[36:37]
	s_mov_b32 m0, s58
	s_addc_u32 s7, s11, 0
	global_load_lds_dwordx4 v[24:25], off
	v_lshl_add_u64 v[24:25], s[6:7], 0, v[140:141]
	s_mov_b32 m0, s8
	s_nop 0
	global_load_lds_dwordx4 v[24:25], off
	v_lshl_add_u64 v[24:25], s[6:7], 0, v[158:159]
	s_mov_b32 m0, s9
	s_nop 0
	global_load_lds_dwordx4 v[24:25], off
	v_lshl_add_u64 v[24:25], v[198:199], 0, s[36:37]
	s_mov_b32 m0, s74
	s_nop 0
	global_load_lds_dwordx4 v[24:25], off
	v_lshl_add_u64 v[24:25], v[204:205], 0, s[36:37]
	s_mov_b32 m0, s75
	s_nop 0
	global_load_lds_dwordx4 v[24:25], off
	s_waitcnt vmcnt(8)
	s_waitcnt lgkmcnt(0)
	s_barrier
	v_mfma_f32_16x16x32_bf16 v[24:27], v[8:11], v[32:35], v[128:131]
	s_setprio 1
	v_mfma_f32_16x16x32_bf16 v[56:59], v[12:15], v[36:39], v[24:27]
	v_mfma_f32_16x16x32_bf16 v[24:27], v[16:19], v[32:35], v[200:203]
	v_mfma_f32_16x16x32_bf16 v[60:63], v[20:23], v[36:39], v[24:27]
	v_mfma_f32_16x16x32_bf16 v[24:27], v[8:11], v[210:213], v[206:209]
	v_mfma_f32_16x16x32_bf16 v[44:47], v[12:15], v[214:217], v[24:27]
	v_mfma_f32_16x16x32_bf16 v[24:27], v[16:19], v[210:213], v[142:145]
	v_mfma_f32_16x16x32_bf16 v[40:43], v[20:23], v[214:217], v[24:27]
	v_mfma_f32_16x16x32_bf16 v[24:27], v[8:11], v[226:229], v[146:149]
	v_mfma_f32_16x16x32_bf16 v[0:3], v[8:11], v[234:237], v[0:3]
	v_mfma_f32_16x16x32_bf16 v[24:27], v[12:15], v[230:233], v[24:27]
	v_mfma_f32_16x16x32_bf16 v[28:31], v[16:19], v[226:229], v[150:153]
	v_mfma_f32_16x16x32_bf16 v[12:15], v[12:15], v[238:241], v[0:3]
	v_mfma_f32_16x16x32_bf16 v[0:3], v[16:19], v[234:237], v[4:7]
	v_mfma_f32_16x16x32_bf16 v[28:31], v[20:23], v[230:233], v[28:31]
	v_mfma_f32_16x16x32_bf16 v[8:11], v[20:23], v[238:241], v[0:3]
	v_mfma_f32_16x16x32_bf16 v[0:3], v[164:167], v[32:35], v[112:115]
	v_mfma_f32_16x16x32_bf16 v[52:55], v[188:191], v[36:39], v[0:3]
	v_mfma_f32_16x16x32_bf16 v[0:3], v[192:195], v[32:35], v[116:119]
	v_mfma_f32_16x16x32_bf16 v[48:51], v[222:225], v[36:39], v[0:3]
	v_mfma_f32_16x16x32_bf16 v[0:3], v[164:167], v[210:213], v[218:221]
	v_mfma_f32_16x16x32_bf16 v[36:39], v[188:191], v[214:217], v[0:3]
	v_mfma_f32_16x16x32_bf16 v[0:3], v[192:195], v[210:213], v[168:171]
	v_mfma_f32_16x16x32_bf16 v[32:35], v[222:225], v[214:217], v[0:3]
	v_mfma_f32_16x16x32_bf16 v[0:3], v[164:167], v[226:229], v[176:179]
	v_mfma_f32_16x16x32_bf16 v[20:23], v[188:191], v[230:233], v[0:3]
	v_mfma_f32_16x16x32_bf16 v[0:3], v[192:195], v[226:229], v[180:183]
	v_mfma_f32_16x16x32_bf16 v[16:19], v[222:225], v[230:233], v[0:3]
	v_mfma_f32_16x16x32_bf16 v[0:3], v[164:167], v[234:237], v[184:187]
	v_mfma_f32_16x16x32_bf16 v[4:7], v[188:191], v[238:241], v[0:3]
	v_mfma_f32_16x16x32_bf16 v[0:3], v[192:195], v[234:237], v[154:157]
	v_mfma_f32_16x16x32_bf16 v[0:3], v[222:225], v[238:241], v[0:3]
	s_barrier
	s_setprio 0
	s_andn2_b64 vcc, exec, s[48:49]
	s_cbranch_vccnz .LBB0_419
	s_barrier

.LBB0_457:
	s_lshl_b64 s[10:11], s[52:53], 17
	s_add_u32 s56, s12, s10
	s_addc_u32 s57, s13, s11
	s_and_b64 s[10:11], s[40:41], exec
	s_cselect_b32 s11, s57, s9
	s_cselect_b32 s10, s56, s8
	s_add_i32 s55, 0, 0x10000
	s_add_i32 s38, 0, 0x14000
	v_add_u32_e32 v212, s55, v138
	v_add_u32_e32 v213, s38, v138
	ds_read_b128 v[0:3], v212
	ds_read_b128 v[4:7], v212 offset:1024
	ds_read_b128 v[8:11], v212 offset:2048
	ds_read_b128 v[12:15], v212 offset:3072
	ds_read_b128 v[16:19], v213
	ds_read_b128 v[20:23], v213 offset:1024
	ds_read_b128 v[24:27], v213 offset:2048
	ds_read_b128 v[28:31], v213 offset:3072
	s_add_u32 s74, s6, 0x40080
	s_addc_u32 s75, s7, 0
	s_add_i32 s61, s26, 0xc000
	v_lshl_add_u64 v[64:65], s[74:75], 0, v[132:133]
	s_mov_b32 m0, s61
	s_add_i32 s24, s26, 0xe000
	ds_read_b128 v[32:35], v139
	ds_read_b128 v[36:39], v139 offset:1024
	ds_read_b128 v[40:43], v139 offset:2048
	ds_read_b128 v[44:47], v139 offset:3072
	ds_read_b128 v[48:51], v139 offset:4096
	ds_read_b128 v[52:55], v139 offset:5120
	ds_read_b128 v[56:59], v139 offset:6144
	ds_read_b128 v[60:63], v139 offset:7168
	global_load_lds_dwordx4 v[64:65], off
	v_lshl_add_u64 v[64:65], s[74:75], 0, v[130:131]
	s_mov_b32 m0, s24
	s_nop 0
	global_load_lds_dwordx4 v[64:65], off
	s_waitcnt vmcnt(8)
	s_waitcnt lgkmcnt(0)
	s_barrier
	v_mfma_f32_16x16x32_bf16 v[64:67], v[0:3], v[32:35], 0
	s_setprio 1
	v_mfma_f32_16x16x32_bf16 v[68:71], v[8:11], v[32:35], 0
	v_mfma_f32_16x16x32_bf16 v[72:75], v[0:3], v[40:43], 0
	v_mfma_f32_16x16x32_bf16 v[76:79], v[8:11], v[40:43], 0
	v_mfma_f32_16x16x32_bf16 v[80:83], v[0:3], v[48:51], 0
	v_mfma_f32_16x16x32_bf16 v[84:87], v[8:11], v[48:51], 0
	v_mfma_f32_16x16x32_bf16 v[88:91], v[0:3], v[56:59], 0
	v_mfma_f32_16x16x32_bf16 v[92:95], v[8:11], v[56:59], 0
	v_mfma_f32_16x16x32_bf16 v[64:67], v[4:7], v[36:39], v[64:67]
	v_mfma_f32_16x16x32_bf16 v[68:71], v[12:15], v[36:39], v[68:71]
	v_mfma_f32_16x16x32_bf16 v[72:75], v[4:7], v[44:47], v[72:75]
	v_mfma_f32_16x16x32_bf16 v[76:79], v[12:15], v[44:47], v[76:79]
	v_mfma_f32_16x16x32_bf16 v[80:83], v[4:7], v[52:55], v[80:83]
	v_mfma_f32_16x16x32_bf16 v[84:87], v[12:15], v[52:55], v[84:87]
	v_mfma_f32_16x16x32_bf16 v[88:91], v[4:7], v[60:63], v[88:91]
	v_mfma_f32_16x16x32_bf16 v[92:95], v[12:15], v[60:63], v[92:95]
	v_mfma_f32_16x16x32_bf16 v[96:99], v[16:19], v[32:35], 0
	v_mfma_f32_16x16x32_bf16 v[32:35], v[24:27], v[32:35], 0
	v_mfma_f32_16x16x32_bf16 v[96:99], v[20:23], v[36:39], v[96:99]
	v_mfma_f32_16x16x32_bf16 v[32:35], v[28:31], v[36:39], v[32:35]
	v_mfma_f32_16x16x32_bf16 v[36:39], v[16:19], v[40:43], 0
	v_mfma_f32_16x16x32_bf16 v[40:43], v[24:27], v[40:43], 0
	v_mfma_f32_16x16x32_bf16 v[36:39], v[20:23], v[44:47], v[36:39]
	v_mfma_f32_16x16x32_bf16 v[40:43], v[28:31], v[44:47], v[40:43]
	v_mfma_f32_16x16x32_bf16 v[44:47], v[16:19], v[48:51], 0
	v_mfma_f32_16x16x32_bf16 v[48:51], v[24:27], v[48:51], 0
	v_mfma_f32_16x16x32_bf16 v[44:47], v[20:23], v[52:55], v[44:47]
	v_mfma_f32_16x16x32_bf16 v[48:51], v[28:31], v[52:55], v[48:51]
	v_mfma_f32_16x16x32_bf16 v[52:55], v[16:19], v[56:59], 0
	v_mfma_f32_16x16x32_bf16 v[56:59], v[24:27], v[56:59], 0
	v_mfma_f32_16x16x32_bf16 v[52:55], v[20:23], v[60:63], v[52:55]
	v_mfma_f32_16x16x32_bf16 v[56:59], v[28:31], v[60:63], v[56:59]
	s_barrier
	s_setprio 0
	s_add_i32 s55, s55, s15
	v_lshl_add_u64 v[198:199], s[8:9], 0, v[140:141]
	s_mov_b64 s[2:3], 0x100
	s_add_i32 s35, s55, 0x2000
	v_lshl_add_u64 v[134:135], v[198:199], 0, s[2:3]
	s_mov_b32 m0, s55
	v_lshl_add_u64 v[204:205], s[8:9], 0, v[128:129]
	s_add_u32 s74, s8, 0x10100
	ds_read_b128 v[60:63], v139 offset:16384
	ds_read_b128 v[100:103], v139 offset:17408
	ds_read_b128 v[104:107], v139 offset:18432
	ds_read_b128 v[108:111], v139 offset:19456
	ds_read_b128 v[112:115], v139 offset:20480
	ds_read_b128 v[116:119], v139 offset:21504
	ds_read_b128 v[120:123], v139 offset:22528
	ds_read_b128 v[124:127], v139 offset:23552
	global_load_lds_dwordx4 v[134:135], off
	v_lshl_add_u64 v[134:135], v[204:205], 0, s[2:3]
	s_mov_b32 m0, s35
	s_addc_u32 s75, s9, 0
	s_add_i32 s38, s38, s15
	global_load_lds_dwordx4 v[134:135], off
	v_lshl_add_u64 v[134:135], s[74:75], 0, v[140:141]
	s_mov_b32 m0, s38
	s_add_i32 s53, s38, 0x2000
	global_load_lds_dwordx4 v[134:135], off
	v_lshl_add_u64 v[134:135], s[74:75], 0, v[128:129]
	s_mov_b32 m0, s53
	v_lshl_add_u64 v[206:207], s[6:7], 0, v[132:133]
	global_load_lds_dwordx4 v[134:135], off
	v_lshl_add_u64 v[134:135], v[206:207], 0, s[2:3]
	s_mov_b32 m0, s26
	v_lshl_add_u64 v[208:209], s[6:7], 0, v[130:131]
	global_load_lds_dwordx4 v[134:135], off
	v_lshl_add_u64 v[134:135], v[208:209], 0, s[2:3]
	s_mov_b32 m0, s27
	s_nop 0
	global_load_lds_dwordx4 v[134:135], off
	s_waitcnt vmcnt(8)
	s_waitcnt lgkmcnt(0)
	s_barrier
	v_mfma_f32_16x16x32_bf16 v[134:137], v[0:3], v[60:63], 0
	s_setprio 1
	v_mfma_f32_16x16x32_bf16 v[146:149], v[0:3], v[104:107], 0
	v_mfma_f32_16x16x32_bf16 v[154:157], v[0:3], v[112:115], 0
	v_mfma_f32_16x16x32_bf16 v[0:3], v[0:3], v[120:123], 0
	v_mfma_f32_16x16x32_bf16 v[134:137], v[4:7], v[100:103], v[134:137]
	v_mfma_f32_16x16x32_bf16 v[146:149], v[4:7], v[108:111], v[146:149]
	v_mfma_f32_16x16x32_bf16 v[154:157], v[4:7], v[116:119], v[154:157]
	v_mfma_f32_16x16x32_bf16 v[0:3], v[4:7], v[124:127], v[0:3]
	v_mfma_f32_16x16x32_bf16 v[4:7], v[8:11], v[120:123], 0
	v_mfma_f32_16x16x32_bf16 v[142:145], v[8:11], v[60:63], 0
	v_mfma_f32_16x16x32_bf16 v[150:153], v[8:11], v[104:107], 0
	v_mfma_f32_16x16x32_bf16 v[158:161], v[8:11], v[112:115], 0
	v_mfma_f32_16x16x32_bf16 v[4:7], v[12:15], v[124:127], v[4:7]
	v_mfma_f32_16x16x32_bf16 v[142:145], v[12:15], v[100:103], v[142:145]
	v_mfma_f32_16x16x32_bf16 v[150:153], v[12:15], v[108:111], v[150:153]
	v_mfma_f32_16x16x32_bf16 v[158:161], v[12:15], v[116:119], v[158:161]
	v_mfma_f32_16x16x32_bf16 v[8:11], v[16:19], v[60:63], 0
	v_mfma_f32_16x16x32_bf16 v[12:15], v[24:27], v[60:63], 0
	v_mfma_f32_16x16x32_bf16 v[8:11], v[20:23], v[100:103], v[8:11]
	v_mfma_f32_16x16x32_bf16 v[12:15], v[28:31], v[100:103], v[12:15]
	v_mfma_f32_16x16x32_bf16 v[60:63], v[16:19], v[104:107], 0
	v_mfma_f32_16x16x32_bf16 v[100:103], v[24:27], v[104:107], 0
	v_mfma_f32_16x16x32_bf16 v[104:107], v[16:19], v[112:115], 0
	v_mfma_f32_16x16x32_bf16 v[16:19], v[16:19], v[120:123], 0
	v_mfma_f32_16x16x32_bf16 v[60:63], v[20:23], v[108:111], v[60:63]
	v_mfma_f32_16x16x32_bf16 v[100:103], v[28:31], v[108:111], v[100:103]
	v_mfma_f32_16x16x32_bf16 v[104:107], v[20:23], v[116:119], v[104:107]
	v_mfma_f32_16x16x32_bf16 v[108:111], v[24:27], v[112:115], 0
	v_mfma_f32_16x16x32_bf16 v[16:19], v[20:23], v[124:127], v[16:19]
	v_mfma_f32_16x16x32_bf16 v[20:23], v[24:27], v[120:123], 0
	v_mfma_f32_16x16x32_bf16 v[108:111], v[28:31], v[116:119], v[108:111]
	v_mfma_f32_16x16x32_bf16 v[20:23], v[28:31], v[124:127], v[20:23]
	s_barrier
	s_setprio 0
	s_add_i32 s60, 0, 0x18000
	s_add_i32 s76, 0, 0x1c000
	v_add_u32_e32 v218, s60, v138
	v_add_u32_e32 v219, s76, v138
	ds_read_b128 v[24:27], v218
	ds_read_b128 v[28:31], v218 offset:1024
	ds_read_b128 v[112:115], v218 offset:2048
	ds_read_b128 v[116:119], v218 offset:3072
	ds_read_b128 v[120:123], v219
	ds_read_b128 v[124:127], v219 offset:1024
	ds_read_b128 v[162:165], v219 offset:2048
	ds_read_b128 v[166:169], v219 offset:3072
	s_add_u32 s74, s6, 0x40100
	s_addc_u32 s75, s7, 0
	s_mov_b32 m0, s28
	v_lshl_add_u64 v[210:211], s[74:75], 0, v[132:133]
	ds_read_b128 v[170:173], v139 offset:32768
	ds_read_b128 v[174:177], v139 offset:33792
	ds_read_b128 v[178:181], v139 offset:34816
	ds_read_b128 v[182:185], v139 offset:35840
	ds_read_b128 v[186:189], v139 offset:36864
	ds_read_b128 v[190:193], v139 offset:37888
	ds_read_b128 v[194:197], v139 offset:38912
	ds_read_b128 v[200:203], v139 offset:39936
	global_load_lds_dwordx4 v[210:211], off
	v_lshl_add_u64 v[210:211], s[74:75], 0, v[130:131]
	s_mov_b32 m0, s29
	s_nop 0
	global_load_lds_dwordx4 v[210:211], off
	s_waitcnt vmcnt(8)
	s_waitcnt lgkmcnt(0)
	s_barrier
	v_mfma_f32_16x16x32_bf16 v[64:67], v[24:27], v[170:173], v[64:67]
	s_setprio 1
	v_mfma_f32_16x16x32_bf16 v[68:71], v[112:115], v[170:173], v[68:71]
	v_mfma_f32_16x16x32_bf16 v[72:75], v[24:27], v[178:181], v[72:75]
	v_mfma_f32_16x16x32_bf16 v[76:79], v[112:115], v[178:181], v[76:79]
	v_mfma_f32_16x16x32_bf16 v[80:83], v[24:27], v[186:189], v[80:83]
	v_mfma_f32_16x16x32_bf16 v[84:87], v[112:115], v[186:189], v[84:87]
	v_mfma_f32_16x16x32_bf16 v[88:91], v[24:27], v[194:197], v[88:91]
	v_mfma_f32_16x16x32_bf16 v[92:95], v[112:115], v[194:197], v[92:95]
	v_mfma_f32_16x16x32_bf16 v[64:67], v[28:31], v[174:177], v[64:67]
	v_mfma_f32_16x16x32_bf16 v[68:71], v[116:119], v[174:177], v[68:71]
	v_mfma_f32_16x16x32_bf16 v[72:75], v[28:31], v[182:185], v[72:75]
	v_mfma_f32_16x16x32_bf16 v[76:79], v[116:119], v[182:185], v[76:79]
	v_mfma_f32_16x16x32_bf16 v[80:83], v[28:31], v[190:193], v[80:83]
	v_mfma_f32_16x16x32_bf16 v[84:87], v[116:119], v[190:193], v[84:87]
	v_mfma_f32_16x16x32_bf16 v[88:91], v[28:31], v[200:203], v[88:91]
	v_mfma_f32_16x16x32_bf16 v[92:95], v[116:119], v[200:203], v[92:95]
	v_mfma_f32_16x16x32_bf16 v[96:99], v[120:123], v[170:173], v[96:99]
	v_mfma_f32_16x16x32_bf16 v[32:35], v[162:165], v[170:173], v[32:35]
	v_mfma_f32_16x16x32_bf16 v[36:39], v[120:123], v[178:181], v[36:39]
	v_mfma_f32_16x16x32_bf16 v[40:43], v[162:165], v[178:181], v[40:43]
	v_mfma_f32_16x16x32_bf16 v[44:47], v[120:123], v[186:189], v[44:47]
	v_mfma_f32_16x16x32_bf16 v[48:51], v[162:165], v[186:189], v[48:51]
	v_mfma_f32_16x16x32_bf16 v[52:55], v[120:123], v[194:197], v[52:55]
	v_mfma_f32_16x16x32_bf16 v[56:59], v[162:165], v[194:197], v[56:59]
	v_mfma_f32_16x16x32_bf16 v[96:99], v[124:127], v[174:177], v[96:99]
	v_mfma_f32_16x16x32_bf16 v[32:35], v[166:169], v[174:177], v[32:35]
	v_mfma_f32_16x16x32_bf16 v[36:39], v[124:127], v[182:185], v[36:39]
	v_mfma_f32_16x16x32_bf16 v[40:43], v[166:169], v[182:185], v[40:43]
	v_mfma_f32_16x16x32_bf16 v[44:47], v[124:127], v[190:193], v[44:47]
	v_mfma_f32_16x16x32_bf16 v[48:51], v[166:169], v[190:193], v[48:51]
	v_mfma_f32_16x16x32_bf16 v[52:55], v[124:127], v[200:203], v[52:55]
	v_mfma_f32_16x16x32_bf16 v[56:59], v[166:169], v[200:203], v[56:59]
	s_barrier
	s_setprio 0
	s_add_i32 s74, s60, s15
	s_mov_b64 s[2:3], 0x180
	s_add_i32 s60, s74, 0x2000
	v_lshl_add_u64 v[198:199], v[198:199], 0, s[2:3]
	s_mov_b32 m0, s74
	s_add_u32 s84, s8, 0x10180
	ds_read_b128 v[170:173], v139 offset:49152
	ds_read_b128 v[174:177], v139 offset:50176
	ds_read_b128 v[178:181], v139 offset:51200
	ds_read_b128 v[182:185], v139 offset:52224
	ds_read_b128 v[186:189], v139 offset:53248
	ds_read_b128 v[190:193], v139 offset:54272
	ds_read_b128 v[194:197], v139 offset:55296
	ds_read_b128 v[200:203], v139 offset:56320
	global_load_lds_dwordx4 v[198:199], off
	v_lshl_add_u64 v[198:199], v[204:205], 0, s[2:3]
	s_mov_b32 m0, s60
	s_addc_u32 s85, s9, 0
	s_add_i32 s8, s76, s15
	global_load_lds_dwordx4 v[198:199], off
	v_lshl_add_u64 v[198:199], s[84:85], 0, v[140:141]
	s_mov_b32 m0, s8
	s_add_i32 s9, s8, 0x2000
	global_load_lds_dwordx4 v[198:199], off
	v_lshl_add_u64 v[198:199], s[84:85], 0, v[128:129]
	s_mov_b32 m0, s9
	s_nop 0
	global_load_lds_dwordx4 v[198:199], off
	v_lshl_add_u64 v[198:199], v[206:207], 0, s[2:3]
	s_mov_b32 m0, s58
	s_nop 0
	global_load_lds_dwordx4 v[198:199], off
	v_lshl_add_u64 v[198:199], v[208:209], 0, s[2:3]
	s_mov_b32 m0, s59
	s_nop 0
	global_load_lds_dwordx4 v[198:199], off
	s_waitcnt vmcnt(8)
	s_waitcnt lgkmcnt(0)
	s_barrier
	v_mfma_f32_16x16x32_bf16 v[0:3], v[24:27], v[194:197], v[0:3]
	s_setprio 1
	v_mfma_f32_16x16x32_bf16 v[4:7], v[112:115], v[194:197], v[4:7]
	v_mfma_f32_16x16x32_bf16 v[134:137], v[24:27], v[170:173], v[134:137]
	v_mfma_f32_16x16x32_bf16 v[142:145], v[112:115], v[170:173], v[142:145]
	v_mfma_f32_16x16x32_bf16 v[146:149], v[24:27], v[178:181], v[146:149]
	v_mfma_f32_16x16x32_bf16 v[150:153], v[112:115], v[178:181], v[150:153]
	v_mfma_f32_16x16x32_bf16 v[154:157], v[24:27], v[186:189], v[154:157]
	v_mfma_f32_16x16x32_bf16 v[158:161], v[112:115], v[186:189], v[158:161]
	v_mfma_f32_16x16x32_bf16 v[0:3], v[28:31], v[200:203], v[0:3]
	v_mfma_f32_16x16x32_bf16 v[4:7], v[116:119], v[200:203], v[4:7]
	v_mfma_f32_16x16x32_bf16 v[134:137], v[28:31], v[174:177], v[134:137]
	v_mfma_f32_16x16x32_bf16 v[142:145], v[116:119], v[174:177], v[142:145]
	v_mfma_f32_16x16x32_bf16 v[146:149], v[28:31], v[182:185], v[146:149]
	v_mfma_f32_16x16x32_bf16 v[150:153], v[116:119], v[182:185], v[150:153]
	v_mfma_f32_16x16x32_bf16 v[154:157], v[28:31], v[190:193], v[154:157]
	v_mfma_f32_16x16x32_bf16 v[158:161], v[116:119], v[190:193], v[158:161]
	v_mfma_f32_16x16x32_bf16 v[8:11], v[120:123], v[170:173], v[8:11]
	v_mfma_f32_16x16x32_bf16 v[12:15], v[162:165], v[170:173], v[12:15]
	v_mfma_f32_16x16x32_bf16 v[24:27], v[120:123], v[178:181], v[60:63]
	v_mfma_f32_16x16x32_bf16 v[28:31], v[162:165], v[178:181], v[100:103]
	v_mfma_f32_16x16x32_bf16 v[60:63], v[120:123], v[186:189], v[104:107]
	v_mfma_f32_16x16x32_bf16 v[100:103], v[162:165], v[186:189], v[108:111]
	v_mfma_f32_16x16x32_bf16 v[16:19], v[120:123], v[194:197], v[16:19]
	v_mfma_f32_16x16x32_bf16 v[20:23], v[162:165], v[194:197], v[20:23]
	v_mfma_f32_16x16x32_bf16 v[8:11], v[124:127], v[174:177], v[8:11]
	v_mfma_f32_16x16x32_bf16 v[12:15], v[166:169], v[174:177], v[12:15]
	v_mfma_f32_16x16x32_bf16 v[24:27], v[124:127], v[182:185], v[24:27]
	v_mfma_f32_16x16x32_bf16 v[28:31], v[166:169], v[182:185], v[28:31]
	v_mfma_f32_16x16x32_bf16 v[60:63], v[124:127], v[190:193], v[60:63]
	v_mfma_f32_16x16x32_bf16 v[100:103], v[166:169], v[190:193], v[100:103]
	v_mfma_f32_16x16x32_bf16 v[16:19], v[124:127], v[200:203], v[16:19]
	v_mfma_f32_16x16x32_bf16 v[20:23], v[166:169], v[200:203], v[20:23]
	s_barrier
	s_setprio 0
	ds_read_b128 v[104:107], v212
	ds_read_b128 v[108:111], v212 offset:1024
	ds_read_b128 v[112:115], v212 offset:2048
	ds_read_b128 v[116:119], v212 offset:3072
	ds_read_b128 v[120:123], v213
	ds_read_b128 v[124:127], v213 offset:1024
	ds_read_b128 v[162:165], v213 offset:2048
	ds_read_b128 v[166:169], v213 offset:3072
	s_add_u32 s6, s6, 0x40180
	s_addc_u32 s7, s7, 0
	s_mov_b32 m0, s61
	v_lshl_add_u64 v[198:199], s[6:7], 0, v[132:133]
	ds_read_b128 v[170:173], v139
	ds_read_b128 v[174:177], v139 offset:1024
	ds_read_b128 v[178:181], v139 offset:2048
	ds_read_b128 v[182:185], v139 offset:3072
	ds_read_b128 v[186:189], v139 offset:4096
	ds_read_b128 v[190:193], v139 offset:5120
	ds_read_b128 v[194:197], v139 offset:6144
	ds_read_b128 v[200:203], v139 offset:7168
	global_load_lds_dwordx4 v[198:199], off
	v_lshl_add_u64 v[198:199], s[6:7], 0, v[130:131]
	s_mov_b32 m0, s24
	s_nop 0
	global_load_lds_dwordx4 v[198:199], off
	s_waitcnt vmcnt(8)
	s_waitcnt lgkmcnt(0)
	s_barrier
	v_mfma_f32_16x16x32_bf16 v[64:67], v[104:107], v[170:173], v[64:67]
	s_setprio 1
	v_mfma_f32_16x16x32_bf16 v[68:71], v[112:115], v[170:173], v[68:71]
	v_mfma_f32_16x16x32_bf16 v[72:75], v[104:107], v[178:181], v[72:75]
	v_mfma_f32_16x16x32_bf16 v[76:79], v[112:115], v[178:181], v[76:79]
	v_mfma_f32_16x16x32_bf16 v[80:83], v[104:107], v[186:189], v[80:83]
	v_mfma_f32_16x16x32_bf16 v[84:87], v[112:115], v[186:189], v[84:87]
	v_mfma_f32_16x16x32_bf16 v[88:91], v[104:107], v[194:197], v[88:91]
	v_mfma_f32_16x16x32_bf16 v[64:67], v[108:111], v[174:177], v[64:67]
	v_mfma_f32_16x16x32_bf16 v[68:71], v[116:119], v[174:177], v[68:71]
	v_mfma_f32_16x16x32_bf16 v[72:75], v[108:111], v[182:185], v[72:75]
	v_mfma_f32_16x16x32_bf16 v[76:79], v[116:119], v[182:185], v[76:79]
	v_mfma_f32_16x16x32_bf16 v[80:83], v[108:111], v[190:193], v[80:83]
	v_mfma_f32_16x16x32_bf16 v[84:87], v[116:119], v[190:193], v[84:87]
	v_mfma_f32_16x16x32_bf16 v[206:209], v[108:111], v[200:203], v[88:91]
	v_mfma_f32_16x16x32_bf16 v[88:91], v[112:115], v[194:197], v[92:95]
	v_mfma_f32_16x16x32_bf16 v[210:213], v[116:119], v[200:203], v[88:91]
	v_mfma_f32_16x16x32_bf16 v[88:91], v[120:123], v[170:173], v[96:99]
	v_mfma_f32_16x16x32_bf16 v[32:35], v[162:165], v[170:173], v[32:35]
	v_mfma_f32_16x16x32_bf16 v[36:39], v[120:123], v[178:181], v[36:39]
	v_mfma_f32_16x16x32_bf16 v[40:43], v[162:165], v[178:181], v[40:43]
	v_mfma_f32_16x16x32_bf16 v[44:47], v[120:123], v[186:189], v[44:47]
	v_mfma_f32_16x16x32_bf16 v[48:51], v[162:165], v[186:189], v[48:51]
	v_mfma_f32_16x16x32_bf16 v[52:55], v[120:123], v[194:197], v[52:55]
	v_mfma_f32_16x16x32_bf16 v[56:59], v[162:165], v[194:197], v[56:59]
	v_mfma_f32_16x16x32_bf16 v[96:99], v[124:127], v[174:177], v[88:91]
	v_mfma_f32_16x16x32_bf16 v[32:35], v[166:169], v[174:177], v[32:35]
	v_mfma_f32_16x16x32_bf16 v[36:39], v[124:127], v[182:185], v[36:39]
	v_mfma_f32_16x16x32_bf16 v[40:43], v[166:169], v[182:185], v[40:43]
	v_mfma_f32_16x16x32_bf16 v[44:47], v[124:127], v[190:193], v[44:47]
	v_mfma_f32_16x16x32_bf16 v[48:51], v[166:169], v[190:193], v[48:51]
	v_mfma_f32_16x16x32_bf16 v[52:55], v[124:127], v[200:203], v[52:55]
	v_mfma_f32_16x16x32_bf16 v[56:59], v[166:169], v[200:203], v[56:59]
	s_barrier
	s_setprio 0
	s_mov_b32 m0, s55
	v_lshl_add_u64 v[198:199], s[10:11], 0, v[140:141]
	s_add_u32 s6, s10, 0x10000
	ds_read_b128 v[88:91], v139 offset:16384
	ds_read_b128 v[92:95], v139 offset:17408
	ds_read_b128 v[170:173], v139 offset:18432
	ds_read_b128 v[174:177], v139 offset:19456
	ds_read_b128 v[178:181], v139 offset:20480
	ds_read_b128 v[182:185], v139 offset:21504
	ds_read_b128 v[186:189], v139 offset:22528
	ds_read_b128 v[190:193], v139 offset:23552
	global_load_lds_dwordx4 v[198:199], off
	v_lshl_add_u64 v[204:205], s[10:11], 0, v[128:129]
	s_mov_b32 m0, s35
	s_addc_u32 s7, s11, 0
	global_load_lds_dwordx4 v[204:205], off
	v_lshl_add_u64 v[194:195], s[6:7], 0, v[140:141]
	s_mov_b32 m0, s38
	v_lshl_add_u64 v[242:243], s[42:43], 0, v[132:133]
	global_load_lds_dwordx4 v[194:195], off
	v_lshl_add_u64 v[194:195], s[6:7], 0, v[128:129]
	s_mov_b32 m0, s53
	v_lshl_add_u64 v[244:245], s[42:43], 0, v[130:131]
	global_load_lds_dwordx4 v[194:195], off
	s_mov_b32 m0, s26
	s_nop 0
	global_load_lds_dwordx4 v[242:243], off
	s_mov_b32 m0, s27
	s_nop 0
	global_load_lds_dwordx4 v[244:245], off
	s_waitcnt vmcnt(8)
	s_waitcnt lgkmcnt(0)
	s_barrier
	v_mfma_f32_16x16x32_bf16 v[0:3], v[104:107], v[186:189], v[0:3]
	s_setprio 1
	v_mfma_f32_16x16x32_bf16 v[4:7], v[112:115], v[186:189], v[4:7]
	v_mfma_f32_16x16x32_bf16 v[134:137], v[104:107], v[88:91], v[134:137]
	v_mfma_f32_16x16x32_bf16 v[142:145], v[112:115], v[88:91], v[142:145]
	v_mfma_f32_16x16x32_bf16 v[146:149], v[104:107], v[170:173], v[146:149]
	v_mfma_f32_16x16x32_bf16 v[150:153], v[112:115], v[170:173], v[150:153]
	v_mfma_f32_16x16x32_bf16 v[154:157], v[104:107], v[178:181], v[154:157]
	v_mfma_f32_16x16x32_bf16 v[158:161], v[112:115], v[178:181], v[158:161]
	v_mfma_f32_16x16x32_bf16 v[0:3], v[108:111], v[190:193], v[0:3]
	v_mfma_f32_16x16x32_bf16 v[4:7], v[116:119], v[190:193], v[4:7]
	v_mfma_f32_16x16x32_bf16 v[134:137], v[108:111], v[92:95], v[134:137]
	v_mfma_f32_16x16x32_bf16 v[142:145], v[116:119], v[92:95], v[142:145]
	v_mfma_f32_16x16x32_bf16 v[146:149], v[108:111], v[174:177], v[146:149]
	v_mfma_f32_16x16x32_bf16 v[150:153], v[116:119], v[174:177], v[150:153]
	v_mfma_f32_16x16x32_bf16 v[154:157], v[108:111], v[182:185], v[154:157]
	v_mfma_f32_16x16x32_bf16 v[158:161], v[116:119], v[182:185], v[158:161]
	v_mfma_f32_16x16x32_bf16 v[8:11], v[120:123], v[88:91], v[8:11]
	v_mfma_f32_16x16x32_bf16 v[194:197], v[124:127], v[92:95], v[8:11]
	v_mfma_f32_16x16x32_bf16 v[8:11], v[162:165], v[88:91], v[12:15]
	v_mfma_f32_16x16x32_bf16 v[200:203], v[166:169], v[92:95], v[8:11]
	v_mfma_f32_16x16x32_bf16 v[8:11], v[120:123], v[170:173], v[24:27]
	v_mfma_f32_16x16x32_bf16 v[214:217], v[124:127], v[174:177], v[8:11]
	v_mfma_f32_16x16x32_bf16 v[8:11], v[162:165], v[170:173], v[28:31]
	v_mfma_f32_16x16x32_bf16 v[170:173], v[166:169], v[174:177], v[8:11]
	v_mfma_f32_16x16x32_bf16 v[8:11], v[120:123], v[178:181], v[60:63]
	v_mfma_f32_16x16x32_bf16 v[174:177], v[124:127], v[182:185], v[8:11]
	v_mfma_f32_16x16x32_bf16 v[8:11], v[162:165], v[178:181], v[100:103]
	v_mfma_f32_16x16x32_bf16 v[178:181], v[166:169], v[182:185], v[8:11]
	v_mfma_f32_16x16x32_bf16 v[8:11], v[120:123], v[186:189], v[16:19]
	v_mfma_f32_16x16x32_bf16 v[182:185], v[124:127], v[190:193], v[8:11]
	v_mfma_f32_16x16x32_bf16 v[8:11], v[162:165], v[186:189], v[20:23]
	v_mfma_f32_16x16x32_bf16 v[162:165], v[166:169], v[190:193], v[8:11]
	s_barrier
	s_setprio 0
	s_nop 4
	ds_read_b128 v[8:11], v218
	ds_read_b128 v[12:15], v218 offset:1024
	ds_read_b128 v[16:19], v218 offset:2048
	ds_read_b128 v[20:23], v218 offset:3072
	ds_read_b128 v[166:169], v219
	ds_read_b128 v[186:189], v219 offset:1024
	ds_read_b128 v[190:193], v219 offset:2048
	ds_read_b128 v[218:221], v219 offset:3072
	s_add_u32 s6, s42, 0x40000
	s_addc_u32 s7, s43, 0
	s_mov_b32 m0, s28
	v_lshl_add_u64 v[88:89], s[6:7], 0, v[132:133]
	ds_read_b128 v[24:27], v139 offset:32768
	ds_read_b128 v[28:31], v139 offset:33792
	ds_read_b128 v[60:63], v139 offset:34816
	ds_read_b128 v[222:225], v139 offset:35840
	ds_read_b128 v[226:229], v139 offset:36864
	ds_read_b128 v[230:233], v139 offset:37888
	ds_read_b128 v[234:237], v139 offset:38912
	ds_read_b128 v[238:241], v139 offset:39936
	global_load_lds_dwordx4 v[88:89], off
	v_lshl_add_u64 v[88:89], s[6:7], 0, v[130:131]
	s_mov_b32 m0, s29
	s_nop 0
	global_load_lds_dwordx4 v[88:89], off
	s_waitcnt vmcnt(8)
	s_waitcnt lgkmcnt(0)
	s_barrier
	v_mfma_f32_16x16x32_bf16 v[64:67], v[8:11], v[24:27], v[64:67]
	s_setprio 1
	v_mfma_f32_16x16x32_bf16 v[120:123], v[12:15], v[28:31], v[64:67]
	v_mfma_f32_16x16x32_bf16 v[64:67], v[16:19], v[24:27], v[68:71]
	v_mfma_f32_16x16x32_bf16 v[124:127], v[20:23], v[28:31], v[64:67]
	v_mfma_f32_16x16x32_bf16 v[64:67], v[8:11], v[60:63], v[72:75]
	v_mfma_f32_16x16x32_bf16 v[104:107], v[12:15], v[222:225], v[64:67]
	v_mfma_f32_16x16x32_bf16 v[64:67], v[16:19], v[60:63], v[76:79]
	v_mfma_f32_16x16x32_bf16 v[108:111], v[20:23], v[222:225], v[64:67]
	v_mfma_f32_16x16x32_bf16 v[64:67], v[8:11], v[226:229], v[80:83]
	v_mfma_f32_16x16x32_bf16 v[88:91], v[12:15], v[230:233], v[64:67]
	v_mfma_f32_16x16x32_bf16 v[64:67], v[16:19], v[226:229], v[84:87]
	v_mfma_f32_16x16x32_bf16 v[92:95], v[20:23], v[230:233], v[64:67]
	v_mfma_f32_16x16x32_bf16 v[64:67], v[8:11], v[234:237], v[206:209]
	v_mfma_f32_16x16x32_bf16 v[72:75], v[12:15], v[238:241], v[64:67]
	v_mfma_f32_16x16x32_bf16 v[64:67], v[16:19], v[234:237], v[210:213]
	v_mfma_f32_16x16x32_bf16 v[76:79], v[20:23], v[238:241], v[64:67]
	v_mfma_f32_16x16x32_bf16 v[64:67], v[166:169], v[24:27], v[96:99]
	v_mfma_f32_16x16x32_bf16 v[24:27], v[190:193], v[24:27], v[32:35]
	v_mfma_f32_16x16x32_bf16 v[112:115], v[218:221], v[28:31], v[24:27]
	v_mfma_f32_16x16x32_bf16 v[24:27], v[166:169], v[60:63], v[36:39]
	v_mfma_f32_16x16x32_bf16 v[100:103], v[186:189], v[222:225], v[24:27]
	v_mfma_f32_16x16x32_bf16 v[24:27], v[190:193], v[60:63], v[40:43]
	v_mfma_f32_16x16x32_bf16 v[96:99], v[218:221], v[222:225], v[24:27]
	v_mfma_f32_16x16x32_bf16 v[24:27], v[166:169], v[226:229], v[44:47]
	v_mfma_f32_16x16x32_bf16 v[84:87], v[186:189], v[230:233], v[24:27]
	v_mfma_f32_16x16x32_bf16 v[24:27], v[190:193], v[226:229], v[48:51]
	v_mfma_f32_16x16x32_bf16 v[80:83], v[218:221], v[230:233], v[24:27]
	v_mfma_f32_16x16x32_bf16 v[24:27], v[166:169], v[234:237], v[52:55]
	v_mfma_f32_16x16x32_bf16 v[68:71], v[186:189], v[238:241], v[24:27]
	v_mfma_f32_16x16x32_bf16 v[24:27], v[190:193], v[234:237], v[56:59]
	v_mfma_f32_16x16x32_bf16 v[116:119], v[186:189], v[28:31], v[64:67]
	v_mfma_f32_16x16x32_bf16 v[64:67], v[218:221], v[238:241], v[24:27]
	s_barrier
	s_setprio 0
	s_mov_b32 m0, s74
	s_nop 2
	v_lshl_add_u64 v[24:25], v[198:199], 0, s[36:37]
	s_add_u32 s6, s10, 0x10080
	ds_read_b128 v[32:35], v139 offset:49152
	ds_read_b128 v[36:39], v139 offset:50176
	ds_read_b128 v[206:209], v139 offset:51200
	ds_read_b128 v[210:213], v139 offset:52224
	ds_read_b128 v[222:225], v139 offset:53248
	ds_read_b128 v[226:229], v139 offset:54272
	ds_read_b128 v[230:233], v139 offset:55296
	ds_read_b128 v[234:237], v139 offset:56320
	global_load_lds_dwordx4 v[24:25], off
	v_lshl_add_u64 v[24:25], v[204:205], 0, s[36:37]
	s_mov_b32 m0, s60
	s_addc_u32 s7, s11, 0
	global_load_lds_dwordx4 v[24:25], off
	v_lshl_add_u64 v[24:25], s[6:7], 0, v[140:141]
	s_mov_b32 m0, s8
	s_nop 0
	global_load_lds_dwordx4 v[24:25], off
	v_lshl_add_u64 v[24:25], s[6:7], 0, v[128:129]
	s_mov_b32 m0, s9
	s_nop 0
	global_load_lds_dwordx4 v[24:25], off
	v_lshl_add_u64 v[24:25], v[242:243], 0, s[36:37]
	s_mov_b32 m0, s58
	s_nop 0
	global_load_lds_dwordx4 v[24:25], off
	v_lshl_add_u64 v[24:25], v[244:245], 0, s[36:37]
	s_mov_b32 m0, s59
	s_nop 0
	global_load_lds_dwordx4 v[24:25], off
	s_waitcnt vmcnt(8)
	s_waitcnt lgkmcnt(0)
	s_barrier
	v_mfma_f32_16x16x32_bf16 v[24:27], v[8:11], v[32:35], v[134:137]
	s_setprio 1
	v_mfma_f32_16x16x32_bf16 v[56:59], v[12:15], v[36:39], v[24:27]
	v_mfma_f32_16x16x32_bf16 v[24:27], v[16:19], v[32:35], v[142:145]
	v_mfma_f32_16x16x32_bf16 v[60:63], v[20:23], v[36:39], v[24:27]
	v_mfma_f32_16x16x32_bf16 v[24:27], v[8:11], v[206:209], v[146:149]
	v_mfma_f32_16x16x32_bf16 v[40:43], v[12:15], v[210:213], v[24:27]
	v_mfma_f32_16x16x32_bf16 v[24:27], v[16:19], v[206:209], v[150:153]
	v_mfma_f32_16x16x32_bf16 v[0:3], v[8:11], v[230:233], v[0:3]
	v_mfma_f32_16x16x32_bf16 v[44:47], v[20:23], v[210:213], v[24:27]
	v_mfma_f32_16x16x32_bf16 v[24:27], v[8:11], v[222:225], v[154:157]
	v_mfma_f32_16x16x32_bf16 v[28:31], v[16:19], v[222:225], v[158:161]
	v_mfma_f32_16x16x32_bf16 v[8:11], v[12:15], v[234:237], v[0:3]
	v_mfma_f32_16x16x32_bf16 v[0:3], v[16:19], v[230:233], v[4:7]
	v_mfma_f32_16x16x32_bf16 v[24:27], v[12:15], v[226:229], v[24:27]
	v_mfma_f32_16x16x32_bf16 v[28:31], v[20:23], v[226:229], v[28:31]
	v_mfma_f32_16x16x32_bf16 v[12:15], v[20:23], v[234:237], v[0:3]
	v_mfma_f32_16x16x32_bf16 v[0:3], v[166:169], v[32:35], v[194:197]
	v_mfma_f32_16x16x32_bf16 v[52:55], v[186:189], v[36:39], v[0:3]
	v_mfma_f32_16x16x32_bf16 v[0:3], v[190:193], v[32:35], v[200:203]
	v_mfma_f32_16x16x32_bf16 v[48:51], v[218:221], v[36:39], v[0:3]
	v_mfma_f32_16x16x32_bf16 v[0:3], v[166:169], v[206:209], v[214:217]
	v_mfma_f32_16x16x32_bf16 v[36:39], v[186:189], v[210:213], v[0:3]
	v_mfma_f32_16x16x32_bf16 v[0:3], v[190:193], v[206:209], v[170:173]
	v_mfma_f32_16x16x32_bf16 v[32:35], v[218:221], v[210:213], v[0:3]
	v_mfma_f32_16x16x32_bf16 v[0:3], v[166:169], v[222:225], v[174:177]
	v_mfma_f32_16x16x32_bf16 v[20:23], v[186:189], v[226:229], v[0:3]
	v_mfma_f32_16x16x32_bf16 v[0:3], v[190:193], v[222:225], v[178:181]
	v_mfma_f32_16x16x32_bf16 v[16:19], v[218:221], v[226:229], v[0:3]
	v_mfma_f32_16x16x32_bf16 v[0:3], v[166:169], v[230:233], v[182:185]
	v_mfma_f32_16x16x32_bf16 v[4:7], v[186:189], v[234:237], v[0:3]
	v_mfma_f32_16x16x32_bf16 v[0:3], v[190:193], v[230:233], v[162:165]
	v_mfma_f32_16x16x32_bf16 v[0:3], v[218:221], v[234:237], v[0:3]
	s_barrier
	s_setprio 0
	s_andn2_b64 vcc, exec, s[48:49]
	s_cbranch_vccnz .LBB0_459
	s_barrier

.LBB0_552:
	s_add_u32 s8, s6, 0xfffc0080
	s_addc_u32 s9, s7, -1
	s_add_i32 s35, 0, 0x10000
	s_cmp_eq_u32 s56, 12
	s_cselect_b32 s11, s4, s9
	s_cselect_b32 s10, s5, s8
	v_add_u32_e32 v140, s35, v165
	s_cselect_b32 s9, s24, s51
	s_cselect_b32 s8, s38, s47
	s_add_i32 s57, 0, 0x14000
	ds_read_b128 v[158:161], v140
	ds_read_b128 v[168:171], v140 offset:1024
	ds_read_b128 v[172:175], v140 offset:2048
	ds_read_b128 v[176:179], v140 offset:3072
	v_add_u32_e32 v140, s57, v165
	ds_read_b128 v[180:183], v140
	ds_read_b128 v[184:187], v140 offset:1024
	ds_read_b128 v[206:209], v140 offset:2048
	ds_read_b128 v[210:213], v140 offset:3072
	v_lshl_add_u64 v[142:143], s[6:7], 0, v[136:137]
	s_add_i32 m0, s66, 0xc000
	ds_read_b128 v[214:217], v166
	ds_read_b128 v[218:221], v166 offset:1024
	ds_read_b128 v[222:225], v166 offset:2048
	ds_read_b128 v[226:229], v166 offset:3072
	ds_read_b128 v[230:233], v166 offset:4096
	ds_read_b128 v[234:237], v166 offset:5120
	ds_read_b128 v[238:241], v166 offset:6144
	ds_read_b128 v[242:245], v166 offset:7168
	global_load_lds_dwordx4 v[142:143], off
	v_lshl_add_u64 v[142:143], s[6:7], 0, v[138:139]
	s_add_i32 m0, s66, 0xe000
	s_nop 0
	global_load_lds_dwordx4 v[142:143], off
	s_waitcnt vmcnt(8)
	s_waitcnt lgkmcnt(0)
	s_barrier
	v_mfma_f32_16x16x32_bf16 v[124:127], v[158:161], v[214:217], v[124:127]
	s_setprio 1
	v_mfma_f32_16x16x32_bf16 v[120:123], v[172:175], v[214:217], v[120:123]
	v_mfma_f32_16x16x32_bf16 v[108:111], v[158:161], v[222:225], v[108:111]
	v_mfma_f32_16x16x32_bf16 v[104:107], v[172:175], v[222:225], v[104:107]
	v_mfma_f32_16x16x32_bf16 v[92:95], v[158:161], v[230:233], v[92:95]
	v_mfma_f32_16x16x32_bf16 v[88:91], v[172:175], v[230:233], v[88:91]
	v_mfma_f32_16x16x32_bf16 v[76:79], v[158:161], v[238:241], v[76:79]
	v_mfma_f32_16x16x32_bf16 v[72:75], v[172:175], v[238:241], v[72:75]
	v_mfma_f32_16x16x32_bf16 v[124:127], v[168:171], v[218:221], v[124:127]
	v_mfma_f32_16x16x32_bf16 v[120:123], v[176:179], v[218:221], v[120:123]
	v_mfma_f32_16x16x32_bf16 v[108:111], v[168:171], v[226:229], v[108:111]
	v_mfma_f32_16x16x32_bf16 v[104:107], v[176:179], v[226:229], v[104:107]
	v_mfma_f32_16x16x32_bf16 v[92:95], v[168:171], v[234:237], v[92:95]
	v_mfma_f32_16x16x32_bf16 v[88:91], v[176:179], v[234:237], v[88:91]
	v_mfma_f32_16x16x32_bf16 v[76:79], v[168:171], v[242:245], v[76:79]
	v_mfma_f32_16x16x32_bf16 v[72:75], v[176:179], v[242:245], v[72:75]
	v_mfma_f32_16x16x32_bf16 v[116:119], v[180:183], v[214:217], v[116:119]
	v_mfma_f32_16x16x32_bf16 v[112:115], v[206:209], v[214:217], v[112:115]
	v_mfma_f32_16x16x32_bf16 v[100:103], v[180:183], v[222:225], v[100:103]
	v_mfma_f32_16x16x32_bf16 v[96:99], v[206:209], v[222:225], v[96:99]
	v_mfma_f32_16x16x32_bf16 v[84:87], v[180:183], v[230:233], v[84:87]
	v_mfma_f32_16x16x32_bf16 v[80:83], v[206:209], v[230:233], v[80:83]
	v_mfma_f32_16x16x32_bf16 v[68:71], v[180:183], v[238:241], v[68:71]
	v_mfma_f32_16x16x32_bf16 v[64:67], v[206:209], v[238:241], v[64:67]
	v_mfma_f32_16x16x32_bf16 v[116:119], v[184:187], v[218:221], v[116:119]
	v_mfma_f32_16x16x32_bf16 v[112:115], v[210:213], v[218:221], v[112:115]
	v_mfma_f32_16x16x32_bf16 v[100:103], v[184:187], v[226:229], v[100:103]
	v_mfma_f32_16x16x32_bf16 v[96:99], v[210:213], v[226:229], v[96:99]
	v_mfma_f32_16x16x32_bf16 v[84:87], v[184:187], v[234:237], v[84:87]
	v_mfma_f32_16x16x32_bf16 v[80:83], v[210:213], v[234:237], v[80:83]
	v_mfma_f32_16x16x32_bf16 v[68:71], v[184:187], v[242:245], v[68:71]
	v_mfma_f32_16x16x32_bf16 v[64:67], v[210:213], v[242:245], v[64:67]
	s_barrier
	s_setprio 0
	s_add_i32 s35, s35, s12
	v_lshl_add_u64 v[142:143], s[8:9], 0, v[132:133]
	s_mov_b32 m0, s35
	ds_read_b128 v[214:217], v166 offset:16384
	ds_read_b128 v[218:221], v166 offset:17408
	ds_read_b128 v[222:225], v166 offset:18432
	ds_read_b128 v[226:229], v166 offset:19456
	ds_read_b128 v[230:233], v166 offset:20480
	ds_read_b128 v[234:237], v166 offset:21504
	ds_read_b128 v[238:241], v166 offset:22528
	ds_read_b128 v[242:245], v166 offset:23552
	global_load_lds_dwordx4 v[142:143], off
	s_add_i32 m0, s35, 0x2000
	s_add_u32 s58, s8, 0x40000
	v_lshl_add_u64 v[144:145], s[8:9], 0, v[128:129]
	s_addc_u32 s59, s9, 0
	s_add_i32 s35, s57, s12
	global_load_lds_dwordx4 v[144:145], off
	v_lshl_add_u64 v[146:147], s[58:59], 0, v[132:133]
	s_mov_b32 m0, s35
	v_lshl_add_u64 v[148:149], s[10:11], 0, v[130:131]
	global_load_lds_dwordx4 v[146:147], off
	v_lshl_add_u64 v[146:147], s[58:59], 0, v[128:129]
	s_add_i32 m0, s35, 0x2000
	s_nop 0
	global_load_lds_dwordx4 v[146:147], off
	v_lshl_add_u64 v[146:147], s[10:11], 0, v[134:135]
	s_mov_b32 m0, s66
	s_nop 0
	global_load_lds_dwordx4 v[146:147], off
	s_mov_b32 m0, s67
	s_nop 0
	global_load_lds_dwordx4 v[148:149], off
	s_waitcnt vmcnt(8)
	s_waitcnt lgkmcnt(0)
	s_barrier
	v_mfma_f32_16x16x32_bf16 v[60:63], v[158:161], v[214:217], v[60:63]
	s_setprio 1
	v_mfma_f32_16x16x32_bf16 v[56:59], v[172:175], v[214:217], v[56:59]
	v_mfma_f32_16x16x32_bf16 v[44:47], v[158:161], v[222:225], v[44:47]
	v_mfma_f32_16x16x32_bf16 v[40:43], v[172:175], v[222:225], v[40:43]
	v_mfma_f32_16x16x32_bf16 v[28:31], v[158:161], v[230:233], v[28:31]
	v_mfma_f32_16x16x32_bf16 v[24:27], v[172:175], v[230:233], v[24:27]
	v_mfma_f32_16x16x32_bf16 v[12:15], v[158:161], v[238:241], v[12:15]
	v_mfma_f32_16x16x32_bf16 v[8:11], v[172:175], v[238:241], v[8:11]
	v_mfma_f32_16x16x32_bf16 v[60:63], v[168:171], v[218:221], v[60:63]
	v_mfma_f32_16x16x32_bf16 v[56:59], v[176:179], v[218:221], v[56:59]
	v_mfma_f32_16x16x32_bf16 v[44:47], v[168:171], v[226:229], v[44:47]
	v_mfma_f32_16x16x32_bf16 v[40:43], v[176:179], v[226:229], v[40:43]
	v_mfma_f32_16x16x32_bf16 v[28:31], v[168:171], v[234:237], v[28:31]
	v_mfma_f32_16x16x32_bf16 v[24:27], v[176:179], v[234:237], v[24:27]
	v_mfma_f32_16x16x32_bf16 v[12:15], v[168:171], v[242:245], v[12:15]
	v_mfma_f32_16x16x32_bf16 v[8:11], v[176:179], v[242:245], v[8:11]
	v_mfma_f32_16x16x32_bf16 v[52:55], v[180:183], v[214:217], v[52:55]
	v_mfma_f32_16x16x32_bf16 v[48:51], v[206:209], v[214:217], v[48:51]
	v_mfma_f32_16x16x32_bf16 v[36:39], v[180:183], v[222:225], v[36:39]
	v_mfma_f32_16x16x32_bf16 v[32:35], v[206:209], v[222:225], v[32:35]
	v_mfma_f32_16x16x32_bf16 v[20:23], v[180:183], v[230:233], v[20:23]
	v_mfma_f32_16x16x32_bf16 v[16:19], v[206:209], v[230:233], v[16:19]
	v_mfma_f32_16x16x32_bf16 v[4:7], v[180:183], v[238:241], v[4:7]
	v_mfma_f32_16x16x32_bf16 v[0:3], v[206:209], v[238:241], v[0:3]
	v_mfma_f32_16x16x32_bf16 v[52:55], v[184:187], v[218:221], v[52:55]
	v_mfma_f32_16x16x32_bf16 v[48:51], v[210:213], v[218:221], v[48:51]
	v_mfma_f32_16x16x32_bf16 v[36:39], v[184:187], v[226:229], v[36:39]
	v_mfma_f32_16x16x32_bf16 v[32:35], v[210:213], v[226:229], v[32:35]
	v_mfma_f32_16x16x32_bf16 v[20:23], v[184:187], v[234:237], v[20:23]
	v_mfma_f32_16x16x32_bf16 v[16:19], v[210:213], v[234:237], v[16:19]
	v_mfma_f32_16x16x32_bf16 v[4:7], v[184:187], v[242:245], v[4:7]
	v_mfma_f32_16x16x32_bf16 v[0:3], v[210:213], v[242:245], v[0:3]
	s_barrier
	s_setprio 0
	s_add_i32 s35, 0, 0x18000
	v_add_u32_e32 v140, s35, v165
	s_add_i32 s57, 0, 0x1c000
	ds_read_b128 v[158:161], v140
	ds_read_b128 v[168:171], v140 offset:1024
	ds_read_b128 v[172:175], v140 offset:2048
	ds_read_b128 v[176:179], v140 offset:3072
	v_add_u32_e32 v140, s57, v165
	ds_read_b128 v[180:183], v140
	ds_read_b128 v[184:187], v140 offset:1024
	ds_read_b128 v[206:209], v140 offset:2048
	ds_read_b128 v[210:213], v140 offset:3072
	s_add_u32 s10, s10, 0x40000
	s_addc_u32 s11, s11, 0
	s_mov_b32 m0, s74
	v_lshl_add_u64 v[150:151], s[10:11], 0, v[134:135]
	ds_read_b128 v[214:217], v166 offset:32768
	ds_read_b128 v[218:221], v166 offset:33792
	ds_read_b128 v[222:225], v166 offset:34816
	ds_read_b128 v[226:229], v166 offset:35840
	ds_read_b128 v[230:233], v166 offset:36864
	ds_read_b128 v[234:237], v166 offset:37888
	ds_read_b128 v[238:241], v166 offset:38912
	ds_read_b128 v[242:245], v166 offset:39936
	global_load_lds_dwordx4 v[150:151], off
	v_lshl_add_u64 v[150:151], s[10:11], 0, v[130:131]
	s_mov_b32 m0, s75
	s_nop 0
	global_load_lds_dwordx4 v[150:151], off
	s_waitcnt vmcnt(8)
	s_waitcnt lgkmcnt(0)
	s_barrier
	v_mfma_f32_16x16x32_bf16 v[124:127], v[158:161], v[214:217], v[124:127]
	s_setprio 1
	v_mfma_f32_16x16x32_bf16 v[120:123], v[172:175], v[214:217], v[120:123]
	v_mfma_f32_16x16x32_bf16 v[108:111], v[158:161], v[222:225], v[108:111]
	v_mfma_f32_16x16x32_bf16 v[104:107], v[172:175], v[222:225], v[104:107]
	v_mfma_f32_16x16x32_bf16 v[92:95], v[158:161], v[230:233], v[92:95]
	v_mfma_f32_16x16x32_bf16 v[88:91], v[172:175], v[230:233], v[88:91]
	v_mfma_f32_16x16x32_bf16 v[76:79], v[158:161], v[238:241], v[76:79]
	v_mfma_f32_16x16x32_bf16 v[72:75], v[172:175], v[238:241], v[72:75]
	v_mfma_f32_16x16x32_bf16 v[124:127], v[168:171], v[218:221], v[124:127]
	v_mfma_f32_16x16x32_bf16 v[120:123], v[176:179], v[218:221], v[120:123]
	v_mfma_f32_16x16x32_bf16 v[108:111], v[168:171], v[226:229], v[108:111]
	v_mfma_f32_16x16x32_bf16 v[104:107], v[176:179], v[226:229], v[104:107]
	v_mfma_f32_16x16x32_bf16 v[92:95], v[168:171], v[234:237], v[92:95]
	v_mfma_f32_16x16x32_bf16 v[88:91], v[176:179], v[234:237], v[88:91]
	v_mfma_f32_16x16x32_bf16 v[76:79], v[168:171], v[242:245], v[76:79]
	v_mfma_f32_16x16x32_bf16 v[72:75], v[176:179], v[242:245], v[72:75]
	v_mfma_f32_16x16x32_bf16 v[116:119], v[180:183], v[214:217], v[116:119]
	v_mfma_f32_16x16x32_bf16 v[112:115], v[206:209], v[214:217], v[112:115]
	v_mfma_f32_16x16x32_bf16 v[100:103], v[180:183], v[222:225], v[100:103]
	v_mfma_f32_16x16x32_bf16 v[96:99], v[206:209], v[222:225], v[96:99]
	v_mfma_f32_16x16x32_bf16 v[84:87], v[180:183], v[230:233], v[84:87]
	v_mfma_f32_16x16x32_bf16 v[80:83], v[206:209], v[230:233], v[80:83]
	v_mfma_f32_16x16x32_bf16 v[68:71], v[180:183], v[238:241], v[68:71]
	v_mfma_f32_16x16x32_bf16 v[64:67], v[206:209], v[238:241], v[64:67]
	v_mfma_f32_16x16x32_bf16 v[116:119], v[184:187], v[218:221], v[116:119]
	v_mfma_f32_16x16x32_bf16 v[112:115], v[210:213], v[218:221], v[112:115]
	v_mfma_f32_16x16x32_bf16 v[100:103], v[184:187], v[226:229], v[100:103]
	v_mfma_f32_16x16x32_bf16 v[96:99], v[210:213], v[226:229], v[96:99]
	v_mfma_f32_16x16x32_bf16 v[84:87], v[184:187], v[234:237], v[84:87]
	v_mfma_f32_16x16x32_bf16 v[80:83], v[210:213], v[234:237], v[80:83]
	v_mfma_f32_16x16x32_bf16 v[68:71], v[184:187], v[242:245], v[68:71]
	v_mfma_f32_16x16x32_bf16 v[64:67], v[210:213], v[242:245], v[64:67]
	s_barrier
	s_setprio 0
	s_add_i32 s10, s35, s12
	v_lshl_add_u64 v[142:143], v[142:143], 0, s[36:37]
	s_mov_b32 m0, s10
	ds_read_b128 v[214:217], v166 offset:49152
	ds_read_b128 v[218:221], v166 offset:50176
	ds_read_b128 v[222:225], v166 offset:51200
	ds_read_b128 v[226:229], v166 offset:52224
	ds_read_b128 v[230:233], v166 offset:53248
	ds_read_b128 v[234:237], v166 offset:54272
	ds_read_b128 v[238:241], v166 offset:55296
	ds_read_b128 v[242:245], v166 offset:56320
	global_load_lds_dwordx4 v[142:143], off
	s_add_i32 m0, s10, 0x2000
	s_add_u32 s8, s8, 0x40080
	v_lshl_add_u64 v[142:143], v[144:145], 0, s[36:37]
	s_addc_u32 s9, s9, 0
	s_add_i32 s10, s57, s12
	global_load_lds_dwordx4 v[142:143], off
	v_lshl_add_u64 v[142:143], s[8:9], 0, v[132:133]
	s_mov_b32 m0, s10
	s_nop 0
	global_load_lds_dwordx4 v[142:143], off
	v_lshl_add_u64 v[142:143], s[8:9], 0, v[128:129]
	s_add_i32 m0, s10, 0x2000
	s_nop 0
	global_load_lds_dwordx4 v[142:143], off
	v_lshl_add_u64 v[142:143], v[146:147], 0, s[36:37]
	s_mov_b32 m0, s26
	s_nop 0
	global_load_lds_dwordx4 v[142:143], off
	v_lshl_add_u64 v[142:143], v[148:149], 0, s[36:37]
	s_mov_b32 m0, s27
	s_nop 0
	global_load_lds_dwordx4 v[142:143], off
	s_waitcnt vmcnt(8)
	s_waitcnt lgkmcnt(0)
	s_barrier
	v_mfma_f32_16x16x32_bf16 v[60:63], v[158:161], v[214:217], v[60:63]
	s_setprio 1
	v_mfma_f32_16x16x32_bf16 v[56:59], v[172:175], v[214:217], v[56:59]
	v_mfma_f32_16x16x32_bf16 v[44:47], v[158:161], v[222:225], v[44:47]
	v_mfma_f32_16x16x32_bf16 v[40:43], v[172:175], v[222:225], v[40:43]
	v_mfma_f32_16x16x32_bf16 v[28:31], v[158:161], v[230:233], v[28:31]
	v_mfma_f32_16x16x32_bf16 v[24:27], v[172:175], v[230:233], v[24:27]
	v_mfma_f32_16x16x32_bf16 v[12:15], v[158:161], v[238:241], v[12:15]
	v_mfma_f32_16x16x32_bf16 v[8:11], v[172:175], v[238:241], v[8:11]
	v_mfma_f32_16x16x32_bf16 v[60:63], v[168:171], v[218:221], v[60:63]
	v_mfma_f32_16x16x32_bf16 v[56:59], v[176:179], v[218:221], v[56:59]
	v_mfma_f32_16x16x32_bf16 v[44:47], v[168:171], v[226:229], v[44:47]
	v_mfma_f32_16x16x32_bf16 v[40:43], v[176:179], v[226:229], v[40:43]
	v_mfma_f32_16x16x32_bf16 v[28:31], v[168:171], v[234:237], v[28:31]
	v_mfma_f32_16x16x32_bf16 v[24:27], v[176:179], v[234:237], v[24:27]
	v_mfma_f32_16x16x32_bf16 v[12:15], v[168:171], v[242:245], v[12:15]
	v_mfma_f32_16x16x32_bf16 v[8:11], v[176:179], v[242:245], v[8:11]
	v_mfma_f32_16x16x32_bf16 v[52:55], v[180:183], v[214:217], v[52:55]
	v_mfma_f32_16x16x32_bf16 v[48:51], v[206:209], v[214:217], v[48:51]
	v_mfma_f32_16x16x32_bf16 v[36:39], v[180:183], v[222:225], v[36:39]
	v_mfma_f32_16x16x32_bf16 v[32:35], v[206:209], v[222:225], v[32:35]
	v_mfma_f32_16x16x32_bf16 v[20:23], v[180:183], v[230:233], v[20:23]
	v_mfma_f32_16x16x32_bf16 v[16:19], v[206:209], v[230:233], v[16:19]
	v_mfma_f32_16x16x32_bf16 v[4:7], v[180:183], v[238:241], v[4:7]
	v_mfma_f32_16x16x32_bf16 v[0:3], v[206:209], v[238:241], v[0:3]
	v_mfma_f32_16x16x32_bf16 v[52:55], v[184:187], v[218:221], v[52:55]
	v_mfma_f32_16x16x32_bf16 v[48:51], v[210:213], v[218:221], v[48:51]
	v_mfma_f32_16x16x32_bf16 v[36:39], v[184:187], v[226:229], v[36:39]
	v_mfma_f32_16x16x32_bf16 v[32:35], v[210:213], v[226:229], v[32:35]
	v_mfma_f32_16x16x32_bf16 v[20:23], v[184:187], v[234:237], v[20:23]
	v_mfma_f32_16x16x32_bf16 v[16:19], v[210:213], v[234:237], v[16:19]
	v_mfma_f32_16x16x32_bf16 v[4:7], v[184:187], v[242:245], v[4:7]
	v_mfma_f32_16x16x32_bf16 v[0:3], v[210:213], v[242:245], v[0:3]
	s_barrier
	s_setprio 0
	s_add_i32 s56, s56, 2
	s_add_u32 s6, s6, 0x100
	s_addc_u32 s7, s7, 0
	s_add_u32 s47, s47, 0x100
	s_addc_u32 s51, s51, 0
	s_cmp_gt_u32 s56, 13
	s_cbranch_scc0 .LBB0_552
	s_and_b64 vcc, exec, s[44:45]
	s_cbranch_vccz .LBB0_555
	s_barrier

.LBB0_676:
	s_lshl_b32 s12, s61, 22
	s_and_b32 s35, s12, 0x3c00000
	s_ashr_i32 s12, s61, 4
	s_ashr_i32 s13, s12, 31
	s_lshl_b64 s[12:13], s[12:13], 9
	s_add_u32 s35, s14, s35
	s_addc_u32 s53, s15, 0
	s_add_u32 s54, s35, s12
	s_addc_u32 s55, s53, s13
	s_and_b64 s[56:57], s[42:43], exec
	s_cselect_b32 s59, s55, s9
	s_cselect_b32 s58, s54, s8
	s_ashr_i32 s53, s52, 31
	s_lshl_b64 s[56:57], s[52:53], 19
	s_add_u32 s35, s26, s56
	s_addc_u32 s53, s27, s57
	s_add_u32 s56, s35, s12
	s_addc_u32 s57, s53, s13
	s_and_b64 s[12:13], s[42:43], exec
	s_cselect_b32 s13, s57, s11
	s_cselect_b32 s12, s56, s10
	s_add_i32 s70, 0, 0x10000
	s_add_i32 s71, 0, 0x14000
	v_add_u32_e32 v152, s70, v138
	v_add_u32_e32 v153, s71, v138
	ds_read_b128 v[0:3], v152
	ds_read_b128 v[4:7], v152 offset:1024
	ds_read_b128 v[8:11], v152 offset:2048
	ds_read_b128 v[12:15], v152 offset:3072
	ds_read_b128 v[16:19], v153
	ds_read_b128 v[20:23], v153 offset:1024
	ds_read_b128 v[24:27], v153 offset:2048
	ds_read_b128 v[28:31], v153 offset:3072
	v_mov_b32_e32 v204, 0x358637bd
	v_mov_b32_e32 v250, 0x260
	v_mov_b32_e32 v251, 0x3e124925
	s_add_u32 s68, s8, 0x200080
	s_addc_u32 s69, s9, 0
	s_add_i32 s72, s4, 0xc000
	v_lshl_add_u64 v[64:65], s[68:69], 0, v[132:133]
	s_mov_b32 m0, s72
	s_add_i32 s35, s4, 0xe000
	ds_read_b128 v[32:35], v139
	ds_read_b128 v[36:39], v139 offset:1024
	ds_read_b128 v[40:43], v139 offset:2048
	ds_read_b128 v[44:47], v139 offset:3072
	ds_read_b128 v[48:51], v139 offset:4096
	ds_read_b128 v[52:55], v139 offset:5120
	ds_read_b128 v[56:59], v139 offset:6144
	ds_read_b128 v[60:63], v139 offset:7168
	global_load_lds_dwordx4 v[64:65], off
	v_lshl_add_u64 v[64:65], s[68:69], 0, v[130:131]
	s_mov_b32 m0, s35
	s_nop 0
	global_load_lds_dwordx4 v[64:65], off
	s_waitcnt vmcnt(8)
	s_waitcnt lgkmcnt(0)
	s_barrier
	v_mfma_f32_16x16x32_bf16 v[64:67], v[0:3], v[32:35], 0
	s_setprio 1
	v_mfma_f32_16x16x32_bf16 v[68:71], v[8:11], v[32:35], 0
	v_mfma_f32_16x16x32_bf16 v[72:75], v[0:3], v[40:43], 0
	v_mfma_f32_16x16x32_bf16 v[76:79], v[8:11], v[40:43], 0
	v_mfma_f32_16x16x32_bf16 v[80:83], v[0:3], v[48:51], 0
	v_mfma_f32_16x16x32_bf16 v[84:87], v[8:11], v[48:51], 0
	v_mfma_f32_16x16x32_bf16 v[88:91], v[0:3], v[56:59], 0
	v_mfma_f32_16x16x32_bf16 v[92:95], v[8:11], v[56:59], 0
	v_mfma_f32_16x16x32_bf16 v[64:67], v[4:7], v[36:39], v[64:67]
	v_mfma_f32_16x16x32_bf16 v[68:71], v[12:15], v[36:39], v[68:71]
	v_mfma_f32_16x16x32_bf16 v[72:75], v[4:7], v[44:47], v[72:75]
	v_mfma_f32_16x16x32_bf16 v[76:79], v[12:15], v[44:47], v[76:79]
	v_mfma_f32_16x16x32_bf16 v[80:83], v[4:7], v[52:55], v[80:83]
	v_mfma_f32_16x16x32_bf16 v[84:87], v[12:15], v[52:55], v[84:87]
	v_mfma_f32_16x16x32_bf16 v[88:91], v[4:7], v[60:63], v[88:91]
	v_mfma_f32_16x16x32_bf16 v[92:95], v[12:15], v[60:63], v[92:95]
	v_mfma_f32_16x16x32_bf16 v[96:99], v[16:19], v[32:35], 0
	v_mfma_f32_16x16x32_bf16 v[32:35], v[24:27], v[32:35], 0
	v_mfma_f32_16x16x32_bf16 v[96:99], v[20:23], v[36:39], v[96:99]
	v_mfma_f32_16x16x32_bf16 v[32:35], v[28:31], v[36:39], v[32:35]
	v_mfma_f32_16x16x32_bf16 v[36:39], v[16:19], v[40:43], 0
	v_mfma_f32_16x16x32_bf16 v[40:43], v[24:27], v[40:43], 0
	v_mfma_f32_16x16x32_bf16 v[36:39], v[20:23], v[44:47], v[36:39]
	v_mfma_f32_16x16x32_bf16 v[40:43], v[28:31], v[44:47], v[40:43]
	v_mfma_f32_16x16x32_bf16 v[44:47], v[16:19], v[48:51], 0
	v_mfma_f32_16x16x32_bf16 v[48:51], v[24:27], v[48:51], 0
	v_mfma_f32_16x16x32_bf16 v[44:47], v[20:23], v[52:55], v[44:47]
	v_mfma_f32_16x16x32_bf16 v[48:51], v[28:31], v[52:55], v[48:51]
	v_mfma_f32_16x16x32_bf16 v[52:55], v[16:19], v[56:59], 0
	v_mfma_f32_16x16x32_bf16 v[56:59], v[24:27], v[56:59], 0
	v_mfma_f32_16x16x32_bf16 v[52:55], v[20:23], v[60:63], v[52:55]
	v_mfma_f32_16x16x32_bf16 v[56:59], v[28:31], v[60:63], v[56:59]
	s_barrier
	s_setprio 0
	s_add_i32 s70, s70, s28
	v_lshl_add_u64 v[142:143], s[10:11], 0, v[140:141]
	s_mov_b64 s[2:3], 0x100
	s_add_i32 s53, s70, 0x2000
	v_lshl_add_u64 v[134:135], v[142:143], 0, s[2:3]
	s_mov_b32 m0, s70
	v_lshl_add_u64 v[144:145], s[10:11], 0, v[128:129]
	s_add_u32 s74, s10, 0x40100
	ds_read_b128 v[60:63], v139 offset:16384
	ds_read_b128 v[100:103], v139 offset:17408
	ds_read_b128 v[104:107], v139 offset:18432
	ds_read_b128 v[108:111], v139 offset:19456
	ds_read_b128 v[112:115], v139 offset:20480
	ds_read_b128 v[116:119], v139 offset:21504
	ds_read_b128 v[120:123], v139 offset:22528
	ds_read_b128 v[124:127], v139 offset:23552
	global_load_lds_dwordx4 v[134:135], off
	v_lshl_add_u64 v[134:135], v[144:145], 0, s[2:3]
	s_mov_b32 m0, s53
	s_addc_u32 s75, s11, 0
	s_add_i32 s68, s71, s28
	global_load_lds_dwordx4 v[134:135], off
	v_lshl_add_u64 v[134:135], s[74:75], 0, v[140:141]
	s_mov_b32 m0, s68
	s_add_i32 s69, s68, 0x2000
	global_load_lds_dwordx4 v[134:135], off
	v_lshl_add_u64 v[134:135], s[74:75], 0, v[128:129]
	s_mov_b32 m0, s69
	v_lshl_add_u64 v[146:147], s[8:9], 0, v[132:133]
	global_load_lds_dwordx4 v[134:135], off
	v_lshl_add_u64 v[134:135], v[146:147], 0, s[2:3]
	s_mov_b32 m0, s4
	v_lshl_add_u64 v[148:149], s[8:9], 0, v[130:131]
	global_load_lds_dwordx4 v[134:135], off
	v_lshl_add_u64 v[134:135], v[148:149], 0, s[2:3]
	s_mov_b32 m0, s5
	s_nop 0
	global_load_lds_dwordx4 v[134:135], off
	s_waitcnt vmcnt(8)
	s_waitcnt lgkmcnt(0)
	s_barrier
	v_mfma_f32_16x16x32_bf16 v[134:137], v[0:3], v[60:63], 0
	s_setprio 1
	v_mfma_f32_16x16x32_bf16 v[162:165], v[0:3], v[104:107], 0
	v_mfma_f32_16x16x32_bf16 v[170:173], v[0:3], v[112:115], 0
	v_mfma_f32_16x16x32_bf16 v[0:3], v[0:3], v[120:123], 0
	v_mfma_f32_16x16x32_bf16 v[134:137], v[4:7], v[100:103], v[134:137]
	v_mfma_f32_16x16x32_bf16 v[162:165], v[4:7], v[108:111], v[162:165]
	v_mfma_f32_16x16x32_bf16 v[170:173], v[4:7], v[116:119], v[170:173]
	v_mfma_f32_16x16x32_bf16 v[0:3], v[4:7], v[124:127], v[0:3]
	v_mfma_f32_16x16x32_bf16 v[4:7], v[8:11], v[120:123], 0
	v_mfma_f32_16x16x32_bf16 v[158:161], v[8:11], v[60:63], 0
	v_mfma_f32_16x16x32_bf16 v[166:169], v[8:11], v[104:107], 0
	v_mfma_f32_16x16x32_bf16 v[174:177], v[8:11], v[112:115], 0
	v_mfma_f32_16x16x32_bf16 v[4:7], v[12:15], v[124:127], v[4:7]
	v_mfma_f32_16x16x32_bf16 v[158:161], v[12:15], v[100:103], v[158:161]
	v_mfma_f32_16x16x32_bf16 v[166:169], v[12:15], v[108:111], v[166:169]
	v_mfma_f32_16x16x32_bf16 v[174:177], v[12:15], v[116:119], v[174:177]
	v_mfma_f32_16x16x32_bf16 v[8:11], v[16:19], v[60:63], 0
	v_mfma_f32_16x16x32_bf16 v[12:15], v[24:27], v[60:63], 0
	v_mfma_f32_16x16x32_bf16 v[8:11], v[20:23], v[100:103], v[8:11]
	v_mfma_f32_16x16x32_bf16 v[12:15], v[28:31], v[100:103], v[12:15]
	v_mfma_f32_16x16x32_bf16 v[60:63], v[16:19], v[104:107], 0
	v_mfma_f32_16x16x32_bf16 v[100:103], v[24:27], v[104:107], 0
	v_mfma_f32_16x16x32_bf16 v[104:107], v[16:19], v[112:115], 0
	v_mfma_f32_16x16x32_bf16 v[16:19], v[16:19], v[120:123], 0
	v_mfma_f32_16x16x32_bf16 v[60:63], v[20:23], v[108:111], v[60:63]
	v_mfma_f32_16x16x32_bf16 v[100:103], v[28:31], v[108:111], v[100:103]
	v_mfma_f32_16x16x32_bf16 v[104:107], v[20:23], v[116:119], v[104:107]
	v_mfma_f32_16x16x32_bf16 v[108:111], v[24:27], v[112:115], 0
	v_mfma_f32_16x16x32_bf16 v[16:19], v[20:23], v[124:127], v[16:19]
	v_mfma_f32_16x16x32_bf16 v[20:23], v[24:27], v[120:123], 0
	v_mfma_f32_16x16x32_bf16 v[108:111], v[28:31], v[116:119], v[108:111]
	v_mfma_f32_16x16x32_bf16 v[20:23], v[28:31], v[124:127], v[20:23]
	s_barrier
	s_setprio 0
	s_add_i32 s73, 0, 0x18000
	s_add_i32 s76, 0, 0x1c000
	v_add_u32_e32 v154, s73, v138
	v_add_u32_e32 v155, s76, v138
	ds_read_b128 v[24:27], v154
	ds_read_b128 v[28:31], v154 offset:1024
	ds_read_b128 v[112:115], v154 offset:2048
	ds_read_b128 v[116:119], v154 offset:3072
	ds_read_b128 v[120:123], v155
	ds_read_b128 v[124:127], v155 offset:1024
	ds_read_b128 v[178:181], v155 offset:2048
	ds_read_b128 v[182:185], v155 offset:3072
	s_add_u32 s74, s8, 0x200100
	s_addc_u32 s75, s9, 0
	s_mov_b32 m0, s24
	v_lshl_add_u64 v[150:151], s[74:75], 0, v[132:133]
	ds_read_b128 v[206:209], v139 offset:32768
	ds_read_b128 v[210:213], v139 offset:33792
	ds_read_b128 v[214:217], v139 offset:34816
	ds_read_b128 v[218:221], v139 offset:35840
	ds_read_b128 v[222:225], v139 offset:36864
	ds_read_b128 v[226:229], v139 offset:37888
	ds_read_b128 v[230:233], v139 offset:38912
	ds_read_b128 v[234:237], v139 offset:39936
	global_load_lds_dwordx4 v[150:151], off
	v_lshl_add_u64 v[150:151], s[74:75], 0, v[130:131]
	s_mov_b32 m0, s29
	s_nop 0
	global_load_lds_dwordx4 v[150:151], off
	s_waitcnt vmcnt(8)
	s_waitcnt lgkmcnt(0)
	s_barrier
	v_mfma_f32_16x16x32_bf16 v[64:67], v[24:27], v[206:209], v[64:67]
	s_setprio 1
	v_mfma_f32_16x16x32_bf16 v[68:71], v[112:115], v[206:209], v[68:71]
	v_mfma_f32_16x16x32_bf16 v[72:75], v[24:27], v[214:217], v[72:75]
	v_mfma_f32_16x16x32_bf16 v[76:79], v[112:115], v[214:217], v[76:79]
	v_mfma_f32_16x16x32_bf16 v[80:83], v[24:27], v[222:225], v[80:83]
	v_mfma_f32_16x16x32_bf16 v[84:87], v[112:115], v[222:225], v[84:87]
	v_mfma_f32_16x16x32_bf16 v[88:91], v[24:27], v[230:233], v[88:91]
	v_mfma_f32_16x16x32_bf16 v[92:95], v[112:115], v[230:233], v[92:95]
	v_mfma_f32_16x16x32_bf16 v[64:67], v[28:31], v[210:213], v[64:67]
	v_mfma_f32_16x16x32_bf16 v[68:71], v[116:119], v[210:213], v[68:71]
	v_mfma_f32_16x16x32_bf16 v[72:75], v[28:31], v[218:221], v[72:75]
	v_mfma_f32_16x16x32_bf16 v[76:79], v[116:119], v[218:221], v[76:79]
	v_mfma_f32_16x16x32_bf16 v[80:83], v[28:31], v[226:229], v[80:83]
	v_mfma_f32_16x16x32_bf16 v[84:87], v[116:119], v[226:229], v[84:87]
	v_mfma_f32_16x16x32_bf16 v[88:91], v[28:31], v[234:237], v[88:91]
	v_mfma_f32_16x16x32_bf16 v[92:95], v[116:119], v[234:237], v[92:95]
	v_mfma_f32_16x16x32_bf16 v[96:99], v[120:123], v[206:209], v[96:99]
	v_mfma_f32_16x16x32_bf16 v[32:35], v[178:181], v[206:209], v[32:35]
	v_mfma_f32_16x16x32_bf16 v[36:39], v[120:123], v[214:217], v[36:39]
	v_mfma_f32_16x16x32_bf16 v[40:43], v[178:181], v[214:217], v[40:43]
	v_mfma_f32_16x16x32_bf16 v[44:47], v[120:123], v[222:225], v[44:47]
	v_mfma_f32_16x16x32_bf16 v[48:51], v[178:181], v[222:225], v[48:51]
	v_mfma_f32_16x16x32_bf16 v[52:55], v[120:123], v[230:233], v[52:55]
	v_mfma_f32_16x16x32_bf16 v[56:59], v[178:181], v[230:233], v[56:59]
	v_mfma_f32_16x16x32_bf16 v[96:99], v[124:127], v[210:213], v[96:99]
	v_mfma_f32_16x16x32_bf16 v[32:35], v[182:185], v[210:213], v[32:35]
	v_mfma_f32_16x16x32_bf16 v[36:39], v[124:127], v[218:221], v[36:39]
	v_mfma_f32_16x16x32_bf16 v[40:43], v[182:185], v[218:221], v[40:43]
	v_mfma_f32_16x16x32_bf16 v[44:47], v[124:127], v[226:229], v[44:47]
	v_mfma_f32_16x16x32_bf16 v[48:51], v[182:185], v[226:229], v[48:51]
	v_mfma_f32_16x16x32_bf16 v[52:55], v[124:127], v[234:237], v[52:55]
	v_mfma_f32_16x16x32_bf16 v[56:59], v[182:185], v[234:237], v[56:59]
	s_barrier
	s_setprio 0
	s_add_i32 s73, s73, s28
	s_mov_b64 s[2:3], 0x180
	s_add_i32 s71, s73, 0x2000
	v_lshl_add_u64 v[142:143], v[142:143], 0, s[2:3]
	s_mov_b32 m0, s73
	s_add_u32 s74, s10, 0x40180
	ds_read_b128 v[206:209], v139 offset:49152
	ds_read_b128 v[210:213], v139 offset:50176
	ds_read_b128 v[214:217], v139 offset:51200
	ds_read_b128 v[218:221], v139 offset:52224
	ds_read_b128 v[222:225], v139 offset:53248
	ds_read_b128 v[226:229], v139 offset:54272
	ds_read_b128 v[230:233], v139 offset:55296
	ds_read_b128 v[234:237], v139 offset:56320
	global_load_lds_dwordx4 v[142:143], off
	v_lshl_add_u64 v[142:143], v[144:145], 0, s[2:3]
	s_mov_b32 m0, s71
	s_addc_u32 s75, s11, 0
	s_add_i32 s10, s76, s28
	global_load_lds_dwordx4 v[142:143], off
	v_lshl_add_u64 v[142:143], s[74:75], 0, v[140:141]
	s_mov_b32 m0, s10
	s_add_i32 s11, s10, 0x2000
	global_load_lds_dwordx4 v[142:143], off
	v_lshl_add_u64 v[142:143], s[74:75], 0, v[128:129]
	s_mov_b32 m0, s11
	s_nop 0
	global_load_lds_dwordx4 v[142:143], off
	v_lshl_add_u64 v[142:143], v[146:147], 0, s[2:3]
	s_mov_b32 m0, s38
	s_nop 0
	global_load_lds_dwordx4 v[142:143], off
	v_lshl_add_u64 v[142:143], v[148:149], 0, s[2:3]
	s_mov_b32 m0, s60
	s_nop 0
	global_load_lds_dwordx4 v[142:143], off
	s_waitcnt vmcnt(8)
	s_waitcnt lgkmcnt(0)
	s_barrier
	v_mfma_f32_16x16x32_bf16 v[0:3], v[24:27], v[230:233], v[0:3]
	s_setprio 1
	v_mfma_f32_16x16x32_bf16 v[4:7], v[112:115], v[230:233], v[4:7]
	v_mfma_f32_16x16x32_bf16 v[134:137], v[24:27], v[206:209], v[134:137]
	v_mfma_f32_16x16x32_bf16 v[158:161], v[112:115], v[206:209], v[158:161]
	v_mfma_f32_16x16x32_bf16 v[162:165], v[24:27], v[214:217], v[162:165]
	v_mfma_f32_16x16x32_bf16 v[166:169], v[112:115], v[214:217], v[166:169]
	v_mfma_f32_16x16x32_bf16 v[170:173], v[24:27], v[222:225], v[170:173]
	v_mfma_f32_16x16x32_bf16 v[174:177], v[112:115], v[222:225], v[174:177]
	v_mfma_f32_16x16x32_bf16 v[0:3], v[28:31], v[234:237], v[0:3]
	v_mfma_f32_16x16x32_bf16 v[4:7], v[116:119], v[234:237], v[4:7]
	v_mfma_f32_16x16x32_bf16 v[134:137], v[28:31], v[210:213], v[134:137]
	v_mfma_f32_16x16x32_bf16 v[158:161], v[116:119], v[210:213], v[158:161]
	v_mfma_f32_16x16x32_bf16 v[162:165], v[28:31], v[218:221], v[162:165]
	v_mfma_f32_16x16x32_bf16 v[166:169], v[116:119], v[218:221], v[166:169]
	v_mfma_f32_16x16x32_bf16 v[170:173], v[28:31], v[226:229], v[170:173]
	v_mfma_f32_16x16x32_bf16 v[174:177], v[116:119], v[226:229], v[174:177]
	v_mfma_f32_16x16x32_bf16 v[8:11], v[120:123], v[206:209], v[8:11]
	v_mfma_f32_16x16x32_bf16 v[12:15], v[178:181], v[206:209], v[12:15]
	v_mfma_f32_16x16x32_bf16 v[24:27], v[120:123], v[214:217], v[60:63]
	v_mfma_f32_16x16x32_bf16 v[28:31], v[178:181], v[214:217], v[100:103]
	v_mfma_f32_16x16x32_bf16 v[60:63], v[120:123], v[222:225], v[104:107]
	v_mfma_f32_16x16x32_bf16 v[100:103], v[178:181], v[222:225], v[108:111]
	v_mfma_f32_16x16x32_bf16 v[16:19], v[120:123], v[230:233], v[16:19]
	v_mfma_f32_16x16x32_bf16 v[20:23], v[178:181], v[230:233], v[20:23]
	v_mfma_f32_16x16x32_bf16 v[8:11], v[124:127], v[210:213], v[8:11]
	v_mfma_f32_16x16x32_bf16 v[12:15], v[182:185], v[210:213], v[12:15]
	v_mfma_f32_16x16x32_bf16 v[24:27], v[124:127], v[218:221], v[24:27]
	v_mfma_f32_16x16x32_bf16 v[28:31], v[182:185], v[218:221], v[28:31]
	v_mfma_f32_16x16x32_bf16 v[60:63], v[124:127], v[226:229], v[60:63]
	v_mfma_f32_16x16x32_bf16 v[100:103], v[182:185], v[226:229], v[100:103]
	v_mfma_f32_16x16x32_bf16 v[16:19], v[124:127], v[234:237], v[16:19]
	v_mfma_f32_16x16x32_bf16 v[20:23], v[182:185], v[234:237], v[20:23]
	s_barrier
	s_setprio 0
	ds_read_b128 v[104:107], v152
	ds_read_b128 v[108:111], v152 offset:1024
	ds_read_b128 v[112:115], v152 offset:2048
	ds_read_b128 v[116:119], v152 offset:3072
	ds_read_b128 v[120:123], v153
	ds_read_b128 v[124:127], v153 offset:1024
	ds_read_b128 v[178:181], v153 offset:2048
	ds_read_b128 v[182:185], v153 offset:3072
	s_add_u32 s8, s8, 0x200180
	s_addc_u32 s9, s9, 0
	s_mov_b32 m0, s72
	v_lshl_add_u64 v[142:143], s[8:9], 0, v[132:133]
	ds_read_b128 v[206:209], v139
	ds_read_b128 v[210:213], v139 offset:1024
	ds_read_b128 v[214:217], v139 offset:2048
	ds_read_b128 v[218:221], v139 offset:3072
	ds_read_b128 v[222:225], v139 offset:4096
	ds_read_b128 v[226:229], v139 offset:5120
	ds_read_b128 v[230:233], v139 offset:6144
	ds_read_b128 v[234:237], v139 offset:7168
	global_load_lds_dwordx4 v[142:143], off
	v_lshl_add_u64 v[142:143], s[8:9], 0, v[130:131]
	s_mov_b32 m0, s35
	s_nop 0
	global_load_lds_dwordx4 v[142:143], off
	s_waitcnt vmcnt(8)
	s_waitcnt lgkmcnt(0)
	s_barrier
	v_mfma_f32_16x16x32_bf16 v[64:67], v[104:107], v[206:209], v[64:67]
	s_setprio 1
	v_mfma_f32_16x16x32_bf16 v[68:71], v[112:115], v[206:209], v[68:71]
	v_mfma_f32_16x16x32_bf16 v[72:75], v[104:107], v[214:217], v[72:75]
	v_mfma_f32_16x16x32_bf16 v[76:79], v[112:115], v[214:217], v[76:79]
	v_mfma_f32_16x16x32_bf16 v[80:83], v[104:107], v[222:225], v[80:83]
	v_mfma_f32_16x16x32_bf16 v[84:87], v[112:115], v[222:225], v[84:87]
	v_mfma_f32_16x16x32_bf16 v[88:91], v[104:107], v[230:233], v[88:91]
	v_mfma_f32_16x16x32_bf16 v[64:67], v[108:111], v[210:213], v[64:67]
	v_mfma_f32_16x16x32_bf16 v[68:71], v[116:119], v[210:213], v[68:71]
	v_mfma_f32_16x16x32_bf16 v[72:75], v[108:111], v[218:221], v[72:75]
	v_mfma_f32_16x16x32_bf16 v[76:79], v[116:119], v[218:221], v[76:79]
	v_mfma_f32_16x16x32_bf16 v[80:83], v[108:111], v[226:229], v[80:83]
	v_mfma_f32_16x16x32_bf16 v[84:87], v[116:119], v[226:229], v[84:87]
	v_mfma_f32_16x16x32_bf16 v[238:241], v[108:111], v[234:237], v[88:91]
	v_mfma_f32_16x16x32_bf16 v[88:91], v[112:115], v[230:233], v[92:95]
	v_mfma_f32_16x16x32_bf16 v[242:245], v[116:119], v[234:237], v[88:91]
	v_mfma_f32_16x16x32_bf16 v[88:91], v[120:123], v[206:209], v[96:99]
	v_mfma_f32_16x16x32_bf16 v[32:35], v[178:181], v[206:209], v[32:35]
	v_mfma_f32_16x16x32_bf16 v[36:39], v[120:123], v[214:217], v[36:39]
	v_mfma_f32_16x16x32_bf16 v[40:43], v[178:181], v[214:217], v[40:43]
	v_mfma_f32_16x16x32_bf16 v[44:47], v[120:123], v[222:225], v[44:47]
	v_mfma_f32_16x16x32_bf16 v[48:51], v[178:181], v[222:225], v[48:51]
	v_mfma_f32_16x16x32_bf16 v[52:55], v[120:123], v[230:233], v[52:55]
	v_mfma_f32_16x16x32_bf16 v[56:59], v[178:181], v[230:233], v[56:59]
	v_mfma_f32_16x16x32_bf16 v[96:99], v[124:127], v[210:213], v[88:91]
	v_mfma_f32_16x16x32_bf16 v[32:35], v[182:185], v[210:213], v[32:35]
	v_mfma_f32_16x16x32_bf16 v[36:39], v[124:127], v[218:221], v[36:39]
	v_mfma_f32_16x16x32_bf16 v[40:43], v[182:185], v[218:221], v[40:43]
	v_mfma_f32_16x16x32_bf16 v[44:47], v[124:127], v[226:229], v[44:47]
	v_mfma_f32_16x16x32_bf16 v[48:51], v[182:185], v[226:229], v[48:51]
	v_mfma_f32_16x16x32_bf16 v[52:55], v[124:127], v[234:237], v[52:55]
	v_mfma_f32_16x16x32_bf16 v[56:59], v[182:185], v[234:237], v[56:59]
	s_barrier
	s_setprio 0
	s_mov_b32 m0, s70
	v_lshl_add_u64 v[190:191], s[12:13], 0, v[140:141]
	s_add_u32 s8, s12, 0x40000
	ds_read_b128 v[88:91], v139 offset:16384
	ds_read_b128 v[92:95], v139 offset:17408
	ds_read_b128 v[206:209], v139 offset:18432
	ds_read_b128 v[210:213], v139 offset:19456
	ds_read_b128 v[214:217], v139 offset:20480
	ds_read_b128 v[218:221], v139 offset:21504
	ds_read_b128 v[222:225], v139 offset:22528
	ds_read_b128 v[226:229], v139 offset:23552
	global_load_lds_dwordx4 v[190:191], off
	v_lshl_add_u64 v[192:193], s[12:13], 0, v[128:129]
	s_mov_b32 m0, s53
	s_addc_u32 s9, s13, 0
	global_load_lds_dwordx4 v[192:193], off
	v_lshl_add_u64 v[142:143], s[8:9], 0, v[140:141]
	s_mov_b32 m0, s68
	v_lshl_add_u64 v[194:195], s[58:59], 0, v[132:133]
	global_load_lds_dwordx4 v[142:143], off
	v_lshl_add_u64 v[142:143], s[8:9], 0, v[128:129]
	s_mov_b32 m0, s69
	v_lshl_add_u64 v[196:197], s[58:59], 0, v[130:131]
	global_load_lds_dwordx4 v[142:143], off
	s_mov_b32 m0, s4
	s_nop 0
	global_load_lds_dwordx4 v[194:195], off
	s_mov_b32 m0, s5
	s_nop 0
	global_load_lds_dwordx4 v[196:197], off
	s_waitcnt vmcnt(8)
	s_waitcnt lgkmcnt(0)
	s_barrier
	v_mfma_f32_16x16x32_bf16 v[0:3], v[104:107], v[222:225], v[0:3]
	s_setprio 1
	v_mfma_f32_16x16x32_bf16 v[4:7], v[112:115], v[222:225], v[4:7]
	v_mfma_f32_16x16x32_bf16 v[134:137], v[104:107], v[88:91], v[134:137]
	v_mfma_f32_16x16x32_bf16 v[158:161], v[112:115], v[88:91], v[158:161]
	v_mfma_f32_16x16x32_bf16 v[162:165], v[104:107], v[206:209], v[162:165]
	v_mfma_f32_16x16x32_bf16 v[166:169], v[112:115], v[206:209], v[166:169]
	v_mfma_f32_16x16x32_bf16 v[170:173], v[104:107], v[214:217], v[170:173]
	v_mfma_f32_16x16x32_bf16 v[174:177], v[112:115], v[214:217], v[174:177]
	v_mfma_f32_16x16x32_bf16 v[0:3], v[108:111], v[226:229], v[0:3]
	v_mfma_f32_16x16x32_bf16 v[4:7], v[116:119], v[226:229], v[4:7]
	v_mfma_f32_16x16x32_bf16 v[134:137], v[108:111], v[92:95], v[134:137]
	v_mfma_f32_16x16x32_bf16 v[158:161], v[116:119], v[92:95], v[158:161]
	v_mfma_f32_16x16x32_bf16 v[162:165], v[108:111], v[210:213], v[162:165]
	v_mfma_f32_16x16x32_bf16 v[166:169], v[116:119], v[210:213], v[166:169]
	v_mfma_f32_16x16x32_bf16 v[170:173], v[108:111], v[218:221], v[170:173]
	v_mfma_f32_16x16x32_bf16 v[174:177], v[116:119], v[218:221], v[174:177]
	v_mfma_f32_16x16x32_bf16 v[8:11], v[120:123], v[88:91], v[8:11]
	v_mfma_f32_16x16x32_bf16 v[230:233], v[124:127], v[92:95], v[8:11]
	v_mfma_f32_16x16x32_bf16 v[8:11], v[178:181], v[88:91], v[12:15]
	v_mfma_f32_16x16x32_bf16 v[234:237], v[182:185], v[92:95], v[8:11]
	v_mfma_f32_16x16x32_bf16 v[8:11], v[120:123], v[206:209], v[24:27]
	v_mfma_f32_16x16x32_bf16 v[246:249], v[124:127], v[210:213], v[8:11]
	v_mfma_f32_16x16x32_bf16 v[8:11], v[178:181], v[206:209], v[28:31]
	v_mfma_f32_16x16x32_bf16 v[206:209], v[182:185], v[210:213], v[8:11]
	v_mfma_f32_16x16x32_bf16 v[8:11], v[120:123], v[214:217], v[60:63]
	v_mfma_f32_16x16x32_bf16 v[210:213], v[124:127], v[218:221], v[8:11]
	v_mfma_f32_16x16x32_bf16 v[8:11], v[178:181], v[214:217], v[100:103]
	v_mfma_f32_16x16x32_bf16 v[214:217], v[182:185], v[218:221], v[8:11]
	v_mfma_f32_16x16x32_bf16 v[8:11], v[120:123], v[222:225], v[16:19]
	v_mfma_f32_16x16x32_bf16 v[218:221], v[124:127], v[226:229], v[8:11]
	v_mfma_f32_16x16x32_bf16 v[8:11], v[178:181], v[222:225], v[20:23]
	v_mfma_f32_16x16x32_bf16 v[178:181], v[182:185], v[226:229], v[8:11]
	s_barrier
	s_setprio 0
	s_nop 4
	ds_read_b128 v[8:11], v154
	ds_read_b128 v[12:15], v154 offset:1024
	ds_read_b128 v[16:19], v154 offset:2048
	ds_read_b128 v[20:23], v154 offset:3072
	ds_read_b128 v[182:185], v155
	ds_read_b128 v[222:225], v155 offset:1024
	ds_read_b128 v[226:229], v155 offset:2048
	ds_read_b128 v[142:145], v155 offset:3072
	s_add_u32 s8, s58, 0x200000
	s_addc_u32 s9, s59, 0
	s_mov_b32 m0, s24
	v_lshl_add_u64 v[88:89], s[8:9], 0, v[132:133]
	ds_read_b128 v[24:27], v139 offset:32768
	ds_read_b128 v[28:31], v139 offset:33792
	ds_read_b128 v[60:63], v139 offset:34816
	ds_read_b128 v[146:149], v139 offset:35840
	ds_read_b128 v[150:153], v139 offset:36864
	ds_read_b128 v[154:157], v139 offset:37888
	ds_read_b128 v[200:203], v139 offset:38912
	ds_read_b128 v[186:189], v139 offset:39936
	global_load_lds_dwordx4 v[88:89], off
	v_lshl_add_u64 v[88:89], s[8:9], 0, v[130:131]
	s_mov_b32 m0, s29
	s_nop 0
	global_load_lds_dwordx4 v[88:89], off
	s_waitcnt vmcnt(8)
	s_waitcnt lgkmcnt(0)
	s_barrier
	v_mfma_f32_16x16x32_bf16 v[64:67], v[8:11], v[24:27], v[64:67]
	s_setprio 1
	v_mfma_f32_16x16x32_bf16 v[124:127], v[12:15], v[28:31], v[64:67]
	v_mfma_f32_16x16x32_bf16 v[64:67], v[16:19], v[24:27], v[68:71]
	v_mfma_f32_16x16x32_bf16 v[120:123], v[20:23], v[28:31], v[64:67]
	v_mfma_f32_16x16x32_bf16 v[64:67], v[8:11], v[60:63], v[72:75]
	v_mfma_f32_16x16x32_bf16 v[108:111], v[12:15], v[146:149], v[64:67]
	v_mfma_f32_16x16x32_bf16 v[64:67], v[16:19], v[60:63], v[76:79]
	v_mfma_f32_16x16x32_bf16 v[104:107], v[20:23], v[146:149], v[64:67]
	v_mfma_f32_16x16x32_bf16 v[64:67], v[8:11], v[150:153], v[80:83]
	v_mfma_f32_16x16x32_bf16 v[92:95], v[12:15], v[154:157], v[64:67]
	v_mfma_f32_16x16x32_bf16 v[64:67], v[16:19], v[150:153], v[84:87]
	v_mfma_f32_16x16x32_bf16 v[88:91], v[20:23], v[154:157], v[64:67]
	v_mfma_f32_16x16x32_bf16 v[64:67], v[8:11], v[200:203], v[238:241]
	v_mfma_f32_16x16x32_bf16 v[68:71], v[12:15], v[186:189], v[64:67]
	v_mfma_f32_16x16x32_bf16 v[64:67], v[16:19], v[200:203], v[242:245]
	v_mfma_f32_16x16x32_bf16 v[64:67], v[20:23], v[186:189], v[64:67]
	v_mfma_f32_16x16x32_bf16 v[72:75], v[182:185], v[24:27], v[96:99]
	v_mfma_f32_16x16x32_bf16 v[24:27], v[226:229], v[24:27], v[32:35]
	v_mfma_f32_16x16x32_bf16 v[112:115], v[142:145], v[28:31], v[24:27]
	v_mfma_f32_16x16x32_bf16 v[24:27], v[182:185], v[60:63], v[36:39]
	v_mfma_f32_16x16x32_bf16 v[100:103], v[222:225], v[146:149], v[24:27]
	v_mfma_f32_16x16x32_bf16 v[24:27], v[226:229], v[60:63], v[40:43]
	v_mfma_f32_16x16x32_bf16 v[96:99], v[142:145], v[146:149], v[24:27]
	v_mfma_f32_16x16x32_bf16 v[24:27], v[182:185], v[150:153], v[44:47]
	v_mfma_f32_16x16x32_bf16 v[84:87], v[222:225], v[154:157], v[24:27]
	v_mfma_f32_16x16x32_bf16 v[24:27], v[226:229], v[150:153], v[48:51]
	v_mfma_f32_16x16x32_bf16 v[80:83], v[142:145], v[154:157], v[24:27]
	v_mfma_f32_16x16x32_bf16 v[24:27], v[182:185], v[200:203], v[52:55]
	v_mfma_f32_16x16x32_bf16 v[52:55], v[222:225], v[186:189], v[24:27]
	v_mfma_f32_16x16x32_bf16 v[24:27], v[226:229], v[200:203], v[56:59]
	v_mfma_f32_16x16x32_bf16 v[116:119], v[222:225], v[28:31], v[72:75]
	v_mfma_f32_16x16x32_bf16 v[48:51], v[142:145], v[186:189], v[24:27]
	s_barrier
	s_setprio 0
	s_mov_b32 m0, s73
	s_nop 2
	v_lshl_add_u64 v[24:25], v[190:191], 0, s[36:37]
	s_add_u32 s8, s12, 0x40080
	ds_read_b128 v[32:35], v139 offset:49152
	ds_read_b128 v[36:39], v139 offset:50176
	ds_read_b128 v[146:149], v139 offset:51200
	ds_read_b128 v[150:153], v139 offset:52224
	ds_read_b128 v[154:157], v139 offset:53248
	ds_read_b128 v[186:189], v139 offset:54272
	ds_read_b128 v[200:203], v139 offset:55296
	ds_read_b128 v[238:241], v139 offset:56320
	global_load_lds_dwordx4 v[24:25], off
	v_lshl_add_u64 v[24:25], v[192:193], 0, s[36:37]
	s_mov_b32 m0, s71
	s_addc_u32 s9, s13, 0
	global_load_lds_dwordx4 v[24:25], off
	v_lshl_add_u64 v[24:25], s[8:9], 0, v[140:141]
	s_mov_b32 m0, s10
	s_nop 0
	global_load_lds_dwordx4 v[24:25], off
	v_lshl_add_u64 v[24:25], s[8:9], 0, v[128:129]
	s_mov_b32 m0, s11
	s_nop 0
	global_load_lds_dwordx4 v[24:25], off
	v_lshl_add_u64 v[24:25], v[194:195], 0, s[36:37]
	s_mov_b32 m0, s38
	s_nop 0
	global_load_lds_dwordx4 v[24:25], off
	v_lshl_add_u64 v[24:25], v[196:197], 0, s[36:37]
	s_mov_b32 m0, s60
	s_nop 0
	global_load_lds_dwordx4 v[24:25], off
	s_waitcnt vmcnt(8)
	s_waitcnt lgkmcnt(0)
	s_barrier
	v_mfma_f32_16x16x32_bf16 v[24:27], v[8:11], v[32:35], v[134:137]
	s_setprio 1
	v_mfma_f32_16x16x32_bf16 v[76:79], v[12:15], v[36:39], v[24:27]
	v_mfma_f32_16x16x32_bf16 v[24:27], v[16:19], v[32:35], v[158:161]
	v_mfma_f32_16x16x32_bf16 v[72:75], v[20:23], v[36:39], v[24:27]
	v_mfma_f32_16x16x32_bf16 v[24:27], v[8:11], v[146:149], v[162:165]
	v_mfma_f32_16x16x32_bf16 v[44:47], v[12:15], v[150:153], v[24:27]
	v_mfma_f32_16x16x32_bf16 v[24:27], v[16:19], v[146:149], v[166:169]
	v_mfma_f32_16x16x32_bf16 v[40:43], v[20:23], v[150:153], v[24:27]
	v_mfma_f32_16x16x32_bf16 v[24:27], v[8:11], v[154:157], v[170:173]
	v_mfma_f32_16x16x32_bf16 v[0:3], v[8:11], v[200:203], v[0:3]
	v_mfma_f32_16x16x32_bf16 v[28:31], v[12:15], v[186:189], v[24:27]
	v_mfma_f32_16x16x32_bf16 v[24:27], v[16:19], v[154:157], v[174:177]
	v_mfma_f32_16x16x32_bf16 v[12:15], v[12:15], v[238:241], v[0:3]
	v_mfma_f32_16x16x32_bf16 v[0:3], v[16:19], v[200:203], v[4:7]
	v_mfma_f32_16x16x32_bf16 v[24:27], v[20:23], v[186:189], v[24:27]
	v_mfma_f32_16x16x32_bf16 v[8:11], v[20:23], v[238:241], v[0:3]
	v_mfma_f32_16x16x32_bf16 v[0:3], v[182:185], v[32:35], v[230:233]
	v_mfma_f32_16x16x32_bf16 v[60:63], v[222:225], v[36:39], v[0:3]
	v_mfma_f32_16x16x32_bf16 v[0:3], v[226:229], v[32:35], v[234:237]
	v_mfma_f32_16x16x32_bf16 v[56:59], v[142:145], v[36:39], v[0:3]
	v_mfma_f32_16x16x32_bf16 v[0:3], v[182:185], v[146:149], v[246:249]
	v_mfma_f32_16x16x32_bf16 v[36:39], v[222:225], v[150:153], v[0:3]
	v_mfma_f32_16x16x32_bf16 v[0:3], v[226:229], v[146:149], v[206:209]
	v_mfma_f32_16x16x32_bf16 v[32:35], v[142:145], v[150:153], v[0:3]
	v_mfma_f32_16x16x32_bf16 v[0:3], v[182:185], v[154:157], v[210:213]
	v_mfma_f32_16x16x32_bf16 v[20:23], v[222:225], v[186:189], v[0:3]
	v_mfma_f32_16x16x32_bf16 v[0:3], v[226:229], v[154:157], v[214:217]
	v_mfma_f32_16x16x32_bf16 v[16:19], v[142:145], v[186:189], v[0:3]
	v_mfma_f32_16x16x32_bf16 v[0:3], v[182:185], v[200:203], v[218:221]
	v_mfma_f32_16x16x32_bf16 v[4:7], v[222:225], v[238:241], v[0:3]
	v_mfma_f32_16x16x32_bf16 v[0:3], v[226:229], v[200:203], v[178:181]
	v_mfma_f32_16x16x32_bf16 v[0:3], v[142:145], v[238:241], v[0:3]
	s_barrier
	s_setprio 0
	s_andn2_b64 vcc, exec, s[48:49]
	s_cbranch_vccnz .LBB0_678
	s_barrier

.LBB0_694:
	s_ashr_i32 s48, s54, 4
	s_ashr_i32 s47, s46, 31
	s_ashr_i32 s49, s48, 31
	s_lshl_b64 s[12:13], s[46:47], 19
	s_lshl_b64 s[50:51], s[48:49], 9
	s_add_u32 s12, s4, s12
	s_addc_u32 s13, s5, s13
	s_add_u32 s48, s12, s50
	s_addc_u32 s49, s13, s51
	s_and_b64 s[12:13], s[40:41], exec
	s_cselect_b32 s53, s49, s9
	s_cselect_b32 s52, s48, s8
	s_lshl_b32 s12, s54, 22
	s_and_b32 s12, s12, 0x3c00000
	s_add_u32 s12, s14, s12
	s_addc_u32 s13, s15, 0
	s_add_u32 s50, s12, s50
	s_addc_u32 s51, s13, s51
	s_and_b64 s[12:13], s[40:41], exec
	s_cselect_b32 s13, s51, s11
	s_cselect_b32 s12, s50, s10
	s_add_i32 s47, 0, 0x10000
	s_add_i32 s57, 0, 0x14000
	v_add_u32_e32 v140, s47, v138
	v_add_u32_e32 v198, s57, v138
	ds_read_b128 v[0:3], v140
	ds_read_b128 v[4:7], v140 offset:1024
	ds_read_b128 v[8:11], v140 offset:2048
	ds_read_b128 v[12:15], v140 offset:3072
	ds_read_b128 v[16:19], v198
	ds_read_b128 v[20:23], v198 offset:1024
	ds_read_b128 v[24:27], v198 offset:2048
	ds_read_b128 v[28:31], v198 offset:3072
	v_mov_b32_e32 v252, 0x358637bd
	s_add_u32 s58, s8, 0x40080
	s_addc_u32 s59, s9, 0
	s_add_i32 s61, s25, 0xc000
	v_lshl_add_u64 v[64:65], s[58:59], 0, v[134:135]
	s_mov_b32 m0, s61
	s_add_i32 s35, s25, 0xe000
	ds_read_b128 v[32:35], v139
	ds_read_b128 v[36:39], v139 offset:1024
	ds_read_b128 v[40:43], v139 offset:2048
	ds_read_b128 v[44:47], v139 offset:3072
	ds_read_b128 v[48:51], v139 offset:4096
	ds_read_b128 v[52:55], v139 offset:5120
	ds_read_b128 v[56:59], v139 offset:6144
	ds_read_b128 v[60:63], v139 offset:7168
	global_load_lds_dwordx4 v[64:65], off
	v_lshl_add_u64 v[64:65], s[58:59], 0, v[130:131]
	s_mov_b32 m0, s35
	s_nop 0
	global_load_lds_dwordx4 v[64:65], off
	s_waitcnt vmcnt(8)
	s_waitcnt lgkmcnt(0)
	s_barrier
	v_mfma_f32_16x16x32_bf16 v[64:67], v[0:3], v[32:35], 0
	s_setprio 1
	v_mfma_f32_16x16x32_bf16 v[68:71], v[8:11], v[32:35], 0
	v_mfma_f32_16x16x32_bf16 v[72:75], v[0:3], v[40:43], 0
	v_mfma_f32_16x16x32_bf16 v[76:79], v[8:11], v[40:43], 0
	v_mfma_f32_16x16x32_bf16 v[80:83], v[0:3], v[48:51], 0
	v_mfma_f32_16x16x32_bf16 v[84:87], v[8:11], v[48:51], 0
	v_mfma_f32_16x16x32_bf16 v[88:91], v[0:3], v[56:59], 0
	v_mfma_f32_16x16x32_bf16 v[92:95], v[8:11], v[56:59], 0
	v_mfma_f32_16x16x32_bf16 v[64:67], v[4:7], v[36:39], v[64:67]
	v_mfma_f32_16x16x32_bf16 v[68:71], v[12:15], v[36:39], v[68:71]
	v_mfma_f32_16x16x32_bf16 v[72:75], v[4:7], v[44:47], v[72:75]
	v_mfma_f32_16x16x32_bf16 v[76:79], v[12:15], v[44:47], v[76:79]
	v_mfma_f32_16x16x32_bf16 v[80:83], v[4:7], v[52:55], v[80:83]
	v_mfma_f32_16x16x32_bf16 v[84:87], v[12:15], v[52:55], v[84:87]
	v_mfma_f32_16x16x32_bf16 v[88:91], v[4:7], v[60:63], v[88:91]
	v_mfma_f32_16x16x32_bf16 v[92:95], v[12:15], v[60:63], v[92:95]
	v_mfma_f32_16x16x32_bf16 v[96:99], v[16:19], v[32:35], 0
	v_mfma_f32_16x16x32_bf16 v[32:35], v[24:27], v[32:35], 0
	v_mfma_f32_16x16x32_bf16 v[96:99], v[20:23], v[36:39], v[96:99]
	v_mfma_f32_16x16x32_bf16 v[32:35], v[28:31], v[36:39], v[32:35]
	v_mfma_f32_16x16x32_bf16 v[36:39], v[16:19], v[40:43], 0
	v_mfma_f32_16x16x32_bf16 v[40:43], v[24:27], v[40:43], 0
	v_mfma_f32_16x16x32_bf16 v[36:39], v[20:23], v[44:47], v[36:39]
	v_mfma_f32_16x16x32_bf16 v[40:43], v[28:31], v[44:47], v[40:43]
	v_mfma_f32_16x16x32_bf16 v[44:47], v[16:19], v[48:51], 0
	v_mfma_f32_16x16x32_bf16 v[48:51], v[24:27], v[48:51], 0
	v_mfma_f32_16x16x32_bf16 v[44:47], v[20:23], v[52:55], v[44:47]
	v_mfma_f32_16x16x32_bf16 v[48:51], v[28:31], v[52:55], v[48:51]
	v_mfma_f32_16x16x32_bf16 v[52:55], v[16:19], v[56:59], 0
	v_mfma_f32_16x16x32_bf16 v[56:59], v[24:27], v[56:59], 0
	v_mfma_f32_16x16x32_bf16 v[52:55], v[20:23], v[60:63], v[52:55]
	v_mfma_f32_16x16x32_bf16 v[56:59], v[28:31], v[60:63], v[56:59]
	s_barrier
	s_setprio 0
	s_add_i32 s59, s47, s24
	v_lshl_add_u64 v[136:137], s[10:11], 0, v[132:133]
	s_mov_b64 s[68:69], 0x100
	s_add_i32 s47, s59, 0x2000
	v_lshl_add_u64 v[142:143], v[136:137], 0, s[68:69]
	s_mov_b32 m0, s59
	v_lshl_add_u64 v[190:191], s[10:11], 0, v[128:129]
	s_add_u32 s66, s10, 0x200100
	ds_read_b128 v[60:63], v139 offset:16384
	ds_read_b128 v[100:103], v139 offset:17408
	ds_read_b128 v[104:107], v139 offset:18432
	ds_read_b128 v[108:111], v139 offset:19456
	ds_read_b128 v[112:115], v139 offset:20480
	ds_read_b128 v[116:119], v139 offset:21504
	ds_read_b128 v[120:123], v139 offset:22528
	ds_read_b128 v[124:127], v139 offset:23552
	global_load_lds_dwordx4 v[142:143], off
	v_lshl_add_u64 v[142:143], v[190:191], 0, s[68:69]
	s_mov_b32 m0, s47
	s_addc_u32 s67, s11, 0
	s_add_i32 s57, s57, s24
	global_load_lds_dwordx4 v[142:143], off
	v_lshl_add_u64 v[142:143], s[66:67], 0, v[132:133]
	s_mov_b32 m0, s57
	s_add_i32 s58, s57, 0x2000
	global_load_lds_dwordx4 v[142:143], off
	v_lshl_add_u64 v[142:143], s[66:67], 0, v[128:129]
	s_mov_b32 m0, s58
	v_lshl_add_u64 v[192:193], s[8:9], 0, v[134:135]
	global_load_lds_dwordx4 v[142:143], off
	v_lshl_add_u64 v[142:143], v[192:193], 0, s[68:69]
	s_mov_b32 m0, s25
	v_lshl_add_u64 v[194:195], s[8:9], 0, v[130:131]
	global_load_lds_dwordx4 v[142:143], off
	v_lshl_add_u64 v[142:143], v[194:195], 0, s[68:69]
	s_mov_b32 m0, s26
	s_nop 0
	global_load_lds_dwordx4 v[142:143], off
	s_waitcnt vmcnt(8)
	s_waitcnt lgkmcnt(0)
	s_barrier
	v_mfma_f32_16x16x32_bf16 v[142:145], v[0:3], v[60:63], 0
	s_setprio 1
	v_mfma_f32_16x16x32_bf16 v[150:153], v[0:3], v[104:107], 0
	v_mfma_f32_16x16x32_bf16 v[158:161], v[0:3], v[112:115], 0
	v_mfma_f32_16x16x32_bf16 v[0:3], v[0:3], v[120:123], 0
	v_mfma_f32_16x16x32_bf16 v[142:145], v[4:7], v[100:103], v[142:145]
	v_mfma_f32_16x16x32_bf16 v[150:153], v[4:7], v[108:111], v[150:153]
	v_mfma_f32_16x16x32_bf16 v[158:161], v[4:7], v[116:119], v[158:161]
	v_mfma_f32_16x16x32_bf16 v[0:3], v[4:7], v[124:127], v[0:3]
	v_mfma_f32_16x16x32_bf16 v[4:7], v[8:11], v[120:123], 0
	v_mfma_f32_16x16x32_bf16 v[146:149], v[8:11], v[60:63], 0
	v_mfma_f32_16x16x32_bf16 v[154:157], v[8:11], v[104:107], 0
	v_mfma_f32_16x16x32_bf16 v[162:165], v[8:11], v[112:115], 0
	v_mfma_f32_16x16x32_bf16 v[4:7], v[12:15], v[124:127], v[4:7]
	v_mfma_f32_16x16x32_bf16 v[146:149], v[12:15], v[100:103], v[146:149]
	v_mfma_f32_16x16x32_bf16 v[154:157], v[12:15], v[108:111], v[154:157]
	v_mfma_f32_16x16x32_bf16 v[162:165], v[12:15], v[116:119], v[162:165]
	v_mfma_f32_16x16x32_bf16 v[8:11], v[16:19], v[60:63], 0
	v_mfma_f32_16x16x32_bf16 v[12:15], v[24:27], v[60:63], 0
	v_mfma_f32_16x16x32_bf16 v[8:11], v[20:23], v[100:103], v[8:11]
	v_mfma_f32_16x16x32_bf16 v[12:15], v[28:31], v[100:103], v[12:15]
	v_mfma_f32_16x16x32_bf16 v[60:63], v[16:19], v[104:107], 0
	v_mfma_f32_16x16x32_bf16 v[100:103], v[24:27], v[104:107], 0
	v_mfma_f32_16x16x32_bf16 v[104:107], v[16:19], v[112:115], 0
	v_mfma_f32_16x16x32_bf16 v[16:19], v[16:19], v[120:123], 0
	v_mfma_f32_16x16x32_bf16 v[60:63], v[20:23], v[108:111], v[60:63]
	v_mfma_f32_16x16x32_bf16 v[100:103], v[28:31], v[108:111], v[100:103]
	v_mfma_f32_16x16x32_bf16 v[104:107], v[20:23], v[116:119], v[104:107]
	v_mfma_f32_16x16x32_bf16 v[108:111], v[24:27], v[112:115], 0
	v_mfma_f32_16x16x32_bf16 v[16:19], v[20:23], v[124:127], v[16:19]
	v_mfma_f32_16x16x32_bf16 v[20:23], v[24:27], v[120:123], 0
	v_mfma_f32_16x16x32_bf16 v[108:111], v[28:31], v[116:119], v[108:111]
	v_mfma_f32_16x16x32_bf16 v[20:23], v[28:31], v[124:127], v[20:23]
	s_barrier
	s_setprio 0
	s_add_i32 s60, 0, 0x18000
	s_add_i32 s70, 0, 0x1c000
	v_add_u32_e32 v230, s60, v138
	v_add_u32_e32 v238, s70, v138
	ds_read_b128 v[24:27], v230
	ds_read_b128 v[28:31], v230 offset:1024
	ds_read_b128 v[112:115], v230 offset:2048
	ds_read_b128 v[116:119], v230 offset:3072
	ds_read_b128 v[120:123], v238
	ds_read_b128 v[124:127], v238 offset:1024
	ds_read_b128 v[166:169], v238 offset:2048
	ds_read_b128 v[170:173], v238 offset:3072
	s_add_u32 s66, s8, 0x40100
	s_addc_u32 s67, s9, 0
	s_mov_b32 m0, s27
	v_lshl_add_u64 v[196:197], s[66:67], 0, v[134:135]
	ds_read_b128 v[174:177], v139 offset:32768
	ds_read_b128 v[178:181], v139 offset:33792
	ds_read_b128 v[182:185], v139 offset:34816
	ds_read_b128 v[186:189], v139 offset:35840
	ds_read_b128 v[200:203], v139 offset:36864
	ds_read_b128 v[206:209], v139 offset:37888
	ds_read_b128 v[210:213], v139 offset:38912
	ds_read_b128 v[214:217], v139 offset:39936
	global_load_lds_dwordx4 v[196:197], off
	v_lshl_add_u64 v[196:197], s[66:67], 0, v[130:131]
	s_mov_b32 m0, s28
	s_nop 0
	global_load_lds_dwordx4 v[196:197], off
	s_waitcnt vmcnt(8)
	s_waitcnt lgkmcnt(0)
	s_barrier
	v_mfma_f32_16x16x32_bf16 v[64:67], v[24:27], v[174:177], v[64:67]
	s_setprio 1
	v_mfma_f32_16x16x32_bf16 v[68:71], v[112:115], v[174:177], v[68:71]
	v_mfma_f32_16x16x32_bf16 v[72:75], v[24:27], v[182:185], v[72:75]
	v_mfma_f32_16x16x32_bf16 v[76:79], v[112:115], v[182:185], v[76:79]
	v_mfma_f32_16x16x32_bf16 v[80:83], v[24:27], v[200:203], v[80:83]
	v_mfma_f32_16x16x32_bf16 v[84:87], v[112:115], v[200:203], v[84:87]
	v_mfma_f32_16x16x32_bf16 v[88:91], v[24:27], v[210:213], v[88:91]
	v_mfma_f32_16x16x32_bf16 v[92:95], v[112:115], v[210:213], v[92:95]
	v_mfma_f32_16x16x32_bf16 v[64:67], v[28:31], v[178:181], v[64:67]
	v_mfma_f32_16x16x32_bf16 v[68:71], v[116:119], v[178:181], v[68:71]
	v_mfma_f32_16x16x32_bf16 v[72:75], v[28:31], v[186:189], v[72:75]
	v_mfma_f32_16x16x32_bf16 v[76:79], v[116:119], v[186:189], v[76:79]
	v_mfma_f32_16x16x32_bf16 v[80:83], v[28:31], v[206:209], v[80:83]
	v_mfma_f32_16x16x32_bf16 v[84:87], v[116:119], v[206:209], v[84:87]
	v_mfma_f32_16x16x32_bf16 v[88:91], v[28:31], v[214:217], v[88:91]
	v_mfma_f32_16x16x32_bf16 v[92:95], v[116:119], v[214:217], v[92:95]
	v_mfma_f32_16x16x32_bf16 v[96:99], v[120:123], v[174:177], v[96:99]
	v_mfma_f32_16x16x32_bf16 v[32:35], v[166:169], v[174:177], v[32:35]
	v_mfma_f32_16x16x32_bf16 v[36:39], v[120:123], v[182:185], v[36:39]
	v_mfma_f32_16x16x32_bf16 v[40:43], v[166:169], v[182:185], v[40:43]
	v_mfma_f32_16x16x32_bf16 v[44:47], v[120:123], v[200:203], v[44:47]
	v_mfma_f32_16x16x32_bf16 v[48:51], v[166:169], v[200:203], v[48:51]
	v_mfma_f32_16x16x32_bf16 v[52:55], v[120:123], v[210:213], v[52:55]
	v_mfma_f32_16x16x32_bf16 v[56:59], v[166:169], v[210:213], v[56:59]
	v_mfma_f32_16x16x32_bf16 v[96:99], v[124:127], v[178:181], v[96:99]
	v_mfma_f32_16x16x32_bf16 v[32:35], v[170:173], v[178:181], v[32:35]
	v_mfma_f32_16x16x32_bf16 v[36:39], v[124:127], v[186:189], v[36:39]
	v_mfma_f32_16x16x32_bf16 v[40:43], v[170:173], v[186:189], v[40:43]
	v_mfma_f32_16x16x32_bf16 v[44:47], v[124:127], v[206:209], v[44:47]
	v_mfma_f32_16x16x32_bf16 v[48:51], v[170:173], v[206:209], v[48:51]
	v_mfma_f32_16x16x32_bf16 v[52:55], v[124:127], v[214:217], v[52:55]
	v_mfma_f32_16x16x32_bf16 v[56:59], v[170:173], v[214:217], v[56:59]
	s_barrier
	s_setprio 0
	s_add_i32 s66, s60, s24
	s_mov_b64 s[74:75], 0x180
	s_add_i32 s60, s66, 0x2000
	v_lshl_add_u64 v[136:137], v[136:137], 0, s[74:75]
	s_mov_b32 m0, s66
	s_add_u32 s68, s10, 0x200180
	ds_read_b128 v[174:177], v139 offset:49152
	ds_read_b128 v[178:181], v139 offset:50176
	ds_read_b128 v[182:185], v139 offset:51200
	ds_read_b128 v[186:189], v139 offset:52224
	ds_read_b128 v[200:203], v139 offset:53248
	ds_read_b128 v[206:209], v139 offset:54272
	ds_read_b128 v[210:213], v139 offset:55296
	ds_read_b128 v[214:217], v139 offset:56320
	global_load_lds_dwordx4 v[136:137], off
	v_lshl_add_u64 v[136:137], v[190:191], 0, s[74:75]
	s_mov_b32 m0, s60
	s_addc_u32 s69, s11, 0
	s_add_i32 s10, s70, s24
	global_load_lds_dwordx4 v[136:137], off
	v_lshl_add_u64 v[136:137], s[68:69], 0, v[132:133]
	s_mov_b32 m0, s10
	s_add_i32 s11, s10, 0x2000
	global_load_lds_dwordx4 v[136:137], off
	v_lshl_add_u64 v[136:137], s[68:69], 0, v[128:129]
	s_mov_b32 m0, s11
	s_nop 0
	global_load_lds_dwordx4 v[136:137], off
	v_lshl_add_u64 v[136:137], v[192:193], 0, s[74:75]
	s_mov_b32 m0, s29
	s_nop 0
	global_load_lds_dwordx4 v[136:137], off
	v_lshl_add_u64 v[136:137], v[194:195], 0, s[74:75]
	s_mov_b32 m0, s38
	s_nop 0
	global_load_lds_dwordx4 v[136:137], off
	s_waitcnt vmcnt(8)
	s_waitcnt lgkmcnt(0)
	s_barrier
	v_mfma_f32_16x16x32_bf16 v[0:3], v[24:27], v[210:213], v[0:3]
	s_setprio 1
	v_mfma_f32_16x16x32_bf16 v[4:7], v[112:115], v[210:213], v[4:7]
	v_mfma_f32_16x16x32_bf16 v[142:145], v[24:27], v[174:177], v[142:145]
	v_mfma_f32_16x16x32_bf16 v[146:149], v[112:115], v[174:177], v[146:149]
	v_mfma_f32_16x16x32_bf16 v[150:153], v[24:27], v[182:185], v[150:153]
	v_mfma_f32_16x16x32_bf16 v[154:157], v[112:115], v[182:185], v[154:157]
	v_mfma_f32_16x16x32_bf16 v[158:161], v[24:27], v[200:203], v[158:161]
	v_mfma_f32_16x16x32_bf16 v[162:165], v[112:115], v[200:203], v[162:165]
	v_mfma_f32_16x16x32_bf16 v[0:3], v[28:31], v[214:217], v[0:3]
	v_mfma_f32_16x16x32_bf16 v[4:7], v[116:119], v[214:217], v[4:7]
	v_mfma_f32_16x16x32_bf16 v[142:145], v[28:31], v[178:181], v[142:145]
	v_mfma_f32_16x16x32_bf16 v[146:149], v[116:119], v[178:181], v[146:149]
	v_mfma_f32_16x16x32_bf16 v[150:153], v[28:31], v[186:189], v[150:153]
	v_mfma_f32_16x16x32_bf16 v[154:157], v[116:119], v[186:189], v[154:157]
	v_mfma_f32_16x16x32_bf16 v[158:161], v[28:31], v[206:209], v[158:161]
	v_mfma_f32_16x16x32_bf16 v[162:165], v[116:119], v[206:209], v[162:165]
	v_mfma_f32_16x16x32_bf16 v[8:11], v[120:123], v[174:177], v[8:11]
	v_mfma_f32_16x16x32_bf16 v[12:15], v[166:169], v[174:177], v[12:15]
	v_mfma_f32_16x16x32_bf16 v[24:27], v[120:123], v[182:185], v[60:63]
	v_mfma_f32_16x16x32_bf16 v[28:31], v[166:169], v[182:185], v[100:103]
	v_mfma_f32_16x16x32_bf16 v[60:63], v[120:123], v[200:203], v[104:107]
	v_mfma_f32_16x16x32_bf16 v[100:103], v[166:169], v[200:203], v[108:111]
	v_mfma_f32_16x16x32_bf16 v[16:19], v[120:123], v[210:213], v[16:19]
	v_mfma_f32_16x16x32_bf16 v[20:23], v[166:169], v[210:213], v[20:23]
	v_mfma_f32_16x16x32_bf16 v[8:11], v[124:127], v[178:181], v[8:11]
	v_mfma_f32_16x16x32_bf16 v[12:15], v[170:173], v[178:181], v[12:15]
	v_mfma_f32_16x16x32_bf16 v[24:27], v[124:127], v[186:189], v[24:27]
	v_mfma_f32_16x16x32_bf16 v[28:31], v[170:173], v[186:189], v[28:31]
	v_mfma_f32_16x16x32_bf16 v[60:63], v[124:127], v[206:209], v[60:63]
	v_mfma_f32_16x16x32_bf16 v[100:103], v[170:173], v[206:209], v[100:103]
	v_mfma_f32_16x16x32_bf16 v[16:19], v[124:127], v[214:217], v[16:19]
	v_mfma_f32_16x16x32_bf16 v[20:23], v[170:173], v[214:217], v[20:23]
	s_barrier
	s_setprio 0
	ds_read_b128 v[104:107], v140
	ds_read_b128 v[108:111], v140 offset:1024
	ds_read_b128 v[112:115], v140 offset:2048
	ds_read_b128 v[116:119], v140 offset:3072
	ds_read_b128 v[120:123], v198
	ds_read_b128 v[124:127], v198 offset:1024
	ds_read_b128 v[166:169], v198 offset:2048
	ds_read_b128 v[170:173], v198 offset:3072
	s_add_u32 s8, s8, 0x40180
	s_addc_u32 s9, s9, 0
	s_mov_b32 m0, s61
	v_lshl_add_u64 v[136:137], s[8:9], 0, v[134:135]
	ds_read_b128 v[174:177], v139
	ds_read_b128 v[178:181], v139 offset:1024
	ds_read_b128 v[182:185], v139 offset:2048
	ds_read_b128 v[186:189], v139 offset:3072
	ds_read_b128 v[200:203], v139 offset:4096
	ds_read_b128 v[206:209], v139 offset:5120
	ds_read_b128 v[210:213], v139 offset:6144
	ds_read_b128 v[214:217], v139 offset:7168
	global_load_lds_dwordx4 v[136:137], off
	v_lshl_add_u64 v[136:137], s[8:9], 0, v[130:131]
	s_mov_b32 m0, s35
	s_nop 0
	global_load_lds_dwordx4 v[136:137], off
	s_waitcnt vmcnt(8)
	s_waitcnt lgkmcnt(0)
	s_barrier
	v_mfma_f32_16x16x32_bf16 v[88:91], v[104:107], v[210:213], v[88:91]
	s_setprio 1
	v_mfma_f32_16x16x32_bf16 v[64:67], v[104:107], v[174:177], v[64:67]
	v_mfma_f32_16x16x32_bf16 v[68:71], v[112:115], v[174:177], v[68:71]
	v_mfma_f32_16x16x32_bf16 v[72:75], v[104:107], v[182:185], v[72:75]
	v_mfma_f32_16x16x32_bf16 v[76:79], v[112:115], v[182:185], v[76:79]
	v_mfma_f32_16x16x32_bf16 v[80:83], v[104:107], v[200:203], v[80:83]
	v_mfma_f32_16x16x32_bf16 v[84:87], v[112:115], v[200:203], v[84:87]
	v_mfma_f32_16x16x32_bf16 v[218:221], v[108:111], v[214:217], v[88:91]
	v_mfma_f32_16x16x32_bf16 v[88:91], v[112:115], v[210:213], v[92:95]
	v_mfma_f32_16x16x32_bf16 v[64:67], v[108:111], v[178:181], v[64:67]
	v_mfma_f32_16x16x32_bf16 v[68:71], v[116:119], v[178:181], v[68:71]
	v_mfma_f32_16x16x32_bf16 v[72:75], v[108:111], v[186:189], v[72:75]
	v_mfma_f32_16x16x32_bf16 v[76:79], v[116:119], v[186:189], v[76:79]
	v_mfma_f32_16x16x32_bf16 v[80:83], v[108:111], v[206:209], v[80:83]
	v_mfma_f32_16x16x32_bf16 v[84:87], v[116:119], v[206:209], v[84:87]
	v_mfma_f32_16x16x32_bf16 v[92:95], v[116:119], v[214:217], v[88:91]
	v_mfma_f32_16x16x32_bf16 v[48:51], v[166:169], v[200:203], v[48:51]
	v_mfma_f32_16x16x32_bf16 v[88:91], v[120:123], v[174:177], v[96:99]
	v_mfma_f32_16x16x32_bf16 v[32:35], v[166:169], v[174:177], v[32:35]
	v_mfma_f32_16x16x32_bf16 v[36:39], v[120:123], v[182:185], v[36:39]
	v_mfma_f32_16x16x32_bf16 v[40:43], v[166:169], v[182:185], v[40:43]
	v_mfma_f32_16x16x32_bf16 v[44:47], v[120:123], v[200:203], v[44:47]
	v_mfma_f32_16x16x32_bf16 v[174:177], v[170:173], v[206:209], v[48:51]
	v_mfma_f32_16x16x32_bf16 v[48:51], v[120:123], v[210:213], v[52:55]
	v_mfma_f32_16x16x32_bf16 v[32:35], v[170:173], v[178:181], v[32:35]
	v_mfma_f32_16x16x32_bf16 v[36:39], v[124:127], v[186:189], v[36:39]
	v_mfma_f32_16x16x32_bf16 v[40:43], v[170:173], v[186:189], v[40:43]
	v_mfma_f32_16x16x32_bf16 v[44:47], v[124:127], v[206:209], v[44:47]
	v_mfma_f32_16x16x32_bf16 v[52:55], v[124:127], v[214:217], v[48:51]
	v_mfma_f32_16x16x32_bf16 v[48:51], v[166:169], v[210:213], v[56:59]
	v_mfma_f32_16x16x32_bf16 v[222:225], v[124:127], v[178:181], v[88:91]
	v_mfma_f32_16x16x32_bf16 v[178:181], v[170:173], v[214:217], v[48:51]
	s_barrier
	s_setprio 0
	s_mov_b32 m0, s59
	v_lshl_add_u64 v[136:137], s[12:13], 0, v[132:133]
	s_add_u32 s8, s12, 0x200000
	s_nop 0
	ds_read_b128 v[48:51], v139 offset:16384
	ds_read_b128 v[56:59], v139 offset:17408
	ds_read_b128 v[88:91], v139 offset:18432
	ds_read_b128 v[96:99], v139 offset:19456
	ds_read_b128 v[182:185], v139 offset:20480
	ds_read_b128 v[186:189], v139 offset:21504
	ds_read_b128 v[200:203], v139 offset:22528
	ds_read_b128 v[206:209], v139 offset:23552
	global_load_lds_dwordx4 v[136:137], off
	v_lshl_add_u64 v[204:205], s[12:13], 0, v[128:129]
	s_mov_b32 m0, s47
	s_addc_u32 s9, s13, 0
	global_load_lds_dwordx4 v[204:205], off
	v_lshl_add_u64 v[190:191], s[8:9], 0, v[132:133]
	s_mov_b32 m0, s57
	v_lshl_add_u64 v[250:251], s[52:53], 0, v[134:135]
	global_load_lds_dwordx4 v[190:191], off
	v_lshl_add_u64 v[190:191], s[8:9], 0, v[128:129]
	s_mov_b32 m0, s58
	v_lshl_add_u64 v[198:199], s[52:53], 0, v[130:131]
	global_load_lds_dwordx4 v[190:191], off
	s_mov_b32 m0, s25
	s_nop 0
	global_load_lds_dwordx4 v[250:251], off
	s_mov_b32 m0, s26
	s_nop 0
	global_load_lds_dwordx4 v[198:199], off
	s_waitcnt vmcnt(8)
	s_waitcnt lgkmcnt(0)
	s_barrier
	v_mfma_f32_16x16x32_bf16 v[0:3], v[104:107], v[200:203], v[0:3]
	s_setprio 1
	v_mfma_f32_16x16x32_bf16 v[4:7], v[112:115], v[200:203], v[4:7]
	v_mfma_f32_16x16x32_bf16 v[142:145], v[104:107], v[48:51], v[142:145]
	v_mfma_f32_16x16x32_bf16 v[146:149], v[112:115], v[48:51], v[146:149]
	v_mfma_f32_16x16x32_bf16 v[150:153], v[104:107], v[88:91], v[150:153]
	v_mfma_f32_16x16x32_bf16 v[154:157], v[112:115], v[88:91], v[154:157]
	v_mfma_f32_16x16x32_bf16 v[158:161], v[104:107], v[182:185], v[158:161]
	v_mfma_f32_16x16x32_bf16 v[162:165], v[112:115], v[182:185], v[162:165]
	v_mfma_f32_16x16x32_bf16 v[0:3], v[108:111], v[206:209], v[0:3]
	v_mfma_f32_16x16x32_bf16 v[4:7], v[116:119], v[206:209], v[4:7]
	v_mfma_f32_16x16x32_bf16 v[142:145], v[108:111], v[56:59], v[142:145]
	v_mfma_f32_16x16x32_bf16 v[146:149], v[116:119], v[56:59], v[146:149]
	v_mfma_f32_16x16x32_bf16 v[150:153], v[108:111], v[96:99], v[150:153]
	v_mfma_f32_16x16x32_bf16 v[154:157], v[116:119], v[96:99], v[154:157]
	v_mfma_f32_16x16x32_bf16 v[158:161], v[108:111], v[186:189], v[158:161]
	v_mfma_f32_16x16x32_bf16 v[162:165], v[116:119], v[186:189], v[162:165]
	v_mfma_f32_16x16x32_bf16 v[12:15], v[166:169], v[48:51], v[12:15]
	v_mfma_f32_16x16x32_bf16 v[210:213], v[170:173], v[56:59], v[12:15]
	v_mfma_f32_16x16x32_bf16 v[12:15], v[120:123], v[88:91], v[24:27]
	v_mfma_f32_16x16x32_bf16 v[24:27], v[124:127], v[96:99], v[12:15]
	v_mfma_f32_16x16x32_bf16 v[12:15], v[166:169], v[88:91], v[28:31]
	v_mfma_f32_16x16x32_bf16 v[214:217], v[170:173], v[96:99], v[12:15]
	v_mfma_f32_16x16x32_bf16 v[12:15], v[120:123], v[182:185], v[60:63]
	v_mfma_f32_16x16x32_bf16 v[226:229], v[124:127], v[186:189], v[12:15]
	v_mfma_f32_16x16x32_bf16 v[12:15], v[166:169], v[182:185], v[100:103]
	v_mfma_f32_16x16x32_bf16 v[8:11], v[120:123], v[48:51], v[8:11]
	v_mfma_f32_16x16x32_bf16 v[182:185], v[170:173], v[186:189], v[12:15]
	v_mfma_f32_16x16x32_bf16 v[12:15], v[120:123], v[200:203], v[16:19]
	v_mfma_f32_16x16x32_bf16 v[8:11], v[124:127], v[56:59], v[8:11]
	v_mfma_f32_16x16x32_bf16 v[186:189], v[124:127], v[206:209], v[12:15]
	v_mfma_f32_16x16x32_bf16 v[12:15], v[166:169], v[200:203], v[20:23]
	v_mfma_f32_16x16x32_bf16 v[166:169], v[170:173], v[206:209], v[12:15]
	s_barrier
	s_setprio 0
	s_nop 4
	ds_read_b128 v[12:15], v230
	ds_read_b128 v[16:19], v230 offset:1024
	ds_read_b128 v[170:173], v230 offset:2048
	ds_read_b128 v[200:203], v230 offset:3072
	ds_read_b128 v[206:209], v238
	ds_read_b128 v[230:233], v238 offset:1024
	ds_read_b128 v[234:237], v238 offset:2048
	ds_read_b128 v[238:241], v238 offset:3072
	s_add_u32 s8, s52, 0x40000
	s_addc_u32 s9, s53, 0
	s_mov_b32 m0, s27
	v_lshl_add_u64 v[48:49], s[8:9], 0, v[134:135]
	ds_read_b128 v[20:23], v139 offset:32768
	ds_read_b128 v[28:31], v139 offset:33792
	ds_read_b128 v[60:63], v139 offset:34816
	ds_read_b128 v[100:103], v139 offset:35840
	ds_read_b128 v[242:245], v139 offset:36864
	ds_read_b128 v[246:249], v139 offset:37888
	ds_read_b128 v[190:193], v139 offset:38912
	ds_read_b128 v[194:197], v139 offset:39936
	global_load_lds_dwordx4 v[48:49], off
	v_lshl_add_u64 v[48:49], s[8:9], 0, v[130:131]
	s_mov_b32 m0, s28
	s_nop 0
	global_load_lds_dwordx4 v[48:49], off
	s_waitcnt vmcnt(8)
	s_waitcnt lgkmcnt(0)
	s_barrier
	v_mfma_f32_16x16x32_bf16 v[48:51], v[12:15], v[20:23], v[64:67]
	s_setprio 1
	v_mfma_f32_16x16x32_bf16 v[120:123], v[16:19], v[28:31], v[48:51]
	v_mfma_f32_16x16x32_bf16 v[48:51], v[170:173], v[20:23], v[68:71]
	v_mfma_f32_16x16x32_bf16 v[112:115], v[200:203], v[28:31], v[48:51]
	v_mfma_f32_16x16x32_bf16 v[48:51], v[12:15], v[60:63], v[72:75]
	v_mfma_f32_16x16x32_bf16 v[104:107], v[16:19], v[100:103], v[48:51]
	v_mfma_f32_16x16x32_bf16 v[48:51], v[170:173], v[60:63], v[76:79]
	v_mfma_f32_16x16x32_bf16 v[96:99], v[200:203], v[100:103], v[48:51]
	v_mfma_f32_16x16x32_bf16 v[48:51], v[12:15], v[242:245], v[80:83]
	v_mfma_f32_16x16x32_bf16 v[88:91], v[16:19], v[246:249], v[48:51]
	v_mfma_f32_16x16x32_bf16 v[48:51], v[170:173], v[242:245], v[84:87]
	v_mfma_f32_16x16x32_bf16 v[80:83], v[200:203], v[246:249], v[48:51]
	v_mfma_f32_16x16x32_bf16 v[48:51], v[12:15], v[190:193], v[218:221]
	v_mfma_f32_16x16x32_bf16 v[56:59], v[16:19], v[194:197], v[48:51]
	v_mfma_f32_16x16x32_bf16 v[48:51], v[170:173], v[190:193], v[92:95]
	v_mfma_f32_16x16x32_bf16 v[48:51], v[200:203], v[194:197], v[48:51]
	v_mfma_f32_16x16x32_bf16 v[64:67], v[206:209], v[20:23], v[222:225]
	v_mfma_f32_16x16x32_bf16 v[20:23], v[234:237], v[20:23], v[32:35]
	v_mfma_f32_16x16x32_bf16 v[116:119], v[238:241], v[28:31], v[20:23]
	v_mfma_f32_16x16x32_bf16 v[20:23], v[206:209], v[60:63], v[36:39]
	v_mfma_f32_16x16x32_bf16 v[108:111], v[230:233], v[100:103], v[20:23]
	v_mfma_f32_16x16x32_bf16 v[20:23], v[234:237], v[60:63], v[40:43]
	v_mfma_f32_16x16x32_bf16 v[100:103], v[238:241], v[100:103], v[20:23]
	v_mfma_f32_16x16x32_bf16 v[20:23], v[206:209], v[242:245], v[44:47]
	v_mfma_f32_16x16x32_bf16 v[92:95], v[230:233], v[246:249], v[20:23]
	v_mfma_f32_16x16x32_bf16 v[20:23], v[234:237], v[242:245], v[174:177]
	v_mfma_f32_16x16x32_bf16 v[84:87], v[238:241], v[246:249], v[20:23]
	v_mfma_f32_16x16x32_bf16 v[20:23], v[206:209], v[190:193], v[52:55]
	v_mfma_f32_16x16x32_bf16 v[60:63], v[230:233], v[194:197], v[20:23]
	v_mfma_f32_16x16x32_bf16 v[20:23], v[234:237], v[190:193], v[178:181]
	v_mfma_f32_16x16x32_bf16 v[124:127], v[230:233], v[28:31], v[64:67]
	v_mfma_f32_16x16x32_bf16 v[52:55], v[238:241], v[194:197], v[20:23]
	s_barrier
	s_setprio 0
	s_mov_b32 m0, s66
	s_nop 2
	v_lshl_add_u64 v[20:21], v[136:137], 0, s[36:37]
	s_add_u32 s8, s12, 0x200080
	ds_read_b128 v[32:35], v139 offset:49152
	ds_read_b128 v[40:43], v139 offset:50176
	ds_read_b128 v[174:177], v139 offset:51200
	ds_read_b128 v[178:181], v139 offset:52224
	ds_read_b128 v[190:193], v139 offset:53248
	ds_read_b128 v[194:197], v139 offset:54272
	ds_read_b128 v[218:221], v139 offset:55296
	ds_read_b128 v[222:225], v139 offset:56320
	global_load_lds_dwordx4 v[20:21], off
	v_lshl_add_u64 v[20:21], v[204:205], 0, s[36:37]
	s_mov_b32 m0, s60
	s_addc_u32 s9, s13, 0
	global_load_lds_dwordx4 v[20:21], off
	v_lshl_add_u64 v[20:21], s[8:9], 0, v[132:133]
	s_mov_b32 m0, s10
	s_nop 0
	global_load_lds_dwordx4 v[20:21], off
	v_lshl_add_u64 v[20:21], s[8:9], 0, v[128:129]
	s_mov_b32 m0, s11
	s_nop 0
	global_load_lds_dwordx4 v[20:21], off
	v_lshl_add_u64 v[20:21], v[250:251], 0, s[36:37]
	s_mov_b32 m0, s29
	s_nop 0
	global_load_lds_dwordx4 v[20:21], off
	v_lshl_add_u64 v[20:21], v[198:199], 0, s[36:37]
	s_mov_b32 m0, s38
	s_nop 0
	global_load_lds_dwordx4 v[20:21], off
	s_waitcnt vmcnt(8)
	s_waitcnt lgkmcnt(0)
	s_barrier
	v_mfma_f32_16x16x32_bf16 v[20:23], v[12:15], v[32:35], v[142:145]
	s_setprio 1
	v_mfma_f32_16x16x32_bf16 v[76:79], v[16:19], v[40:43], v[20:23]
	v_mfma_f32_16x16x32_bf16 v[20:23], v[170:173], v[32:35], v[146:149]
	v_mfma_f32_16x16x32_bf16 v[68:71], v[200:203], v[40:43], v[20:23]
	v_mfma_f32_16x16x32_bf16 v[20:23], v[12:15], v[174:177], v[150:153]
	v_mfma_f32_16x16x32_bf16 v[44:47], v[16:19], v[178:181], v[20:23]
	v_mfma_f32_16x16x32_bf16 v[20:23], v[170:173], v[174:177], v[154:157]
	v_mfma_f32_16x16x32_bf16 v[36:39], v[200:203], v[178:181], v[20:23]
	v_mfma_f32_16x16x32_bf16 v[20:23], v[12:15], v[190:193], v[158:161]
	v_mfma_f32_16x16x32_bf16 v[0:3], v[12:15], v[218:221], v[0:3]
	v_mfma_f32_16x16x32_bf16 v[28:31], v[16:19], v[194:197], v[20:23]
	v_mfma_f32_16x16x32_bf16 v[20:23], v[170:173], v[190:193], v[162:165]
	v_mfma_f32_16x16x32_bf16 v[12:15], v[16:19], v[222:225], v[0:3]
	v_mfma_f32_16x16x32_bf16 v[0:3], v[170:173], v[218:221], v[4:7]
	v_mfma_f32_16x16x32_bf16 v[20:23], v[200:203], v[194:197], v[20:23]
	v_mfma_f32_16x16x32_bf16 v[4:7], v[200:203], v[222:225], v[0:3]
	v_mfma_f32_16x16x32_bf16 v[0:3], v[206:209], v[32:35], v[8:11]
	v_mfma_f32_16x16x32_bf16 v[72:75], v[230:233], v[40:43], v[0:3]
	v_mfma_f32_16x16x32_bf16 v[0:3], v[234:237], v[32:35], v[210:213]
	v_mfma_f32_16x16x32_bf16 v[64:67], v[238:241], v[40:43], v[0:3]
	v_mfma_f32_16x16x32_bf16 v[0:3], v[206:209], v[174:177], v[24:27]
	v_mfma_f32_16x16x32_bf16 v[40:43], v[230:233], v[178:181], v[0:3]
	v_mfma_f32_16x16x32_bf16 v[0:3], v[234:237], v[174:177], v[214:217]
	v_mfma_f32_16x16x32_bf16 v[32:35], v[238:241], v[178:181], v[0:3]
	v_mfma_f32_16x16x32_bf16 v[0:3], v[206:209], v[190:193], v[226:229]
	v_mfma_f32_16x16x32_bf16 v[24:27], v[230:233], v[194:197], v[0:3]
	v_mfma_f32_16x16x32_bf16 v[0:3], v[234:237], v[190:193], v[182:185]
	v_mfma_f32_16x16x32_bf16 v[16:19], v[238:241], v[194:197], v[0:3]
	v_mfma_f32_16x16x32_bf16 v[0:3], v[206:209], v[218:221], v[186:189]
	v_mfma_f32_16x16x32_bf16 v[8:11], v[230:233], v[222:225], v[0:3]
	v_mfma_f32_16x16x32_bf16 v[0:3], v[234:237], v[218:221], v[166:169]
	v_mfma_f32_16x16x32_bf16 v[0:3], v[238:241], v[222:225], v[0:3]
	s_barrier
	s_setprio 0
	s_andn2_b64 vcc, exec, s[42:43]
	s_cbranch_vccnz .LBB0_696
	s_barrier

.LBB0_714:
	s_add_u32 s8, s6, 0xfffc0080
	s_addc_u32 s9, s7, -1
	s_add_i32 s35, 0, 0x10000
	s_cmp_eq_u32 s59, 12
	s_cselect_b32 s11, s24, s9
	s_cselect_b32 s10, s51, s8
	v_add_u32_e32 v138, s35, v164
	s_cselect_b32 s9, s49, s58
	s_cselect_b32 s8, s56, s57
	s_add_i32 s66, 0, 0x14000
	ds_read_b128 v[158:161], v138
	ds_read_b128 v[166:169], v138 offset:1024
	ds_read_b128 v[170:173], v138 offset:2048
	ds_read_b128 v[174:177], v138 offset:3072
	v_add_u32_e32 v138, s66, v164
	ds_read_b128 v[178:181], v138
	ds_read_b128 v[182:185], v138 offset:1024
	ds_read_b128 v[206:209], v138 offset:2048
	ds_read_b128 v[210:213], v138 offset:3072
	v_lshl_add_u64 v[138:139], s[6:7], 0, v[134:135]
	s_add_i32 m0, s17, 0xc000
	ds_read_b128 v[214:217], v165
	ds_read_b128 v[218:221], v165 offset:1024
	ds_read_b128 v[222:225], v165 offset:2048
	ds_read_b128 v[226:229], v165 offset:3072
	ds_read_b128 v[230:233], v165 offset:4096
	ds_read_b128 v[234:237], v165 offset:5120
	ds_read_b128 v[238:241], v165 offset:6144
	ds_read_b128 v[242:245], v165 offset:7168
	global_load_lds_dwordx4 v[138:139], off
	v_lshl_add_u64 v[138:139], s[6:7], 0, v[136:137]
	s_add_i32 m0, s17, 0xe000
	s_nop 0
	global_load_lds_dwordx4 v[138:139], off
	s_waitcnt vmcnt(8)
	s_waitcnt lgkmcnt(0)
	s_barrier
	v_mfma_f32_16x16x32_bf16 v[124:127], v[158:161], v[214:217], v[124:127]
	s_setprio 1
	v_mfma_f32_16x16x32_bf16 v[120:123], v[170:173], v[214:217], v[120:123]
	v_mfma_f32_16x16x32_bf16 v[108:111], v[158:161], v[222:225], v[108:111]
	v_mfma_f32_16x16x32_bf16 v[104:107], v[170:173], v[222:225], v[104:107]
	v_mfma_f32_16x16x32_bf16 v[92:95], v[158:161], v[230:233], v[92:95]
	v_mfma_f32_16x16x32_bf16 v[88:91], v[170:173], v[230:233], v[88:91]
	v_mfma_f32_16x16x32_bf16 v[76:79], v[158:161], v[238:241], v[76:79]
	v_mfma_f32_16x16x32_bf16 v[72:75], v[170:173], v[238:241], v[72:75]
	v_mfma_f32_16x16x32_bf16 v[124:127], v[166:169], v[218:221], v[124:127]
	v_mfma_f32_16x16x32_bf16 v[120:123], v[174:177], v[218:221], v[120:123]
	v_mfma_f32_16x16x32_bf16 v[108:111], v[166:169], v[226:229], v[108:111]
	v_mfma_f32_16x16x32_bf16 v[104:107], v[174:177], v[226:229], v[104:107]
	v_mfma_f32_16x16x32_bf16 v[92:95], v[166:169], v[234:237], v[92:95]
	v_mfma_f32_16x16x32_bf16 v[88:91], v[174:177], v[234:237], v[88:91]
	v_mfma_f32_16x16x32_bf16 v[76:79], v[166:169], v[242:245], v[76:79]
	v_mfma_f32_16x16x32_bf16 v[72:75], v[174:177], v[242:245], v[72:75]
	v_mfma_f32_16x16x32_bf16 v[116:119], v[178:181], v[214:217], v[116:119]
	v_mfma_f32_16x16x32_bf16 v[112:115], v[206:209], v[214:217], v[112:115]
	v_mfma_f32_16x16x32_bf16 v[100:103], v[178:181], v[222:225], v[100:103]
	v_mfma_f32_16x16x32_bf16 v[96:99], v[206:209], v[222:225], v[96:99]
	v_mfma_f32_16x16x32_bf16 v[84:87], v[178:181], v[230:233], v[84:87]
	v_mfma_f32_16x16x32_bf16 v[80:83], v[206:209], v[230:233], v[80:83]
	v_mfma_f32_16x16x32_bf16 v[68:71], v[178:181], v[238:241], v[68:71]
	v_mfma_f32_16x16x32_bf16 v[64:67], v[206:209], v[238:241], v[64:67]
	v_mfma_f32_16x16x32_bf16 v[116:119], v[182:185], v[218:221], v[116:119]
	v_mfma_f32_16x16x32_bf16 v[112:115], v[210:213], v[218:221], v[112:115]
	v_mfma_f32_16x16x32_bf16 v[100:103], v[182:185], v[226:229], v[100:103]
	v_mfma_f32_16x16x32_bf16 v[96:99], v[210:213], v[226:229], v[96:99]
	v_mfma_f32_16x16x32_bf16 v[84:87], v[182:185], v[234:237], v[84:87]
	v_mfma_f32_16x16x32_bf16 v[80:83], v[210:213], v[234:237], v[80:83]
	v_mfma_f32_16x16x32_bf16 v[68:71], v[182:185], v[242:245], v[68:71]
	v_mfma_f32_16x16x32_bf16 v[64:67], v[210:213], v[242:245], v[64:67]
	s_barrier
	s_setprio 0
	s_add_i32 s35, s35, s14
	v_lshl_add_u64 v[138:139], s[8:9], 0, v[140:141]
	s_mov_b32 m0, s35
	ds_read_b128 v[214:217], v165 offset:16384
	ds_read_b128 v[218:221], v165 offset:17408
	ds_read_b128 v[222:225], v165 offset:18432
	ds_read_b128 v[226:229], v165 offset:19456
	ds_read_b128 v[230:233], v165 offset:20480
	ds_read_b128 v[234:237], v165 offset:21504
	ds_read_b128 v[238:241], v165 offset:22528
	ds_read_b128 v[242:245], v165 offset:23552
	global_load_lds_dwordx4 v[138:139], off
	s_add_i32 m0, s35, 0x2000
	s_add_u32 s60, s8, 0x40000
	v_lshl_add_u64 v[142:143], s[8:9], 0, v[128:129]
	s_addc_u32 s61, s9, 0
	s_add_i32 s35, s66, s14
	global_load_lds_dwordx4 v[142:143], off
	v_lshl_add_u64 v[144:145], s[60:61], 0, v[140:141]
	s_mov_b32 m0, s35
	v_lshl_add_u64 v[146:147], s[10:11], 0, v[130:131]
	global_load_lds_dwordx4 v[144:145], off
	v_lshl_add_u64 v[144:145], s[60:61], 0, v[128:129]
	s_add_i32 m0, s35, 0x2000
	s_nop 0
	global_load_lds_dwordx4 v[144:145], off
	v_lshl_add_u64 v[144:145], s[10:11], 0, v[132:133]
	s_mov_b32 m0, s17
	s_nop 0
	global_load_lds_dwordx4 v[144:145], off
	s_mov_b32 m0, s25
	s_nop 0
	global_load_lds_dwordx4 v[146:147], off
	s_waitcnt vmcnt(8)
	s_waitcnt lgkmcnt(0)
	s_barrier
	v_mfma_f32_16x16x32_bf16 v[60:63], v[158:161], v[214:217], v[60:63]
	s_setprio 1
	v_mfma_f32_16x16x32_bf16 v[56:59], v[170:173], v[214:217], v[56:59]
	v_mfma_f32_16x16x32_bf16 v[44:47], v[158:161], v[222:225], v[44:47]
	v_mfma_f32_16x16x32_bf16 v[40:43], v[170:173], v[222:225], v[40:43]
	v_mfma_f32_16x16x32_bf16 v[28:31], v[158:161], v[230:233], v[28:31]
	v_mfma_f32_16x16x32_bf16 v[24:27], v[170:173], v[230:233], v[24:27]
	v_mfma_f32_16x16x32_bf16 v[12:15], v[158:161], v[238:241], v[12:15]
	v_mfma_f32_16x16x32_bf16 v[8:11], v[170:173], v[238:241], v[8:11]
	v_mfma_f32_16x16x32_bf16 v[60:63], v[166:169], v[218:221], v[60:63]
	v_mfma_f32_16x16x32_bf16 v[56:59], v[174:177], v[218:221], v[56:59]
	v_mfma_f32_16x16x32_bf16 v[44:47], v[166:169], v[226:229], v[44:47]
	v_mfma_f32_16x16x32_bf16 v[40:43], v[174:177], v[226:229], v[40:43]
	v_mfma_f32_16x16x32_bf16 v[28:31], v[166:169], v[234:237], v[28:31]
	v_mfma_f32_16x16x32_bf16 v[24:27], v[174:177], v[234:237], v[24:27]
	v_mfma_f32_16x16x32_bf16 v[12:15], v[166:169], v[242:245], v[12:15]
	v_mfma_f32_16x16x32_bf16 v[8:11], v[174:177], v[242:245], v[8:11]
	v_mfma_f32_16x16x32_bf16 v[52:55], v[178:181], v[214:217], v[52:55]
	v_mfma_f32_16x16x32_bf16 v[48:51], v[206:209], v[214:217], v[48:51]
	v_mfma_f32_16x16x32_bf16 v[36:39], v[178:181], v[222:225], v[36:39]
	v_mfma_f32_16x16x32_bf16 v[32:35], v[206:209], v[222:225], v[32:35]
	v_mfma_f32_16x16x32_bf16 v[20:23], v[178:181], v[230:233], v[20:23]
	v_mfma_f32_16x16x32_bf16 v[16:19], v[206:209], v[230:233], v[16:19]
	v_mfma_f32_16x16x32_bf16 v[4:7], v[178:181], v[238:241], v[4:7]
	v_mfma_f32_16x16x32_bf16 v[0:3], v[206:209], v[238:241], v[0:3]
	v_mfma_f32_16x16x32_bf16 v[52:55], v[182:185], v[218:221], v[52:55]
	v_mfma_f32_16x16x32_bf16 v[48:51], v[210:213], v[218:221], v[48:51]
	v_mfma_f32_16x16x32_bf16 v[36:39], v[182:185], v[226:229], v[36:39]
	v_mfma_f32_16x16x32_bf16 v[32:35], v[210:213], v[226:229], v[32:35]
	v_mfma_f32_16x16x32_bf16 v[20:23], v[182:185], v[234:237], v[20:23]
	v_mfma_f32_16x16x32_bf16 v[16:19], v[210:213], v[234:237], v[16:19]
	v_mfma_f32_16x16x32_bf16 v[4:7], v[182:185], v[242:245], v[4:7]
	v_mfma_f32_16x16x32_bf16 v[0:3], v[210:213], v[242:245], v[0:3]
	s_barrier
	s_setprio 0
	s_add_i32 s35, 0, 0x18000
	v_add_u32_e32 v148, s35, v164
	s_add_i32 s60, 0, 0x1c000
	ds_read_b128 v[158:161], v148
	ds_read_b128 v[166:169], v148 offset:1024
	ds_read_b128 v[170:173], v148 offset:2048
	ds_read_b128 v[174:177], v148 offset:3072
	v_add_u32_e32 v148, s60, v164
	ds_read_b128 v[178:181], v148
	ds_read_b128 v[182:185], v148 offset:1024
	ds_read_b128 v[206:209], v148 offset:2048
	ds_read_b128 v[210:213], v148 offset:3072
	s_add_u32 s10, s10, 0x40000
	s_addc_u32 s11, s11, 0
	s_mov_b32 m0, s26
	v_lshl_add_u64 v[148:149], s[10:11], 0, v[132:133]
	ds_read_b128 v[214:217], v165 offset:32768
	ds_read_b128 v[218:221], v165 offset:33792
	ds_read_b128 v[222:225], v165 offset:34816
	ds_read_b128 v[226:229], v165 offset:35840
	ds_read_b128 v[230:233], v165 offset:36864
	ds_read_b128 v[234:237], v165 offset:37888
	ds_read_b128 v[238:241], v165 offset:38912
	ds_read_b128 v[242:245], v165 offset:39936
	global_load_lds_dwordx4 v[148:149], off
	v_lshl_add_u64 v[148:149], s[10:11], 0, v[130:131]
	s_mov_b32 m0, s27
	s_nop 0
	global_load_lds_dwordx4 v[148:149], off
	s_waitcnt vmcnt(8)
	s_waitcnt lgkmcnt(0)
	s_barrier
	v_mfma_f32_16x16x32_bf16 v[124:127], v[158:161], v[214:217], v[124:127]
	s_setprio 1
	v_mfma_f32_16x16x32_bf16 v[120:123], v[170:173], v[214:217], v[120:123]
	v_mfma_f32_16x16x32_bf16 v[108:111], v[158:161], v[222:225], v[108:111]
	v_mfma_f32_16x16x32_bf16 v[104:107], v[170:173], v[222:225], v[104:107]
	v_mfma_f32_16x16x32_bf16 v[92:95], v[158:161], v[230:233], v[92:95]
	v_mfma_f32_16x16x32_bf16 v[88:91], v[170:173], v[230:233], v[88:91]
	v_mfma_f32_16x16x32_bf16 v[76:79], v[158:161], v[238:241], v[76:79]
	v_mfma_f32_16x16x32_bf16 v[72:75], v[170:173], v[238:241], v[72:75]
	v_mfma_f32_16x16x32_bf16 v[124:127], v[166:169], v[218:221], v[124:127]
	v_mfma_f32_16x16x32_bf16 v[120:123], v[174:177], v[218:221], v[120:123]
	v_mfma_f32_16x16x32_bf16 v[108:111], v[166:169], v[226:229], v[108:111]
	v_mfma_f32_16x16x32_bf16 v[104:107], v[174:177], v[226:229], v[104:107]
	v_mfma_f32_16x16x32_bf16 v[92:95], v[166:169], v[234:237], v[92:95]
	v_mfma_f32_16x16x32_bf16 v[88:91], v[174:177], v[234:237], v[88:91]
	v_mfma_f32_16x16x32_bf16 v[76:79], v[166:169], v[242:245], v[76:79]
	v_mfma_f32_16x16x32_bf16 v[72:75], v[174:177], v[242:245], v[72:75]
	v_mfma_f32_16x16x32_bf16 v[116:119], v[178:181], v[214:217], v[116:119]
	v_mfma_f32_16x16x32_bf16 v[112:115], v[206:209], v[214:217], v[112:115]
	v_mfma_f32_16x16x32_bf16 v[100:103], v[178:181], v[222:225], v[100:103]
	v_mfma_f32_16x16x32_bf16 v[96:99], v[206:209], v[222:225], v[96:99]
	v_mfma_f32_16x16x32_bf16 v[84:87], v[178:181], v[230:233], v[84:87]
	v_mfma_f32_16x16x32_bf16 v[80:83], v[206:209], v[230:233], v[80:83]
	v_mfma_f32_16x16x32_bf16 v[68:71], v[178:181], v[238:241], v[68:71]
	v_mfma_f32_16x16x32_bf16 v[64:67], v[206:209], v[238:241], v[64:67]
	v_mfma_f32_16x16x32_bf16 v[116:119], v[182:185], v[218:221], v[116:119]
	v_mfma_f32_16x16x32_bf16 v[112:115], v[210:213], v[218:221], v[112:115]
	v_mfma_f32_16x16x32_bf16 v[100:103], v[182:185], v[226:229], v[100:103]
	v_mfma_f32_16x16x32_bf16 v[96:99], v[210:213], v[226:229], v[96:99]
	v_mfma_f32_16x16x32_bf16 v[84:87], v[182:185], v[234:237], v[84:87]
	v_mfma_f32_16x16x32_bf16 v[80:83], v[210:213], v[234:237], v[80:83]
	v_mfma_f32_16x16x32_bf16 v[68:71], v[182:185], v[242:245], v[68:71]
	v_mfma_f32_16x16x32_bf16 v[64:67], v[210:213], v[242:245], v[64:67]
	s_barrier
	s_setprio 0
	s_add_i32 s10, s35, s14
	v_lshl_add_u64 v[138:139], v[138:139], 0, s[36:37]
	s_mov_b32 m0, s10
	ds_read_b128 v[214:217], v165 offset:49152
	ds_read_b128 v[218:221], v165 offset:50176
	ds_read_b128 v[222:225], v165 offset:51200
	ds_read_b128 v[226:229], v165 offset:52224
	ds_read_b128 v[230:233], v165 offset:53248
	ds_read_b128 v[234:237], v165 offset:54272
	ds_read_b128 v[238:241], v165 offset:55296
	ds_read_b128 v[242:245], v165 offset:56320
	global_load_lds_dwordx4 v[138:139], off
	s_add_i32 m0, s10, 0x2000
	s_add_u32 s8, s8, 0x40080
	v_lshl_add_u64 v[138:139], v[142:143], 0, s[36:37]
	s_addc_u32 s9, s9, 0
	s_add_i32 s10, s60, s14
	global_load_lds_dwordx4 v[138:139], off
	v_lshl_add_u64 v[138:139], s[8:9], 0, v[140:141]
	s_mov_b32 m0, s10
	s_nop 0
	global_load_lds_dwordx4 v[138:139], off
	v_lshl_add_u64 v[138:139], s[8:9], 0, v[128:129]
	s_add_i32 m0, s10, 0x2000
	s_nop 0
	global_load_lds_dwordx4 v[138:139], off
	v_lshl_add_u64 v[138:139], v[144:145], 0, s[36:37]
	s_mov_b32 m0, s28
	s_nop 0
	global_load_lds_dwordx4 v[138:139], off
	v_lshl_add_u64 v[138:139], v[146:147], 0, s[36:37]
	s_mov_b32 m0, s29
	s_nop 0
	global_load_lds_dwordx4 v[138:139], off
	s_waitcnt vmcnt(8)
	s_waitcnt lgkmcnt(0)
	s_barrier
	v_mfma_f32_16x16x32_bf16 v[60:63], v[158:161], v[214:217], v[60:63]
	s_setprio 1
	v_mfma_f32_16x16x32_bf16 v[56:59], v[170:173], v[214:217], v[56:59]
	v_mfma_f32_16x16x32_bf16 v[44:47], v[158:161], v[222:225], v[44:47]
	v_mfma_f32_16x16x32_bf16 v[40:43], v[170:173], v[222:225], v[40:43]
	v_mfma_f32_16x16x32_bf16 v[28:31], v[158:161], v[230:233], v[28:31]
	v_mfma_f32_16x16x32_bf16 v[24:27], v[170:173], v[230:233], v[24:27]
	v_mfma_f32_16x16x32_bf16 v[12:15], v[158:161], v[238:241], v[12:15]
	v_mfma_f32_16x16x32_bf16 v[8:11], v[170:173], v[238:241], v[8:11]
	v_mfma_f32_16x16x32_bf16 v[60:63], v[166:169], v[218:221], v[60:63]
	v_mfma_f32_16x16x32_bf16 v[56:59], v[174:177], v[218:221], v[56:59]
	v_mfma_f32_16x16x32_bf16 v[44:47], v[166:169], v[226:229], v[44:47]
	v_mfma_f32_16x16x32_bf16 v[40:43], v[174:177], v[226:229], v[40:43]
	v_mfma_f32_16x16x32_bf16 v[28:31], v[166:169], v[234:237], v[28:31]
	v_mfma_f32_16x16x32_bf16 v[24:27], v[174:177], v[234:237], v[24:27]
	v_mfma_f32_16x16x32_bf16 v[12:15], v[166:169], v[242:245], v[12:15]
	v_mfma_f32_16x16x32_bf16 v[8:11], v[174:177], v[242:245], v[8:11]
	v_mfma_f32_16x16x32_bf16 v[52:55], v[178:181], v[214:217], v[52:55]
	v_mfma_f32_16x16x32_bf16 v[48:51], v[206:209], v[214:217], v[48:51]
	v_mfma_f32_16x16x32_bf16 v[36:39], v[178:181], v[222:225], v[36:39]
	v_mfma_f32_16x16x32_bf16 v[32:35], v[206:209], v[222:225], v[32:35]
	v_mfma_f32_16x16x32_bf16 v[20:23], v[178:181], v[230:233], v[20:23]
	v_mfma_f32_16x16x32_bf16 v[16:19], v[206:209], v[230:233], v[16:19]
	v_mfma_f32_16x16x32_bf16 v[4:7], v[178:181], v[238:241], v[4:7]
	v_mfma_f32_16x16x32_bf16 v[0:3], v[206:209], v[238:241], v[0:3]
	v_mfma_f32_16x16x32_bf16 v[52:55], v[182:185], v[218:221], v[52:55]
	v_mfma_f32_16x16x32_bf16 v[48:51], v[210:213], v[218:221], v[48:51]
	v_mfma_f32_16x16x32_bf16 v[36:39], v[182:185], v[226:229], v[36:39]
	v_mfma_f32_16x16x32_bf16 v[32:35], v[210:213], v[226:229], v[32:35]
	v_mfma_f32_16x16x32_bf16 v[20:23], v[182:185], v[234:237], v[20:23]
	v_mfma_f32_16x16x32_bf16 v[16:19], v[210:213], v[234:237], v[16:19]
	v_mfma_f32_16x16x32_bf16 v[4:7], v[182:185], v[242:245], v[4:7]
	v_mfma_f32_16x16x32_bf16 v[0:3], v[210:213], v[242:245], v[0:3]
	s_barrier
	s_setprio 0
	s_add_i32 s59, s59, 2
	s_add_u32 s6, s6, 0x100
	s_addc_u32 s7, s7, 0
	s_add_u32 s57, s57, 0x100
	s_addc_u32 s58, s58, 0
	s_cmp_gt_u32 s59, 13
	s_cbranch_scc0 .LBB0_714
	s_and_b64 vcc, exec, s[46:47]
	s_cbranch_vccz .LBB0_717
	s_barrier
